# also non-temporal stores of the final LayerNorm output rows (never re-read)
# speedup vs baseline: 1.0024x; 1.0024x over previous
.LBB0_745:
	s_or_b64 exec, exec, s[0:1]
	s_mov_b64 s[4:5], s[88:89]
	s_waitcnt lgkmcnt(0)
	s_barrier
	s_cmpk_lg_u32 s56, 0x100
	s_cbranch_scc1 .Llo_generic
	s_load_dwordx2 s[6:7], s[4:5], 0xa0
	s_load_dwordx4 s[40:43], s[4:5], 0x90
	v_mbcnt_lo_u32_b32 v0, -1, 0
	v_mbcnt_hi_u32_b32 v0, -1, v0
	v_lshlrev_b32_e32 v1, 4, v0
	s_lshr_b32 s0, s29, 6
	s_lshl_b32 s96, s92, 24
	s_lshl_b64 s[8:9], s[96:97], 2
	v_mov_b32_e32 v2, 0x3a800000
	v_mov_b32_e32 v4, 0x3727c5ac
	s_waitcnt lgkmcnt(0)
	s_add_u32 s4, s6, s8
	s_addc_u32 s5, s7, s9
	s_cmp_eq_u32 s92, 2
	s_cbranch_scc1 .Llo_even
	s_cmp_lt_u32 s86, 64
	s_cbranch_scc1 .Ltr_29
	s_sub_u32 s1, s86, 64
	s_lshl_b32 s1, s1, 3
	s_add_i32 s0, s0, s1
	s_lshl_b32 s1, s0, 12
	s_add_u32 s4, s4, s1
	s_addc_u32 s5, s5, 0
	s_cmpk_lt_u32 s0, 0x400
	s_cbranch_scc0 .Llo_r10
	global_load_dwordx4 v[40:43], v1, s[4:5] nt
	global_load_dwordx4 v[44:47], v1, s[4:5] offset:1024 nt
	global_load_dwordx4 v[48:51], v1, s[4:5] offset:2048 nt
	global_load_dwordx4 v[52:55], v1, s[4:5] offset:3072 nt
	global_load_dwordx4 v[8:11], v1, s[40:41]
	global_load_dwordx4 v[12:15], v1, s[40:41] offset:1024
	global_load_dwordx4 v[16:19], v1, s[40:41] offset:2048
	global_load_dwordx4 v[20:23], v1, s[40:41] offset:3072
	global_load_dwordx4 v[24:27], v1, s[42:43]
	global_load_dwordx4 v[28:31], v1, s[42:43] offset:1024
	global_load_dwordx4 v[32:35], v1, s[42:43] offset:2048
	global_load_dwordx4 v[36:39], v1, s[42:43] offset:3072
	v_add_u32_e32 v170, 0x600000, v1
	global_load_dwordx4 v[56:59], v170, s[4:5] nt
	global_load_dwordx4 v[60:63], v170, s[4:5] offset:1024 nt
	global_load_dwordx4 v[64:67], v170, s[4:5] offset:2048 nt
	global_load_dwordx4 v[68:71], v170, s[4:5] offset:3072 nt
	v_add_u32_e32 v170, 0xc00000, v1
	global_load_dwordx4 v[72:75], v170, s[4:5] nt
	global_load_dwordx4 v[76:79], v170, s[4:5] offset:1024 nt
	global_load_dwordx4 v[80:83], v170, s[4:5] offset:2048 nt
	global_load_dwordx4 v[84:87], v170, s[4:5] offset:3072 nt
	v_add_u32_e32 v170, 0x1200000, v1
	global_load_dwordx4 v[88:91], v170, s[4:5] nt
	global_load_dwordx4 v[92:95], v170, s[4:5] offset:1024 nt
	global_load_dwordx4 v[96:99], v170, s[4:5] offset:2048 nt
	global_load_dwordx4 v[100:103], v170, s[4:5] offset:3072 nt
	v_add_u32_e32 v170, 0x1800000, v1
	global_load_dwordx4 v[104:107], v170, s[4:5] nt
	global_load_dwordx4 v[108:111], v170, s[4:5] offset:1024 nt
	global_load_dwordx4 v[112:115], v170, s[4:5] offset:2048 nt
	global_load_dwordx4 v[116:119], v170, s[4:5] offset:3072 nt
	v_add_u32_e32 v170, 0x1e00000, v1
	global_load_dwordx4 v[120:123], v170, s[4:5] nt
	global_load_dwordx4 v[124:127], v170, s[4:5] offset:1024 nt
	global_load_dwordx4 v[128:131], v170, s[4:5] offset:2048 nt
	global_load_dwordx4 v[132:135], v170, s[4:5] offset:3072 nt
	v_add_u32_e32 v170, 0x2400000, v1
	global_load_dwordx4 v[136:139], v170, s[4:5] nt
	global_load_dwordx4 v[140:143], v170, s[4:5] offset:1024 nt
	global_load_dwordx4 v[144:147], v170, s[4:5] offset:2048 nt
	global_load_dwordx4 v[148:151], v170, s[4:5] offset:3072 nt
	v_add_u32_e32 v170, 0x2a00000, v1
	global_load_dwordx4 v[152:155], v170, s[4:5] nt
	global_load_dwordx4 v[156:159], v170, s[4:5] offset:1024 nt
	global_load_dwordx4 v[160:163], v170, s[4:5] offset:2048 nt
	global_load_dwordx4 v[164:167], v170, s[4:5] offset:3072 nt
	s_waitcnt vmcnt(36)
	v_add_f32_e32 v180, v40, v41
	v_add_f32_e32 v181, v44, v45
	v_add_f32_e32 v182, v48, v49
	v_add_f32_e32 v183, v52, v53
	v_add_f32_e32 v180, v180, v42
	v_add_f32_e32 v181, v181, v46
	v_add_f32_e32 v182, v182, v50
	v_add_f32_e32 v183, v183, v54
	v_add_f32_e32 v180, v180, v43
	v_add_f32_e32 v181, v181, v47
	v_add_f32_e32 v182, v182, v51
	v_add_f32_e32 v183, v183, v55
	v_add_f32_e32 v180, v180, v181
	v_add_f32_e32 v182, v182, v183
	v_add_f32_e32 v180, v180, v182
	s_nop 1
	v_add_f32_dpp v180, v180, v180 quad_perm:[1,0,3,2] row_mask:0xf bank_mask:0xf
	s_nop 1
	v_add_f32_dpp v180, v180, v180 quad_perm:[2,3,0,1] row_mask:0xf bank_mask:0xf
	s_nop 1
	v_add_f32_dpp v180, v180, v180 row_half_mirror row_mask:0xf bank_mask:0xf
	s_nop 1
	v_add_f32_dpp v180, v180, v180 row_mirror row_mask:0xf bank_mask:0xf
	s_nop 1
	v_add_f32_dpp v180, v180, v180 row_bcast:15 row_mask:0xa bank_mask:0xf
	s_nop 1
	v_add_f32_dpp v180, v180, v180 row_bcast:31 row_mask:0xc bank_mask:0xf
	s_nop 0
	v_readlane_b32 s20, v180, 63
	s_nop 1
	v_mul_f32_e32 v184, s20, v2
	v_sub_f32_e32 v40, v40, v184
	v_sub_f32_e32 v41, v41, v184
	v_sub_f32_e32 v42, v42, v184
	v_sub_f32_e32 v43, v43, v184
	v_sub_f32_e32 v44, v44, v184
	v_sub_f32_e32 v45, v45, v184
	v_sub_f32_e32 v46, v46, v184
	v_sub_f32_e32 v47, v47, v184
	v_sub_f32_e32 v48, v48, v184
	v_sub_f32_e32 v49, v49, v184
	v_sub_f32_e32 v50, v50, v184
	v_sub_f32_e32 v51, v51, v184
	v_sub_f32_e32 v52, v52, v184
	v_sub_f32_e32 v53, v53, v184
	v_sub_f32_e32 v54, v54, v184
	v_sub_f32_e32 v55, v55, v184
	v_mul_f32_e32 v180, v40, v40
	v_mul_f32_e32 v181, v44, v44
	v_mul_f32_e32 v182, v48, v48
	v_mul_f32_e32 v183, v52, v52
	v_fmac_f32_e32 v180, v41, v41
	v_fmac_f32_e32 v181, v45, v45
	v_fmac_f32_e32 v182, v49, v49
	v_fmac_f32_e32 v183, v53, v53
	v_fmac_f32_e32 v180, v42, v42
	v_fmac_f32_e32 v181, v46, v46
	v_fmac_f32_e32 v182, v50, v50
	v_fmac_f32_e32 v183, v54, v54
	v_fmac_f32_e32 v180, v43, v43
	v_fmac_f32_e32 v181, v47, v47
	v_fmac_f32_e32 v182, v51, v51
	v_fmac_f32_e32 v183, v55, v55
	v_add_f32_e32 v180, v180, v181
	v_add_f32_e32 v182, v182, v183
	v_add_f32_e32 v180, v180, v182
	s_nop 1
	v_add_f32_dpp v180, v180, v180 quad_perm:[1,0,3,2] row_mask:0xf bank_mask:0xf
	s_nop 1
	v_add_f32_dpp v180, v180, v180 quad_perm:[2,3,0,1] row_mask:0xf bank_mask:0xf
	s_nop 1
	v_add_f32_dpp v180, v180, v180 row_half_mirror row_mask:0xf bank_mask:0xf
	s_nop 1
	v_add_f32_dpp v180, v180, v180 row_mirror row_mask:0xf bank_mask:0xf
	s_nop 1
	v_add_f32_dpp v180, v180, v180 row_bcast:15 row_mask:0xa bank_mask:0xf
	s_nop 1
	v_add_f32_dpp v180, v180, v180 row_bcast:31 row_mask:0xc bank_mask:0xf
	s_nop 0
	v_readlane_b32 s20, v180, 63
	s_nop 1
	v_mov_b32_e32 v185, s20
	v_fma_f32 v185, v185, v2, v4
	v_rsq_f32_e32 v185, v185
	s_nop 0
	v_mul_f32_e32 v40, v40, v185
	v_mul_f32_e32 v41, v41, v185
	v_mul_f32_e32 v42, v42, v185
	v_mul_f32_e32 v43, v43, v185
	v_mul_f32_e32 v44, v44, v185
	v_mul_f32_e32 v45, v45, v185
	v_mul_f32_e32 v46, v46, v185
	v_mul_f32_e32 v47, v47, v185
	v_mul_f32_e32 v48, v48, v185
	v_mul_f32_e32 v49, v49, v185
	v_mul_f32_e32 v50, v50, v185
	v_mul_f32_e32 v51, v51, v185
	v_mul_f32_e32 v52, v52, v185
	v_mul_f32_e32 v53, v53, v185
	v_mul_f32_e32 v54, v54, v185
	v_mul_f32_e32 v55, v55, v185
	s_waitcnt vmcnt(28)
	v_fma_f32 v40, v40, v8, v24
	v_fma_f32 v41, v41, v9, v25
	v_fma_f32 v42, v42, v10, v26
	v_fma_f32 v43, v43, v11, v27
	v_fma_f32 v44, v44, v12, v28
	v_fma_f32 v45, v45, v13, v29
	v_fma_f32 v46, v46, v14, v30
	v_fma_f32 v47, v47, v15, v31
	v_fma_f32 v48, v48, v16, v32
	v_fma_f32 v49, v49, v17, v33
	v_fma_f32 v50, v50, v18, v34
	v_fma_f32 v51, v51, v19, v35
	v_fma_f32 v52, v52, v20, v36
	v_fma_f32 v53, v53, v21, v37
	v_fma_f32 v54, v54, v22, v38
	v_fma_f32 v55, v55, v23, v39
	global_store_dwordx4 v1, v[40:43], s[4:5] nt
	global_store_dwordx4 v1, v[44:47], s[4:5] offset:1024 nt
	global_store_dwordx4 v1, v[48:51], s[4:5] offset:2048 nt
	global_store_dwordx4 v1, v[52:55], s[4:5] offset:3072 nt
	s_nop 1
	v_add_u32_e32 v170, 0x3000000, v1
	global_load_dwordx4 v[40:43], v170, s[4:5] nt
	global_load_dwordx4 v[44:47], v170, s[4:5] offset:1024 nt
	global_load_dwordx4 v[48:51], v170, s[4:5] offset:2048 nt
	global_load_dwordx4 v[52:55], v170, s[4:5] offset:3072 nt
	s_waitcnt vmcnt(32)
	v_add_f32_e32 v180, v56, v57
	v_add_f32_e32 v181, v60, v61
	v_add_f32_e32 v182, v64, v65
	v_add_f32_e32 v183, v68, v69
	v_add_f32_e32 v180, v180, v58
	v_add_f32_e32 v181, v181, v62
	v_add_f32_e32 v182, v182, v66
	v_add_f32_e32 v183, v183, v70
	v_add_f32_e32 v180, v180, v59
	v_add_f32_e32 v181, v181, v63
	v_add_f32_e32 v182, v182, v67
	v_add_f32_e32 v183, v183, v71
	v_add_f32_e32 v180, v180, v181
	v_add_f32_e32 v182, v182, v183
	v_add_f32_e32 v180, v180, v182
	s_nop 1
	v_add_f32_dpp v180, v180, v180 quad_perm:[1,0,3,2] row_mask:0xf bank_mask:0xf
	s_nop 1
	v_add_f32_dpp v180, v180, v180 quad_perm:[2,3,0,1] row_mask:0xf bank_mask:0xf
	s_nop 1
	v_add_f32_dpp v180, v180, v180 row_half_mirror row_mask:0xf bank_mask:0xf
	s_nop 1
	v_add_f32_dpp v180, v180, v180 row_mirror row_mask:0xf bank_mask:0xf
	s_nop 1
	v_add_f32_dpp v180, v180, v180 row_bcast:15 row_mask:0xa bank_mask:0xf
	s_nop 1
	v_add_f32_dpp v180, v180, v180 row_bcast:31 row_mask:0xc bank_mask:0xf
	s_nop 0
	v_readlane_b32 s20, v180, 63
	s_nop 1
	v_mul_f32_e32 v184, s20, v2
	v_sub_f32_e32 v56, v56, v184
	v_sub_f32_e32 v57, v57, v184
	v_sub_f32_e32 v58, v58, v184
	v_sub_f32_e32 v59, v59, v184
	v_sub_f32_e32 v60, v60, v184
	v_sub_f32_e32 v61, v61, v184
	v_sub_f32_e32 v62, v62, v184
	v_sub_f32_e32 v63, v63, v184
	v_sub_f32_e32 v64, v64, v184
	v_sub_f32_e32 v65, v65, v184
	v_sub_f32_e32 v66, v66, v184
	v_sub_f32_e32 v67, v67, v184
	v_sub_f32_e32 v68, v68, v184
	v_sub_f32_e32 v69, v69, v184
	v_sub_f32_e32 v70, v70, v184
	v_sub_f32_e32 v71, v71, v184
	v_mul_f32_e32 v180, v56, v56
	v_mul_f32_e32 v181, v60, v60
	v_mul_f32_e32 v182, v64, v64
	v_mul_f32_e32 v183, v68, v68
	v_fmac_f32_e32 v180, v57, v57
	v_fmac_f32_e32 v181, v61, v61
	v_fmac_f32_e32 v182, v65, v65
	v_fmac_f32_e32 v183, v69, v69
	v_fmac_f32_e32 v180, v58, v58
	v_fmac_f32_e32 v181, v62, v62
	v_fmac_f32_e32 v182, v66, v66
	v_fmac_f32_e32 v183, v70, v70
	v_fmac_f32_e32 v180, v59, v59
	v_fmac_f32_e32 v181, v63, v63
	v_fmac_f32_e32 v182, v67, v67
	v_fmac_f32_e32 v183, v71, v71
	v_add_f32_e32 v180, v180, v181
	v_add_f32_e32 v182, v182, v183
	v_add_f32_e32 v180, v180, v182
	s_nop 1
	v_add_f32_dpp v180, v180, v180 quad_perm:[1,0,3,2] row_mask:0xf bank_mask:0xf
	s_nop 1
	v_add_f32_dpp v180, v180, v180 quad_perm:[2,3,0,1] row_mask:0xf bank_mask:0xf
	s_nop 1
	v_add_f32_dpp v180, v180, v180 row_half_mirror row_mask:0xf bank_mask:0xf
	s_nop 1
	v_add_f32_dpp v180, v180, v180 row_mirror row_mask:0xf bank_mask:0xf
	s_nop 1
	v_add_f32_dpp v180, v180, v180 row_bcast:15 row_mask:0xa bank_mask:0xf
	s_nop 1
	v_add_f32_dpp v180, v180, v180 row_bcast:31 row_mask:0xc bank_mask:0xf
	s_nop 0
	v_readlane_b32 s20, v180, 63
	s_nop 1
	v_mov_b32_e32 v185, s20
	v_fma_f32 v185, v185, v2, v4
	v_rsq_f32_e32 v185, v185
	s_nop 0
	v_mul_f32_e32 v56, v56, v185
	v_mul_f32_e32 v57, v57, v185
	v_mul_f32_e32 v58, v58, v185
	v_mul_f32_e32 v59, v59, v185
	v_mul_f32_e32 v60, v60, v185
	v_mul_f32_e32 v61, v61, v185
	v_mul_f32_e32 v62, v62, v185
	v_mul_f32_e32 v63, v63, v185
	v_mul_f32_e32 v64, v64, v185
	v_mul_f32_e32 v65, v65, v185
	v_mul_f32_e32 v66, v66, v185
	v_mul_f32_e32 v67, v67, v185
	v_mul_f32_e32 v68, v68, v185
	v_mul_f32_e32 v69, v69, v185
	v_mul_f32_e32 v70, v70, v185
	v_mul_f32_e32 v71, v71, v185
	v_fma_f32 v56, v56, v8, v24
	v_fma_f32 v57, v57, v9, v25
	v_fma_f32 v58, v58, v10, v26
	v_fma_f32 v59, v59, v11, v27
	v_fma_f32 v60, v60, v12, v28
	v_fma_f32 v61, v61, v13, v29
	v_fma_f32 v62, v62, v14, v30
	v_fma_f32 v63, v63, v15, v31
	v_fma_f32 v64, v64, v16, v32
	v_fma_f32 v65, v65, v17, v33
	v_fma_f32 v66, v66, v18, v34
	v_fma_f32 v67, v67, v19, v35
	v_fma_f32 v68, v68, v20, v36
	v_fma_f32 v69, v69, v21, v37
	v_fma_f32 v70, v70, v22, v38
	v_fma_f32 v71, v71, v23, v39
	v_add_u32_e32 v171, 0x600000, v1
	global_store_dwordx4 v171, v[56:59], s[4:5] nt
	global_store_dwordx4 v171, v[60:63], s[4:5] offset:1024 nt
	global_store_dwordx4 v171, v[64:67], s[4:5] offset:2048 nt
	global_store_dwordx4 v171, v[68:71], s[4:5] offset:3072 nt
	s_nop 1
	v_add_u32_e32 v170, 0x3600000, v1
	global_load_dwordx4 v[56:59], v170, s[4:5] nt
	global_load_dwordx4 v[60:63], v170, s[4:5] offset:1024 nt
	global_load_dwordx4 v[64:67], v170, s[4:5] offset:2048 nt
	global_load_dwordx4 v[68:71], v170, s[4:5] offset:3072 nt
	s_waitcnt vmcnt(36)
	v_add_f32_e32 v180, v72, v73
	v_add_f32_e32 v181, v76, v77
	v_add_f32_e32 v182, v80, v81
	v_add_f32_e32 v183, v84, v85
	v_add_f32_e32 v180, v180, v74
	v_add_f32_e32 v181, v181, v78
	v_add_f32_e32 v182, v182, v82
	v_add_f32_e32 v183, v183, v86
	v_add_f32_e32 v180, v180, v75
	v_add_f32_e32 v181, v181, v79
	v_add_f32_e32 v182, v182, v83
	v_add_f32_e32 v183, v183, v87
	v_add_f32_e32 v180, v180, v181
	v_add_f32_e32 v182, v182, v183
	v_add_f32_e32 v180, v180, v182
	s_nop 1
	v_add_f32_dpp v180, v180, v180 quad_perm:[1,0,3,2] row_mask:0xf bank_mask:0xf
	s_nop 1
	v_add_f32_dpp v180, v180, v180 quad_perm:[2,3,0,1] row_mask:0xf bank_mask:0xf
	s_nop 1
	v_add_f32_dpp v180, v180, v180 row_half_mirror row_mask:0xf bank_mask:0xf
	s_nop 1
	v_add_f32_dpp v180, v180, v180 row_mirror row_mask:0xf bank_mask:0xf
	s_nop 1
	v_add_f32_dpp v180, v180, v180 row_bcast:15 row_mask:0xa bank_mask:0xf
	s_nop 1
	v_add_f32_dpp v180, v180, v180 row_bcast:31 row_mask:0xc bank_mask:0xf
	s_nop 0
	v_readlane_b32 s20, v180, 63
	s_nop 1
	v_mul_f32_e32 v184, s20, v2
	v_sub_f32_e32 v72, v72, v184
	v_sub_f32_e32 v73, v73, v184
	v_sub_f32_e32 v74, v74, v184
	v_sub_f32_e32 v75, v75, v184
	v_sub_f32_e32 v76, v76, v184
	v_sub_f32_e32 v77, v77, v184
	v_sub_f32_e32 v78, v78, v184
	v_sub_f32_e32 v79, v79, v184
	v_sub_f32_e32 v80, v80, v184
	v_sub_f32_e32 v81, v81, v184
	v_sub_f32_e32 v82, v82, v184
	v_sub_f32_e32 v83, v83, v184
	v_sub_f32_e32 v84, v84, v184
	v_sub_f32_e32 v85, v85, v184
	v_sub_f32_e32 v86, v86, v184
	v_sub_f32_e32 v87, v87, v184
	v_mul_f32_e32 v180, v72, v72
	v_mul_f32_e32 v181, v76, v76
	v_mul_f32_e32 v182, v80, v80
	v_mul_f32_e32 v183, v84, v84
	v_fmac_f32_e32 v180, v73, v73
	v_fmac_f32_e32 v181, v77, v77
	v_fmac_f32_e32 v182, v81, v81
	v_fmac_f32_e32 v183, v85, v85
	v_fmac_f32_e32 v180, v74, v74
	v_fmac_f32_e32 v181, v78, v78
	v_fmac_f32_e32 v182, v82, v82
	v_fmac_f32_e32 v183, v86, v86
	v_fmac_f32_e32 v180, v75, v75
	v_fmac_f32_e32 v181, v79, v79
	v_fmac_f32_e32 v182, v83, v83
	v_fmac_f32_e32 v183, v87, v87
	v_add_f32_e32 v180, v180, v181
	v_add_f32_e32 v182, v182, v183
	v_add_f32_e32 v180, v180, v182
	s_nop 1
	v_add_f32_dpp v180, v180, v180 quad_perm:[1,0,3,2] row_mask:0xf bank_mask:0xf
	s_nop 1
	v_add_f32_dpp v180, v180, v180 quad_perm:[2,3,0,1] row_mask:0xf bank_mask:0xf
	s_nop 1
	v_add_f32_dpp v180, v180, v180 row_half_mirror row_mask:0xf bank_mask:0xf
	s_nop 1
	v_add_f32_dpp v180, v180, v180 row_mirror row_mask:0xf bank_mask:0xf
	s_nop 1
	v_add_f32_dpp v180, v180, v180 row_bcast:15 row_mask:0xa bank_mask:0xf
	s_nop 1
	v_add_f32_dpp v180, v180, v180 row_bcast:31 row_mask:0xc bank_mask:0xf
	s_nop 0
	v_readlane_b32 s20, v180, 63
	s_nop 1
	v_mov_b32_e32 v185, s20
	v_fma_f32 v185, v185, v2, v4
	v_rsq_f32_e32 v185, v185
	s_nop 0
	v_mul_f32_e32 v72, v72, v185
	v_mul_f32_e32 v73, v73, v185
	v_mul_f32_e32 v74, v74, v185
	v_mul_f32_e32 v75, v75, v185
	v_mul_f32_e32 v76, v76, v185
	v_mul_f32_e32 v77, v77, v185
	v_mul_f32_e32 v78, v78, v185
	v_mul_f32_e32 v79, v79, v185
	v_mul_f32_e32 v80, v80, v185
	v_mul_f32_e32 v81, v81, v185
	v_mul_f32_e32 v82, v82, v185
	v_mul_f32_e32 v83, v83, v185
	v_mul_f32_e32 v84, v84, v185
	v_mul_f32_e32 v85, v85, v185
	v_mul_f32_e32 v86, v86, v185
	v_mul_f32_e32 v87, v87, v185
	v_fma_f32 v72, v72, v8, v24
	v_fma_f32 v73, v73, v9, v25
	v_fma_f32 v74, v74, v10, v26
	v_fma_f32 v75, v75, v11, v27
	v_fma_f32 v76, v76, v12, v28
	v_fma_f32 v77, v77, v13, v29
	v_fma_f32 v78, v78, v14, v30
	v_fma_f32 v79, v79, v15, v31
	v_fma_f32 v80, v80, v16, v32
	v_fma_f32 v81, v81, v17, v33
	v_fma_f32 v82, v82, v18, v34
	v_fma_f32 v83, v83, v19, v35
	v_fma_f32 v84, v84, v20, v36
	v_fma_f32 v85, v85, v21, v37
	v_fma_f32 v86, v86, v22, v38
	v_fma_f32 v87, v87, v23, v39
	v_add_u32_e32 v171, 0xc00000, v1
	global_store_dwordx4 v171, v[72:75], s[4:5] nt
	global_store_dwordx4 v171, v[76:79], s[4:5] offset:1024 nt
	global_store_dwordx4 v171, v[80:83], s[4:5] offset:2048 nt
	global_store_dwordx4 v171, v[84:87], s[4:5] offset:3072 nt
	s_nop 1
	v_add_u32_e32 v170, 0x3c00000, v1
	global_load_dwordx4 v[72:75], v170, s[4:5] nt
	global_load_dwordx4 v[76:79], v170, s[4:5] offset:1024 nt
	global_load_dwordx4 v[80:83], v170, s[4:5] offset:2048 nt
	global_load_dwordx4 v[84:87], v170, s[4:5] offset:3072 nt
	s_waitcnt vmcnt(40)
	v_add_f32_e32 v180, v88, v89
	v_add_f32_e32 v181, v92, v93
	v_add_f32_e32 v182, v96, v97
	v_add_f32_e32 v183, v100, v101
	v_add_f32_e32 v180, v180, v90
	v_add_f32_e32 v181, v181, v94
	v_add_f32_e32 v182, v182, v98
	v_add_f32_e32 v183, v183, v102
	v_add_f32_e32 v180, v180, v91
	v_add_f32_e32 v181, v181, v95
	v_add_f32_e32 v182, v182, v99
	v_add_f32_e32 v183, v183, v103
	v_add_f32_e32 v180, v180, v181
	v_add_f32_e32 v182, v182, v183
	v_add_f32_e32 v180, v180, v182
	s_nop 1
	v_add_f32_dpp v180, v180, v180 quad_perm:[1,0,3,2] row_mask:0xf bank_mask:0xf
	s_nop 1
	v_add_f32_dpp v180, v180, v180 quad_perm:[2,3,0,1] row_mask:0xf bank_mask:0xf
	s_nop 1
	v_add_f32_dpp v180, v180, v180 row_half_mirror row_mask:0xf bank_mask:0xf
	s_nop 1
	v_add_f32_dpp v180, v180, v180 row_mirror row_mask:0xf bank_mask:0xf
	s_nop 1
	v_add_f32_dpp v180, v180, v180 row_bcast:15 row_mask:0xa bank_mask:0xf
	s_nop 1
	v_add_f32_dpp v180, v180, v180 row_bcast:31 row_mask:0xc bank_mask:0xf
	s_nop 0
	v_readlane_b32 s20, v180, 63
	s_nop 1
	v_mul_f32_e32 v184, s20, v2
	v_sub_f32_e32 v88, v88, v184
	v_sub_f32_e32 v89, v89, v184
	v_sub_f32_e32 v90, v90, v184
	v_sub_f32_e32 v91, v91, v184
	v_sub_f32_e32 v92, v92, v184
	v_sub_f32_e32 v93, v93, v184
	v_sub_f32_e32 v94, v94, v184
	v_sub_f32_e32 v95, v95, v184
	v_sub_f32_e32 v96, v96, v184
	v_sub_f32_e32 v97, v97, v184
	v_sub_f32_e32 v98, v98, v184
	v_sub_f32_e32 v99, v99, v184
	v_sub_f32_e32 v100, v100, v184
	v_sub_f32_e32 v101, v101, v184
	v_sub_f32_e32 v102, v102, v184
	v_sub_f32_e32 v103, v103, v184
	v_mul_f32_e32 v180, v88, v88
	v_mul_f32_e32 v181, v92, v92
	v_mul_f32_e32 v182, v96, v96
	v_mul_f32_e32 v183, v100, v100
	v_fmac_f32_e32 v180, v89, v89
	v_fmac_f32_e32 v181, v93, v93
	v_fmac_f32_e32 v182, v97, v97
	v_fmac_f32_e32 v183, v101, v101
	v_fmac_f32_e32 v180, v90, v90
	v_fmac_f32_e32 v181, v94, v94
	v_fmac_f32_e32 v182, v98, v98
	v_fmac_f32_e32 v183, v102, v102
	v_fmac_f32_e32 v180, v91, v91
	v_fmac_f32_e32 v181, v95, v95
	v_fmac_f32_e32 v182, v99, v99
	v_fmac_f32_e32 v183, v103, v103
	v_add_f32_e32 v180, v180, v181
	v_add_f32_e32 v182, v182, v183
	v_add_f32_e32 v180, v180, v182
	s_nop 1
	v_add_f32_dpp v180, v180, v180 quad_perm:[1,0,3,2] row_mask:0xf bank_mask:0xf
	s_nop 1
	v_add_f32_dpp v180, v180, v180 quad_perm:[2,3,0,1] row_mask:0xf bank_mask:0xf
	s_nop 1
	v_add_f32_dpp v180, v180, v180 row_half_mirror row_mask:0xf bank_mask:0xf
	s_nop 1
	v_add_f32_dpp v180, v180, v180 row_mirror row_mask:0xf bank_mask:0xf
	s_nop 1
	v_add_f32_dpp v180, v180, v180 row_bcast:15 row_mask:0xa bank_mask:0xf
	s_nop 1
	v_add_f32_dpp v180, v180, v180 row_bcast:31 row_mask:0xc bank_mask:0xf
	s_nop 0
	v_readlane_b32 s20, v180, 63
	s_nop 1
	v_mov_b32_e32 v185, s20
	v_fma_f32 v185, v185, v2, v4
	v_rsq_f32_e32 v185, v185
	s_nop 0
	v_mul_f32_e32 v88, v88, v185
	v_mul_f32_e32 v89, v89, v185
	v_mul_f32_e32 v90, v90, v185
	v_mul_f32_e32 v91, v91, v185
	v_mul_f32_e32 v92, v92, v185
	v_mul_f32_e32 v93, v93, v185
	v_mul_f32_e32 v94, v94, v185
	v_mul_f32_e32 v95, v95, v185
	v_mul_f32_e32 v96, v96, v185
	v_mul_f32_e32 v97, v97, v185
	v_mul_f32_e32 v98, v98, v185
	v_mul_f32_e32 v99, v99, v185
	v_mul_f32_e32 v100, v100, v185
	v_mul_f32_e32 v101, v101, v185
	v_mul_f32_e32 v102, v102, v185
	v_mul_f32_e32 v103, v103, v185
	v_fma_f32 v88, v88, v8, v24
	v_fma_f32 v89, v89, v9, v25
	v_fma_f32 v90, v90, v10, v26
	v_fma_f32 v91, v91, v11, v27
	v_fma_f32 v92, v92, v12, v28
	v_fma_f32 v93, v93, v13, v29
	v_fma_f32 v94, v94, v14, v30
	v_fma_f32 v95, v95, v15, v31
	v_fma_f32 v96, v96, v16, v32
	v_fma_f32 v97, v97, v17, v33
	v_fma_f32 v98, v98, v18, v34
	v_fma_f32 v99, v99, v19, v35
	v_fma_f32 v100, v100, v20, v36
	v_fma_f32 v101, v101, v21, v37
	v_fma_f32 v102, v102, v22, v38
	v_fma_f32 v103, v103, v23, v39
	v_add_u32_e32 v171, 0x1200000, v1
	global_store_dwordx4 v171, v[88:91], s[4:5] nt
	global_store_dwordx4 v171, v[92:95], s[4:5] offset:1024 nt
	global_store_dwordx4 v171, v[96:99], s[4:5] offset:2048 nt
	global_store_dwordx4 v171, v[100:103], s[4:5] offset:3072 nt
	s_waitcnt vmcnt(40)
	v_add_f32_e32 v180, v104, v105
	v_add_f32_e32 v181, v108, v109
	v_add_f32_e32 v182, v112, v113
	v_add_f32_e32 v183, v116, v117
	v_add_f32_e32 v180, v180, v106
	v_add_f32_e32 v181, v181, v110
	v_add_f32_e32 v182, v182, v114
	v_add_f32_e32 v183, v183, v118
	v_add_f32_e32 v180, v180, v107
	v_add_f32_e32 v181, v181, v111
	v_add_f32_e32 v182, v182, v115
	v_add_f32_e32 v183, v183, v119
	v_add_f32_e32 v180, v180, v181
	v_add_f32_e32 v182, v182, v183
	v_add_f32_e32 v180, v180, v182
	s_nop 1
	v_add_f32_dpp v180, v180, v180 quad_perm:[1,0,3,2] row_mask:0xf bank_mask:0xf
	s_nop 1
	v_add_f32_dpp v180, v180, v180 quad_perm:[2,3,0,1] row_mask:0xf bank_mask:0xf
	s_nop 1
	v_add_f32_dpp v180, v180, v180 row_half_mirror row_mask:0xf bank_mask:0xf
	s_nop 1
	v_add_f32_dpp v180, v180, v180 row_mirror row_mask:0xf bank_mask:0xf
	s_nop 1
	v_add_f32_dpp v180, v180, v180 row_bcast:15 row_mask:0xa bank_mask:0xf
	s_nop 1
	v_add_f32_dpp v180, v180, v180 row_bcast:31 row_mask:0xc bank_mask:0xf
	s_nop 0
	v_readlane_b32 s20, v180, 63
	s_nop 1
	v_mul_f32_e32 v184, s20, v2
	v_sub_f32_e32 v104, v104, v184
	v_sub_f32_e32 v105, v105, v184
	v_sub_f32_e32 v106, v106, v184
	v_sub_f32_e32 v107, v107, v184
	v_sub_f32_e32 v108, v108, v184
	v_sub_f32_e32 v109, v109, v184
	v_sub_f32_e32 v110, v110, v184
	v_sub_f32_e32 v111, v111, v184
	v_sub_f32_e32 v112, v112, v184
	v_sub_f32_e32 v113, v113, v184
	v_sub_f32_e32 v114, v114, v184
	v_sub_f32_e32 v115, v115, v184
	v_sub_f32_e32 v116, v116, v184
	v_sub_f32_e32 v117, v117, v184
	v_sub_f32_e32 v118, v118, v184
	v_sub_f32_e32 v119, v119, v184
	v_mul_f32_e32 v180, v104, v104
	v_mul_f32_e32 v181, v108, v108
	v_mul_f32_e32 v182, v112, v112
	v_mul_f32_e32 v183, v116, v116
	v_fmac_f32_e32 v180, v105, v105
	v_fmac_f32_e32 v181, v109, v109
	v_fmac_f32_e32 v182, v113, v113
	v_fmac_f32_e32 v183, v117, v117
	v_fmac_f32_e32 v180, v106, v106
	v_fmac_f32_e32 v181, v110, v110
	v_fmac_f32_e32 v182, v114, v114
	v_fmac_f32_e32 v183, v118, v118
	v_fmac_f32_e32 v180, v107, v107
	v_fmac_f32_e32 v181, v111, v111
	v_fmac_f32_e32 v182, v115, v115
	v_fmac_f32_e32 v183, v119, v119
	v_add_f32_e32 v180, v180, v181
	v_add_f32_e32 v182, v182, v183
	v_add_f32_e32 v180, v180, v182
	s_nop 1
	v_add_f32_dpp v180, v180, v180 quad_perm:[1,0,3,2] row_mask:0xf bank_mask:0xf
	s_nop 1
	v_add_f32_dpp v180, v180, v180 quad_perm:[2,3,0,1] row_mask:0xf bank_mask:0xf
	s_nop 1
	v_add_f32_dpp v180, v180, v180 row_half_mirror row_mask:0xf bank_mask:0xf
	s_nop 1
	v_add_f32_dpp v180, v180, v180 row_mirror row_mask:0xf bank_mask:0xf
	s_nop 1
	v_add_f32_dpp v180, v180, v180 row_bcast:15 row_mask:0xa bank_mask:0xf
	s_nop 1
	v_add_f32_dpp v180, v180, v180 row_bcast:31 row_mask:0xc bank_mask:0xf
	s_nop 0
	v_readlane_b32 s20, v180, 63
	s_nop 1
	v_mov_b32_e32 v185, s20
	v_fma_f32 v185, v185, v2, v4
	v_rsq_f32_e32 v185, v185
	s_nop 0
	v_mul_f32_e32 v104, v104, v185
	v_mul_f32_e32 v105, v105, v185
	v_mul_f32_e32 v106, v106, v185
	v_mul_f32_e32 v107, v107, v185
	v_mul_f32_e32 v108, v108, v185
	v_mul_f32_e32 v109, v109, v185
	v_mul_f32_e32 v110, v110, v185
	v_mul_f32_e32 v111, v111, v185
	v_mul_f32_e32 v112, v112, v185
	v_mul_f32_e32 v113, v113, v185
	v_mul_f32_e32 v114, v114, v185
	v_mul_f32_e32 v115, v115, v185
	v_mul_f32_e32 v116, v116, v185
	v_mul_f32_e32 v117, v117, v185
	v_mul_f32_e32 v118, v118, v185
	v_mul_f32_e32 v119, v119, v185
	v_fma_f32 v104, v104, v8, v24
	v_fma_f32 v105, v105, v9, v25
	v_fma_f32 v106, v106, v10, v26
	v_fma_f32 v107, v107, v11, v27
	v_fma_f32 v108, v108, v12, v28
	v_fma_f32 v109, v109, v13, v29
	v_fma_f32 v110, v110, v14, v30
	v_fma_f32 v111, v111, v15, v31
	v_fma_f32 v112, v112, v16, v32
	v_fma_f32 v113, v113, v17, v33
	v_fma_f32 v114, v114, v18, v34
	v_fma_f32 v115, v115, v19, v35
	v_fma_f32 v116, v116, v20, v36
	v_fma_f32 v117, v117, v21, v37
	v_fma_f32 v118, v118, v22, v38
	v_fma_f32 v119, v119, v23, v39
	v_add_u32_e32 v171, 0x1800000, v1
	global_store_dwordx4 v171, v[104:107], s[4:5] nt
	global_store_dwordx4 v171, v[108:111], s[4:5] offset:1024 nt
	global_store_dwordx4 v171, v[112:115], s[4:5] offset:2048 nt
	global_store_dwordx4 v171, v[116:119], s[4:5] offset:3072 nt
	s_waitcnt vmcnt(40)
	v_add_f32_e32 v180, v120, v121
	v_add_f32_e32 v181, v124, v125
	v_add_f32_e32 v182, v128, v129
	v_add_f32_e32 v183, v132, v133
	v_add_f32_e32 v180, v180, v122
	v_add_f32_e32 v181, v181, v126
	v_add_f32_e32 v182, v182, v130
	v_add_f32_e32 v183, v183, v134
	v_add_f32_e32 v180, v180, v123
	v_add_f32_e32 v181, v181, v127
	v_add_f32_e32 v182, v182, v131
	v_add_f32_e32 v183, v183, v135
	v_add_f32_e32 v180, v180, v181
	v_add_f32_e32 v182, v182, v183
	v_add_f32_e32 v180, v180, v182
	s_nop 1
	v_add_f32_dpp v180, v180, v180 quad_perm:[1,0,3,2] row_mask:0xf bank_mask:0xf
	s_nop 1
	v_add_f32_dpp v180, v180, v180 quad_perm:[2,3,0,1] row_mask:0xf bank_mask:0xf
	s_nop 1
	v_add_f32_dpp v180, v180, v180 row_half_mirror row_mask:0xf bank_mask:0xf
	s_nop 1
	v_add_f32_dpp v180, v180, v180 row_mirror row_mask:0xf bank_mask:0xf
	s_nop 1
	v_add_f32_dpp v180, v180, v180 row_bcast:15 row_mask:0xa bank_mask:0xf
	s_nop 1
	v_add_f32_dpp v180, v180, v180 row_bcast:31 row_mask:0xc bank_mask:0xf
	s_nop 0
	v_readlane_b32 s20, v180, 63
	s_nop 1
	v_mul_f32_e32 v184, s20, v2
	v_sub_f32_e32 v120, v120, v184
	v_sub_f32_e32 v121, v121, v184
	v_sub_f32_e32 v122, v122, v184
	v_sub_f32_e32 v123, v123, v184
	v_sub_f32_e32 v124, v124, v184
	v_sub_f32_e32 v125, v125, v184
	v_sub_f32_e32 v126, v126, v184
	v_sub_f32_e32 v127, v127, v184
	v_sub_f32_e32 v128, v128, v184
	v_sub_f32_e32 v129, v129, v184
	v_sub_f32_e32 v130, v130, v184
	v_sub_f32_e32 v131, v131, v184
	v_sub_f32_e32 v132, v132, v184
	v_sub_f32_e32 v133, v133, v184
	v_sub_f32_e32 v134, v134, v184
	v_sub_f32_e32 v135, v135, v184
	v_mul_f32_e32 v180, v120, v120
	v_mul_f32_e32 v181, v124, v124
	v_mul_f32_e32 v182, v128, v128
	v_mul_f32_e32 v183, v132, v132
	v_fmac_f32_e32 v180, v121, v121
	v_fmac_f32_e32 v181, v125, v125
	v_fmac_f32_e32 v182, v129, v129
	v_fmac_f32_e32 v183, v133, v133
	v_fmac_f32_e32 v180, v122, v122
	v_fmac_f32_e32 v181, v126, v126
	v_fmac_f32_e32 v182, v130, v130
	v_fmac_f32_e32 v183, v134, v134
	v_fmac_f32_e32 v180, v123, v123
	v_fmac_f32_e32 v181, v127, v127
	v_fmac_f32_e32 v182, v131, v131
	v_fmac_f32_e32 v183, v135, v135
	v_add_f32_e32 v180, v180, v181
	v_add_f32_e32 v182, v182, v183
	v_add_f32_e32 v180, v180, v182
	s_nop 1
	v_add_f32_dpp v180, v180, v180 quad_perm:[1,0,3,2] row_mask:0xf bank_mask:0xf
	s_nop 1
	v_add_f32_dpp v180, v180, v180 quad_perm:[2,3,0,1] row_mask:0xf bank_mask:0xf
	s_nop 1
	v_add_f32_dpp v180, v180, v180 row_half_mirror row_mask:0xf bank_mask:0xf
	s_nop 1
	v_add_f32_dpp v180, v180, v180 row_mirror row_mask:0xf bank_mask:0xf
	s_nop 1
	v_add_f32_dpp v180, v180, v180 row_bcast:15 row_mask:0xa bank_mask:0xf
	s_nop 1
	v_add_f32_dpp v180, v180, v180 row_bcast:31 row_mask:0xc bank_mask:0xf
	s_nop 0
	v_readlane_b32 s20, v180, 63
	s_nop 1
	v_mov_b32_e32 v185, s20
	v_fma_f32 v185, v185, v2, v4
	v_rsq_f32_e32 v185, v185
	s_nop 0
	v_mul_f32_e32 v120, v120, v185
	v_mul_f32_e32 v121, v121, v185
	v_mul_f32_e32 v122, v122, v185
	v_mul_f32_e32 v123, v123, v185
	v_mul_f32_e32 v124, v124, v185
	v_mul_f32_e32 v125, v125, v185
	v_mul_f32_e32 v126, v126, v185
	v_mul_f32_e32 v127, v127, v185
	v_mul_f32_e32 v128, v128, v185
	v_mul_f32_e32 v129, v129, v185
	v_mul_f32_e32 v130, v130, v185
	v_mul_f32_e32 v131, v131, v185
	v_mul_f32_e32 v132, v132, v185
	v_mul_f32_e32 v133, v133, v185
	v_mul_f32_e32 v134, v134, v185
	v_mul_f32_e32 v135, v135, v185
	v_fma_f32 v120, v120, v8, v24
	v_fma_f32 v121, v121, v9, v25
	v_fma_f32 v122, v122, v10, v26
	v_fma_f32 v123, v123, v11, v27
	v_fma_f32 v124, v124, v12, v28
	v_fma_f32 v125, v125, v13, v29
	v_fma_f32 v126, v126, v14, v30
	v_fma_f32 v127, v127, v15, v31
	v_fma_f32 v128, v128, v16, v32
	v_fma_f32 v129, v129, v17, v33
	v_fma_f32 v130, v130, v18, v34
	v_fma_f32 v131, v131, v19, v35
	v_fma_f32 v132, v132, v20, v36
	v_fma_f32 v133, v133, v21, v37
	v_fma_f32 v134, v134, v22, v38
	v_fma_f32 v135, v135, v23, v39
	v_add_u32_e32 v171, 0x1e00000, v1
	global_store_dwordx4 v171, v[120:123], s[4:5] nt
	global_store_dwordx4 v171, v[124:127], s[4:5] offset:1024 nt
	global_store_dwordx4 v171, v[128:131], s[4:5] offset:2048 nt
	global_store_dwordx4 v171, v[132:135], s[4:5] offset:3072 nt
	s_waitcnt vmcnt(40)
	v_add_f32_e32 v180, v136, v137
	v_add_f32_e32 v181, v140, v141
	v_add_f32_e32 v182, v144, v145
	v_add_f32_e32 v183, v148, v149
	v_add_f32_e32 v180, v180, v138
	v_add_f32_e32 v181, v181, v142
	v_add_f32_e32 v182, v182, v146
	v_add_f32_e32 v183, v183, v150
	v_add_f32_e32 v180, v180, v139
	v_add_f32_e32 v181, v181, v143
	v_add_f32_e32 v182, v182, v147
	v_add_f32_e32 v183, v183, v151
	v_add_f32_e32 v180, v180, v181
	v_add_f32_e32 v182, v182, v183
	v_add_f32_e32 v180, v180, v182
	s_nop 1
	v_add_f32_dpp v180, v180, v180 quad_perm:[1,0,3,2] row_mask:0xf bank_mask:0xf
	s_nop 1
	v_add_f32_dpp v180, v180, v180 quad_perm:[2,3,0,1] row_mask:0xf bank_mask:0xf
	s_nop 1
	v_add_f32_dpp v180, v180, v180 row_half_mirror row_mask:0xf bank_mask:0xf
	s_nop 1
	v_add_f32_dpp v180, v180, v180 row_mirror row_mask:0xf bank_mask:0xf
	s_nop 1
	v_add_f32_dpp v180, v180, v180 row_bcast:15 row_mask:0xa bank_mask:0xf
	s_nop 1
	v_add_f32_dpp v180, v180, v180 row_bcast:31 row_mask:0xc bank_mask:0xf
	s_nop 0
	v_readlane_b32 s20, v180, 63
	s_nop 1
	v_mul_f32_e32 v184, s20, v2
	v_sub_f32_e32 v136, v136, v184
	v_sub_f32_e32 v137, v137, v184
	v_sub_f32_e32 v138, v138, v184
	v_sub_f32_e32 v139, v139, v184
	v_sub_f32_e32 v140, v140, v184
	v_sub_f32_e32 v141, v141, v184
	v_sub_f32_e32 v142, v142, v184
	v_sub_f32_e32 v143, v143, v184
	v_sub_f32_e32 v144, v144, v184
	v_sub_f32_e32 v145, v145, v184
	v_sub_f32_e32 v146, v146, v184
	v_sub_f32_e32 v147, v147, v184
	v_sub_f32_e32 v148, v148, v184
	v_sub_f32_e32 v149, v149, v184
	v_sub_f32_e32 v150, v150, v184
	v_sub_f32_e32 v151, v151, v184
	v_mul_f32_e32 v180, v136, v136
	v_mul_f32_e32 v181, v140, v140
	v_mul_f32_e32 v182, v144, v144
	v_mul_f32_e32 v183, v148, v148
	v_fmac_f32_e32 v180, v137, v137
	v_fmac_f32_e32 v181, v141, v141
	v_fmac_f32_e32 v182, v145, v145
	v_fmac_f32_e32 v183, v149, v149
	v_fmac_f32_e32 v180, v138, v138
	v_fmac_f32_e32 v181, v142, v142
	v_fmac_f32_e32 v182, v146, v146
	v_fmac_f32_e32 v183, v150, v150
	v_fmac_f32_e32 v180, v139, v139
	v_fmac_f32_e32 v181, v143, v143
	v_fmac_f32_e32 v182, v147, v147
	v_fmac_f32_e32 v183, v151, v151
	v_add_f32_e32 v180, v180, v181
	v_add_f32_e32 v182, v182, v183
	v_add_f32_e32 v180, v180, v182
	s_nop 1
	v_add_f32_dpp v180, v180, v180 quad_perm:[1,0,3,2] row_mask:0xf bank_mask:0xf
	s_nop 1
	v_add_f32_dpp v180, v180, v180 quad_perm:[2,3,0,1] row_mask:0xf bank_mask:0xf
	s_nop 1
	v_add_f32_dpp v180, v180, v180 row_half_mirror row_mask:0xf bank_mask:0xf
	s_nop 1
	v_add_f32_dpp v180, v180, v180 row_mirror row_mask:0xf bank_mask:0xf
	s_nop 1
	v_add_f32_dpp v180, v180, v180 row_bcast:15 row_mask:0xa bank_mask:0xf
	s_nop 1
	v_add_f32_dpp v180, v180, v180 row_bcast:31 row_mask:0xc bank_mask:0xf
	s_nop 0
	v_readlane_b32 s20, v180, 63
	s_nop 1
	v_mov_b32_e32 v185, s20
	v_fma_f32 v185, v185, v2, v4
	v_rsq_f32_e32 v185, v185
	s_nop 0
	v_mul_f32_e32 v136, v136, v185
	v_mul_f32_e32 v137, v137, v185
	v_mul_f32_e32 v138, v138, v185
	v_mul_f32_e32 v139, v139, v185
	v_mul_f32_e32 v140, v140, v185
	v_mul_f32_e32 v141, v141, v185
	v_mul_f32_e32 v142, v142, v185
	v_mul_f32_e32 v143, v143, v185
	v_mul_f32_e32 v144, v144, v185
	v_mul_f32_e32 v145, v145, v185
	v_mul_f32_e32 v146, v146, v185
	v_mul_f32_e32 v147, v147, v185
	v_mul_f32_e32 v148, v148, v185
	v_mul_f32_e32 v149, v149, v185
	v_mul_f32_e32 v150, v150, v185
	v_mul_f32_e32 v151, v151, v185
	v_fma_f32 v136, v136, v8, v24
	v_fma_f32 v137, v137, v9, v25
	v_fma_f32 v138, v138, v10, v26
	v_fma_f32 v139, v139, v11, v27
	v_fma_f32 v140, v140, v12, v28
	v_fma_f32 v141, v141, v13, v29
	v_fma_f32 v142, v142, v14, v30
	v_fma_f32 v143, v143, v15, v31
	v_fma_f32 v144, v144, v16, v32
	v_fma_f32 v145, v145, v17, v33
	v_fma_f32 v146, v146, v18, v34
	v_fma_f32 v147, v147, v19, v35
	v_fma_f32 v148, v148, v20, v36
	v_fma_f32 v149, v149, v21, v37
	v_fma_f32 v150, v150, v22, v38
	v_fma_f32 v151, v151, v23, v39
	v_add_u32_e32 v171, 0x2400000, v1
	global_store_dwordx4 v171, v[136:139], s[4:5] nt
	global_store_dwordx4 v171, v[140:143], s[4:5] offset:1024 nt
	global_store_dwordx4 v171, v[144:147], s[4:5] offset:2048 nt
	global_store_dwordx4 v171, v[148:151], s[4:5] offset:3072 nt
	s_waitcnt vmcnt(40)
	v_add_f32_e32 v180, v152, v153
	v_add_f32_e32 v181, v156, v157
	v_add_f32_e32 v182, v160, v161
	v_add_f32_e32 v183, v164, v165
	v_add_f32_e32 v180, v180, v154
	v_add_f32_e32 v181, v181, v158
	v_add_f32_e32 v182, v182, v162
	v_add_f32_e32 v183, v183, v166
	v_add_f32_e32 v180, v180, v155
	v_add_f32_e32 v181, v181, v159
	v_add_f32_e32 v182, v182, v163
	v_add_f32_e32 v183, v183, v167
	v_add_f32_e32 v180, v180, v181
	v_add_f32_e32 v182, v182, v183
	v_add_f32_e32 v180, v180, v182
	s_nop 1
	v_add_f32_dpp v180, v180, v180 quad_perm:[1,0,3,2] row_mask:0xf bank_mask:0xf
	s_nop 1
	v_add_f32_dpp v180, v180, v180 quad_perm:[2,3,0,1] row_mask:0xf bank_mask:0xf
	s_nop 1
	v_add_f32_dpp v180, v180, v180 row_half_mirror row_mask:0xf bank_mask:0xf
	s_nop 1
	v_add_f32_dpp v180, v180, v180 row_mirror row_mask:0xf bank_mask:0xf
	s_nop 1
	v_add_f32_dpp v180, v180, v180 row_bcast:15 row_mask:0xa bank_mask:0xf
	s_nop 1
	v_add_f32_dpp v180, v180, v180 row_bcast:31 row_mask:0xc bank_mask:0xf
	s_nop 0
	v_readlane_b32 s20, v180, 63
	s_nop 1
	v_mul_f32_e32 v184, s20, v2
	v_sub_f32_e32 v152, v152, v184
	v_sub_f32_e32 v153, v153, v184
	v_sub_f32_e32 v154, v154, v184
	v_sub_f32_e32 v155, v155, v184
	v_sub_f32_e32 v156, v156, v184
	v_sub_f32_e32 v157, v157, v184
	v_sub_f32_e32 v158, v158, v184
	v_sub_f32_e32 v159, v159, v184
	v_sub_f32_e32 v160, v160, v184
	v_sub_f32_e32 v161, v161, v184
	v_sub_f32_e32 v162, v162, v184
	v_sub_f32_e32 v163, v163, v184
	v_sub_f32_e32 v164, v164, v184
	v_sub_f32_e32 v165, v165, v184
	v_sub_f32_e32 v166, v166, v184
	v_sub_f32_e32 v167, v167, v184
	v_mul_f32_e32 v180, v152, v152
	v_mul_f32_e32 v181, v156, v156
	v_mul_f32_e32 v182, v160, v160
	v_mul_f32_e32 v183, v164, v164
	v_fmac_f32_e32 v180, v153, v153
	v_fmac_f32_e32 v181, v157, v157
	v_fmac_f32_e32 v182, v161, v161
	v_fmac_f32_e32 v183, v165, v165
	v_fmac_f32_e32 v180, v154, v154
	v_fmac_f32_e32 v181, v158, v158
	v_fmac_f32_e32 v182, v162, v162
	v_fmac_f32_e32 v183, v166, v166
	v_fmac_f32_e32 v180, v155, v155
	v_fmac_f32_e32 v181, v159, v159
	v_fmac_f32_e32 v182, v163, v163
	v_fmac_f32_e32 v183, v167, v167
	v_add_f32_e32 v180, v180, v181
	v_add_f32_e32 v182, v182, v183
	v_add_f32_e32 v180, v180, v182
	s_nop 1
	v_add_f32_dpp v180, v180, v180 quad_perm:[1,0,3,2] row_mask:0xf bank_mask:0xf
	s_nop 1
	v_add_f32_dpp v180, v180, v180 quad_perm:[2,3,0,1] row_mask:0xf bank_mask:0xf
	s_nop 1
	v_add_f32_dpp v180, v180, v180 row_half_mirror row_mask:0xf bank_mask:0xf
	s_nop 1
	v_add_f32_dpp v180, v180, v180 row_mirror row_mask:0xf bank_mask:0xf
	s_nop 1
	v_add_f32_dpp v180, v180, v180 row_bcast:15 row_mask:0xa bank_mask:0xf
	s_nop 1
	v_add_f32_dpp v180, v180, v180 row_bcast:31 row_mask:0xc bank_mask:0xf
	s_nop 0
	v_readlane_b32 s20, v180, 63
	s_nop 1
	v_mov_b32_e32 v185, s20
	v_fma_f32 v185, v185, v2, v4
	v_rsq_f32_e32 v185, v185
	s_nop 0
	v_mul_f32_e32 v152, v152, v185
	v_mul_f32_e32 v153, v153, v185
	v_mul_f32_e32 v154, v154, v185
	v_mul_f32_e32 v155, v155, v185
	v_mul_f32_e32 v156, v156, v185
	v_mul_f32_e32 v157, v157, v185
	v_mul_f32_e32 v158, v158, v185
	v_mul_f32_e32 v159, v159, v185
	v_mul_f32_e32 v160, v160, v185
	v_mul_f32_e32 v161, v161, v185
	v_mul_f32_e32 v162, v162, v185
	v_mul_f32_e32 v163, v163, v185
	v_mul_f32_e32 v164, v164, v185
	v_mul_f32_e32 v165, v165, v185
	v_mul_f32_e32 v166, v166, v185
	v_mul_f32_e32 v167, v167, v185
	v_fma_f32 v152, v152, v8, v24
	v_fma_f32 v153, v153, v9, v25
	v_fma_f32 v154, v154, v10, v26
	v_fma_f32 v155, v155, v11, v27
	v_fma_f32 v156, v156, v12, v28
	v_fma_f32 v157, v157, v13, v29
	v_fma_f32 v158, v158, v14, v30
	v_fma_f32 v159, v159, v15, v31
	v_fma_f32 v160, v160, v16, v32
	v_fma_f32 v161, v161, v17, v33
	v_fma_f32 v162, v162, v18, v34
	v_fma_f32 v163, v163, v19, v35
	v_fma_f32 v164, v164, v20, v36
	v_fma_f32 v165, v165, v21, v37
	v_fma_f32 v166, v166, v22, v38
	v_fma_f32 v167, v167, v23, v39
	v_add_u32_e32 v171, 0x2a00000, v1
	global_store_dwordx4 v171, v[152:155], s[4:5] nt
	global_store_dwordx4 v171, v[156:159], s[4:5] offset:1024 nt
	global_store_dwordx4 v171, v[160:163], s[4:5] offset:2048 nt
	global_store_dwordx4 v171, v[164:167], s[4:5] offset:3072 nt
	s_waitcnt vmcnt(36)
	v_add_f32_e32 v180, v40, v41
	v_add_f32_e32 v181, v44, v45
	v_add_f32_e32 v182, v48, v49
	v_add_f32_e32 v183, v52, v53
	v_add_f32_e32 v180, v180, v42
	v_add_f32_e32 v181, v181, v46
	v_add_f32_e32 v182, v182, v50
	v_add_f32_e32 v183, v183, v54
	v_add_f32_e32 v180, v180, v43
	v_add_f32_e32 v181, v181, v47
	v_add_f32_e32 v182, v182, v51
	v_add_f32_e32 v183, v183, v55
	v_add_f32_e32 v180, v180, v181
	v_add_f32_e32 v182, v182, v183
	v_add_f32_e32 v180, v180, v182
	s_nop 1
	v_add_f32_dpp v180, v180, v180 quad_perm:[1,0,3,2] row_mask:0xf bank_mask:0xf
	s_nop 1
	v_add_f32_dpp v180, v180, v180 quad_perm:[2,3,0,1] row_mask:0xf bank_mask:0xf
	s_nop 1
	v_add_f32_dpp v180, v180, v180 row_half_mirror row_mask:0xf bank_mask:0xf
	s_nop 1
	v_add_f32_dpp v180, v180, v180 row_mirror row_mask:0xf bank_mask:0xf
	s_nop 1
	v_add_f32_dpp v180, v180, v180 row_bcast:15 row_mask:0xa bank_mask:0xf
	s_nop 1
	v_add_f32_dpp v180, v180, v180 row_bcast:31 row_mask:0xc bank_mask:0xf
	s_nop 0
	v_readlane_b32 s20, v180, 63
	s_nop 1
	v_mul_f32_e32 v184, s20, v2
	v_sub_f32_e32 v40, v40, v184
	v_sub_f32_e32 v41, v41, v184
	v_sub_f32_e32 v42, v42, v184
	v_sub_f32_e32 v43, v43, v184
	v_sub_f32_e32 v44, v44, v184
	v_sub_f32_e32 v45, v45, v184
	v_sub_f32_e32 v46, v46, v184
	v_sub_f32_e32 v47, v47, v184
	v_sub_f32_e32 v48, v48, v184
	v_sub_f32_e32 v49, v49, v184
	v_sub_f32_e32 v50, v50, v184
	v_sub_f32_e32 v51, v51, v184
	v_sub_f32_e32 v52, v52, v184
	v_sub_f32_e32 v53, v53, v184
	v_sub_f32_e32 v54, v54, v184
	v_sub_f32_e32 v55, v55, v184
	v_mul_f32_e32 v180, v40, v40
	v_mul_f32_e32 v181, v44, v44
	v_mul_f32_e32 v182, v48, v48
	v_mul_f32_e32 v183, v52, v52
	v_fmac_f32_e32 v180, v41, v41
	v_fmac_f32_e32 v181, v45, v45
	v_fmac_f32_e32 v182, v49, v49
	v_fmac_f32_e32 v183, v53, v53
	v_fmac_f32_e32 v180, v42, v42
	v_fmac_f32_e32 v181, v46, v46
	v_fmac_f32_e32 v182, v50, v50
	v_fmac_f32_e32 v183, v54, v54
	v_fmac_f32_e32 v180, v43, v43
	v_fmac_f32_e32 v181, v47, v47
	v_fmac_f32_e32 v182, v51, v51
	v_fmac_f32_e32 v183, v55, v55
	v_add_f32_e32 v180, v180, v181
	v_add_f32_e32 v182, v182, v183
	v_add_f32_e32 v180, v180, v182
	s_nop 1
	v_add_f32_dpp v180, v180, v180 quad_perm:[1,0,3,2] row_mask:0xf bank_mask:0xf
	s_nop 1
	v_add_f32_dpp v180, v180, v180 quad_perm:[2,3,0,1] row_mask:0xf bank_mask:0xf
	s_nop 1
	v_add_f32_dpp v180, v180, v180 row_half_mirror row_mask:0xf bank_mask:0xf
	s_nop 1
	v_add_f32_dpp v180, v180, v180 row_mirror row_mask:0xf bank_mask:0xf
	s_nop 1
	v_add_f32_dpp v180, v180, v180 row_bcast:15 row_mask:0xa bank_mask:0xf
	s_nop 1
	v_add_f32_dpp v180, v180, v180 row_bcast:31 row_mask:0xc bank_mask:0xf
	s_nop 0
	v_readlane_b32 s20, v180, 63
	s_nop 1
	v_mov_b32_e32 v185, s20
	v_fma_f32 v185, v185, v2, v4
	v_rsq_f32_e32 v185, v185
	s_nop 0
	v_mul_f32_e32 v40, v40, v185
	v_mul_f32_e32 v41, v41, v185
	v_mul_f32_e32 v42, v42, v185
	v_mul_f32_e32 v43, v43, v185
	v_mul_f32_e32 v44, v44, v185
	v_mul_f32_e32 v45, v45, v185
	v_mul_f32_e32 v46, v46, v185
	v_mul_f32_e32 v47, v47, v185
	v_mul_f32_e32 v48, v48, v185
	v_mul_f32_e32 v49, v49, v185
	v_mul_f32_e32 v50, v50, v185
	v_mul_f32_e32 v51, v51, v185
	v_mul_f32_e32 v52, v52, v185
	v_mul_f32_e32 v53, v53, v185
	v_mul_f32_e32 v54, v54, v185
	v_mul_f32_e32 v55, v55, v185
	v_fma_f32 v40, v40, v8, v24
	v_fma_f32 v41, v41, v9, v25
	v_fma_f32 v42, v42, v10, v26
	v_fma_f32 v43, v43, v11, v27
	v_fma_f32 v44, v44, v12, v28
	v_fma_f32 v45, v45, v13, v29
	v_fma_f32 v46, v46, v14, v30
	v_fma_f32 v47, v47, v15, v31
	v_fma_f32 v48, v48, v16, v32
	v_fma_f32 v49, v49, v17, v33
	v_fma_f32 v50, v50, v18, v34
	v_fma_f32 v51, v51, v19, v35
	v_fma_f32 v52, v52, v20, v36
	v_fma_f32 v53, v53, v21, v37
	v_fma_f32 v54, v54, v22, v38
	v_fma_f32 v55, v55, v23, v39
	v_add_u32_e32 v171, 0x3000000, v1
	global_store_dwordx4 v171, v[40:43], s[4:5] nt
	global_store_dwordx4 v171, v[44:47], s[4:5] offset:1024 nt
	global_store_dwordx4 v171, v[48:51], s[4:5] offset:2048 nt
	global_store_dwordx4 v171, v[52:55], s[4:5] offset:3072 nt
	s_waitcnt vmcnt(32)
	v_add_f32_e32 v180, v56, v57
	v_add_f32_e32 v181, v60, v61
	v_add_f32_e32 v182, v64, v65
	v_add_f32_e32 v183, v68, v69
	v_add_f32_e32 v180, v180, v58
	v_add_f32_e32 v181, v181, v62
	v_add_f32_e32 v182, v182, v66
	v_add_f32_e32 v183, v183, v70
	v_add_f32_e32 v180, v180, v59
	v_add_f32_e32 v181, v181, v63
	v_add_f32_e32 v182, v182, v67
	v_add_f32_e32 v183, v183, v71
	v_add_f32_e32 v180, v180, v181
	v_add_f32_e32 v182, v182, v183
	v_add_f32_e32 v180, v180, v182
	s_nop 1
	v_add_f32_dpp v180, v180, v180 quad_perm:[1,0,3,2] row_mask:0xf bank_mask:0xf
	s_nop 1
	v_add_f32_dpp v180, v180, v180 quad_perm:[2,3,0,1] row_mask:0xf bank_mask:0xf
	s_nop 1
	v_add_f32_dpp v180, v180, v180 row_half_mirror row_mask:0xf bank_mask:0xf
	s_nop 1
	v_add_f32_dpp v180, v180, v180 row_mirror row_mask:0xf bank_mask:0xf
	s_nop 1
	v_add_f32_dpp v180, v180, v180 row_bcast:15 row_mask:0xa bank_mask:0xf
	s_nop 1
	v_add_f32_dpp v180, v180, v180 row_bcast:31 row_mask:0xc bank_mask:0xf
	s_nop 0
	v_readlane_b32 s20, v180, 63
	s_nop 1
	v_mul_f32_e32 v184, s20, v2
	v_sub_f32_e32 v56, v56, v184
	v_sub_f32_e32 v57, v57, v184
	v_sub_f32_e32 v58, v58, v184
	v_sub_f32_e32 v59, v59, v184
	v_sub_f32_e32 v60, v60, v184
	v_sub_f32_e32 v61, v61, v184
	v_sub_f32_e32 v62, v62, v184
	v_sub_f32_e32 v63, v63, v184
	v_sub_f32_e32 v64, v64, v184
	v_sub_f32_e32 v65, v65, v184
	v_sub_f32_e32 v66, v66, v184
	v_sub_f32_e32 v67, v67, v184
	v_sub_f32_e32 v68, v68, v184
	v_sub_f32_e32 v69, v69, v184
	v_sub_f32_e32 v70, v70, v184
	v_sub_f32_e32 v71, v71, v184
	v_mul_f32_e32 v180, v56, v56
	v_mul_f32_e32 v181, v60, v60
	v_mul_f32_e32 v182, v64, v64
	v_mul_f32_e32 v183, v68, v68
	v_fmac_f32_e32 v180, v57, v57
	v_fmac_f32_e32 v181, v61, v61
	v_fmac_f32_e32 v182, v65, v65
	v_fmac_f32_e32 v183, v69, v69
	v_fmac_f32_e32 v180, v58, v58
	v_fmac_f32_e32 v181, v62, v62
	v_fmac_f32_e32 v182, v66, v66
	v_fmac_f32_e32 v183, v70, v70
	v_fmac_f32_e32 v180, v59, v59
	v_fmac_f32_e32 v181, v63, v63
	v_fmac_f32_e32 v182, v67, v67
	v_fmac_f32_e32 v183, v71, v71
	v_add_f32_e32 v180, v180, v181
	v_add_f32_e32 v182, v182, v183
	v_add_f32_e32 v180, v180, v182
	s_nop 1
	v_add_f32_dpp v180, v180, v180 quad_perm:[1,0,3,2] row_mask:0xf bank_mask:0xf
	s_nop 1
	v_add_f32_dpp v180, v180, v180 quad_perm:[2,3,0,1] row_mask:0xf bank_mask:0xf
	s_nop 1
	v_add_f32_dpp v180, v180, v180 row_half_mirror row_mask:0xf bank_mask:0xf
	s_nop 1
	v_add_f32_dpp v180, v180, v180 row_mirror row_mask:0xf bank_mask:0xf
	s_nop 1
	v_add_f32_dpp v180, v180, v180 row_bcast:15 row_mask:0xa bank_mask:0xf
	s_nop 1
	v_add_f32_dpp v180, v180, v180 row_bcast:31 row_mask:0xc bank_mask:0xf
	s_nop 0
	v_readlane_b32 s20, v180, 63
	s_nop 1
	v_mov_b32_e32 v185, s20
	v_fma_f32 v185, v185, v2, v4
	v_rsq_f32_e32 v185, v185
	s_nop 0
	v_mul_f32_e32 v56, v56, v185
	v_mul_f32_e32 v57, v57, v185
	v_mul_f32_e32 v58, v58, v185
	v_mul_f32_e32 v59, v59, v185
	v_mul_f32_e32 v60, v60, v185
	v_mul_f32_e32 v61, v61, v185
	v_mul_f32_e32 v62, v62, v185
	v_mul_f32_e32 v63, v63, v185
	v_mul_f32_e32 v64, v64, v185
	v_mul_f32_e32 v65, v65, v185
	v_mul_f32_e32 v66, v66, v185
	v_mul_f32_e32 v67, v67, v185
	v_mul_f32_e32 v68, v68, v185
	v_mul_f32_e32 v69, v69, v185
	v_mul_f32_e32 v70, v70, v185
	v_mul_f32_e32 v71, v71, v185
	v_fma_f32 v56, v56, v8, v24
	v_fma_f32 v57, v57, v9, v25
	v_fma_f32 v58, v58, v10, v26
	v_fma_f32 v59, v59, v11, v27
	v_fma_f32 v60, v60, v12, v28
	v_fma_f32 v61, v61, v13, v29
	v_fma_f32 v62, v62, v14, v30
	v_fma_f32 v63, v63, v15, v31
	v_fma_f32 v64, v64, v16, v32
	v_fma_f32 v65, v65, v17, v33
	v_fma_f32 v66, v66, v18, v34
	v_fma_f32 v67, v67, v19, v35
	v_fma_f32 v68, v68, v20, v36
	v_fma_f32 v69, v69, v21, v37
	v_fma_f32 v70, v70, v22, v38
	v_fma_f32 v71, v71, v23, v39
	v_add_u32_e32 v171, 0x3600000, v1
	global_store_dwordx4 v171, v[56:59], s[4:5] nt
	global_store_dwordx4 v171, v[60:63], s[4:5] offset:1024 nt
	global_store_dwordx4 v171, v[64:67], s[4:5] offset:2048 nt
	global_store_dwordx4 v171, v[68:71], s[4:5] offset:3072 nt
	s_waitcnt vmcnt(28)
	v_add_f32_e32 v180, v72, v73
	v_add_f32_e32 v181, v76, v77
	v_add_f32_e32 v182, v80, v81
	v_add_f32_e32 v183, v84, v85
	v_add_f32_e32 v180, v180, v74
	v_add_f32_e32 v181, v181, v78
	v_add_f32_e32 v182, v182, v82
	v_add_f32_e32 v183, v183, v86
	v_add_f32_e32 v180, v180, v75
	v_add_f32_e32 v181, v181, v79
	v_add_f32_e32 v182, v182, v83
	v_add_f32_e32 v183, v183, v87
	v_add_f32_e32 v180, v180, v181
	v_add_f32_e32 v182, v182, v183
	v_add_f32_e32 v180, v180, v182
	s_nop 1
	v_add_f32_dpp v180, v180, v180 quad_perm:[1,0,3,2] row_mask:0xf bank_mask:0xf
	s_nop 1
	v_add_f32_dpp v180, v180, v180 quad_perm:[2,3,0,1] row_mask:0xf bank_mask:0xf
	s_nop 1
	v_add_f32_dpp v180, v180, v180 row_half_mirror row_mask:0xf bank_mask:0xf
	s_nop 1
	v_add_f32_dpp v180, v180, v180 row_mirror row_mask:0xf bank_mask:0xf
	s_nop 1
	v_add_f32_dpp v180, v180, v180 row_bcast:15 row_mask:0xa bank_mask:0xf
	s_nop 1
	v_add_f32_dpp v180, v180, v180 row_bcast:31 row_mask:0xc bank_mask:0xf
	s_nop 0
	v_readlane_b32 s20, v180, 63
	s_nop 1
	v_mul_f32_e32 v184, s20, v2
	v_sub_f32_e32 v72, v72, v184
	v_sub_f32_e32 v73, v73, v184
	v_sub_f32_e32 v74, v74, v184
	v_sub_f32_e32 v75, v75, v184
	v_sub_f32_e32 v76, v76, v184
	v_sub_f32_e32 v77, v77, v184
	v_sub_f32_e32 v78, v78, v184
	v_sub_f32_e32 v79, v79, v184
	v_sub_f32_e32 v80, v80, v184
	v_sub_f32_e32 v81, v81, v184
	v_sub_f32_e32 v82, v82, v184
	v_sub_f32_e32 v83, v83, v184
	v_sub_f32_e32 v84, v84, v184
	v_sub_f32_e32 v85, v85, v184
	v_sub_f32_e32 v86, v86, v184
	v_sub_f32_e32 v87, v87, v184
	v_mul_f32_e32 v180, v72, v72
	v_mul_f32_e32 v181, v76, v76
	v_mul_f32_e32 v182, v80, v80
	v_mul_f32_e32 v183, v84, v84
	v_fmac_f32_e32 v180, v73, v73
	v_fmac_f32_e32 v181, v77, v77
	v_fmac_f32_e32 v182, v81, v81
	v_fmac_f32_e32 v183, v85, v85
	v_fmac_f32_e32 v180, v74, v74
	v_fmac_f32_e32 v181, v78, v78
	v_fmac_f32_e32 v182, v82, v82
	v_fmac_f32_e32 v183, v86, v86
	v_fmac_f32_e32 v180, v75, v75
	v_fmac_f32_e32 v181, v79, v79
	v_fmac_f32_e32 v182, v83, v83
	v_fmac_f32_e32 v183, v87, v87
	v_add_f32_e32 v180, v180, v181
	v_add_f32_e32 v182, v182, v183
	v_add_f32_e32 v180, v180, v182
	s_nop 1
	v_add_f32_dpp v180, v180, v180 quad_perm:[1,0,3,2] row_mask:0xf bank_mask:0xf
	s_nop 1
	v_add_f32_dpp v180, v180, v180 quad_perm:[2,3,0,1] row_mask:0xf bank_mask:0xf
	s_nop 1
	v_add_f32_dpp v180, v180, v180 row_half_mirror row_mask:0xf bank_mask:0xf
	s_nop 1
	v_add_f32_dpp v180, v180, v180 row_mirror row_mask:0xf bank_mask:0xf
	s_nop 1
	v_add_f32_dpp v180, v180, v180 row_bcast:15 row_mask:0xa bank_mask:0xf
	s_nop 1
	v_add_f32_dpp v180, v180, v180 row_bcast:31 row_mask:0xc bank_mask:0xf
	s_nop 0
	v_readlane_b32 s20, v180, 63
	s_nop 1
	v_mov_b32_e32 v185, s20
	v_fma_f32 v185, v185, v2, v4
	v_rsq_f32_e32 v185, v185
	s_nop 0
	v_mul_f32_e32 v72, v72, v185
	v_mul_f32_e32 v73, v73, v185
	v_mul_f32_e32 v74, v74, v185
	v_mul_f32_e32 v75, v75, v185
	v_mul_f32_e32 v76, v76, v185
	v_mul_f32_e32 v77, v77, v185
	v_mul_f32_e32 v78, v78, v185
	v_mul_f32_e32 v79, v79, v185
	v_mul_f32_e32 v80, v80, v185
	v_mul_f32_e32 v81, v81, v185
	v_mul_f32_e32 v82, v82, v185
	v_mul_f32_e32 v83, v83, v185
	v_mul_f32_e32 v84, v84, v185
	v_mul_f32_e32 v85, v85, v185
	v_mul_f32_e32 v86, v86, v185
	v_mul_f32_e32 v87, v87, v185
	v_fma_f32 v72, v72, v8, v24
	v_fma_f32 v73, v73, v9, v25
	v_fma_f32 v74, v74, v10, v26
	v_fma_f32 v75, v75, v11, v27
	v_fma_f32 v76, v76, v12, v28
	v_fma_f32 v77, v77, v13, v29
	v_fma_f32 v78, v78, v14, v30
	v_fma_f32 v79, v79, v15, v31
	v_fma_f32 v80, v80, v16, v32
	v_fma_f32 v81, v81, v17, v33
	v_fma_f32 v82, v82, v18, v34
	v_fma_f32 v83, v83, v19, v35
	v_fma_f32 v84, v84, v20, v36
	v_fma_f32 v85, v85, v21, v37
	v_fma_f32 v86, v86, v22, v38
	v_fma_f32 v87, v87, v23, v39
	v_add_u32_e32 v171, 0x3c00000, v1
	global_store_dwordx4 v171, v[72:75], s[4:5] nt
	global_store_dwordx4 v171, v[76:79], s[4:5] offset:1024 nt
	global_store_dwordx4 v171, v[80:83], s[4:5] offset:2048 nt
	global_store_dwordx4 v171, v[84:87], s[4:5] offset:3072 nt
	s_branch .Ltr_29
.Llo_r10:
	global_load_dwordx4 v[40:43], v1, s[4:5] nt
	global_load_dwordx4 v[44:47], v1, s[4:5] offset:1024 nt
	global_load_dwordx4 v[48:51], v1, s[4:5] offset:2048 nt
	global_load_dwordx4 v[52:55], v1, s[4:5] offset:3072 nt
	global_load_dwordx4 v[8:11], v1, s[40:41]
	global_load_dwordx4 v[12:15], v1, s[40:41] offset:1024
	global_load_dwordx4 v[16:19], v1, s[40:41] offset:2048
	global_load_dwordx4 v[20:23], v1, s[40:41] offset:3072
	global_load_dwordx4 v[24:27], v1, s[42:43]
	global_load_dwordx4 v[28:31], v1, s[42:43] offset:1024
	global_load_dwordx4 v[32:35], v1, s[42:43] offset:2048
	global_load_dwordx4 v[36:39], v1, s[42:43] offset:3072
	v_add_u32_e32 v170, 0x600000, v1
	global_load_dwordx4 v[56:59], v170, s[4:5] nt
	global_load_dwordx4 v[60:63], v170, s[4:5] offset:1024 nt
	global_load_dwordx4 v[64:67], v170, s[4:5] offset:2048 nt
	global_load_dwordx4 v[68:71], v170, s[4:5] offset:3072 nt
	v_add_u32_e32 v170, 0xc00000, v1
	global_load_dwordx4 v[72:75], v170, s[4:5] nt
	global_load_dwordx4 v[76:79], v170, s[4:5] offset:1024 nt
	global_load_dwordx4 v[80:83], v170, s[4:5] offset:2048 nt
	global_load_dwordx4 v[84:87], v170, s[4:5] offset:3072 nt
	v_add_u32_e32 v170, 0x1200000, v1
	global_load_dwordx4 v[88:91], v170, s[4:5] nt
	global_load_dwordx4 v[92:95], v170, s[4:5] offset:1024 nt
	global_load_dwordx4 v[96:99], v170, s[4:5] offset:2048 nt
	global_load_dwordx4 v[100:103], v170, s[4:5] offset:3072 nt
	v_add_u32_e32 v170, 0x1800000, v1
	global_load_dwordx4 v[104:107], v170, s[4:5] nt
	global_load_dwordx4 v[108:111], v170, s[4:5] offset:1024 nt
	global_load_dwordx4 v[112:115], v170, s[4:5] offset:2048 nt
	global_load_dwordx4 v[116:119], v170, s[4:5] offset:3072 nt
	v_add_u32_e32 v170, 0x1e00000, v1
	global_load_dwordx4 v[120:123], v170, s[4:5] nt
	global_load_dwordx4 v[124:127], v170, s[4:5] offset:1024 nt
	global_load_dwordx4 v[128:131], v170, s[4:5] offset:2048 nt
	global_load_dwordx4 v[132:135], v170, s[4:5] offset:3072 nt
	v_add_u32_e32 v170, 0x2400000, v1
	global_load_dwordx4 v[136:139], v170, s[4:5] nt
	global_load_dwordx4 v[140:143], v170, s[4:5] offset:1024 nt
	global_load_dwordx4 v[144:147], v170, s[4:5] offset:2048 nt
	global_load_dwordx4 v[148:151], v170, s[4:5] offset:3072 nt
	v_add_u32_e32 v170, 0x2a00000, v1
	global_load_dwordx4 v[152:155], v170, s[4:5] nt
	global_load_dwordx4 v[156:159], v170, s[4:5] offset:1024 nt
	global_load_dwordx4 v[160:163], v170, s[4:5] offset:2048 nt
	global_load_dwordx4 v[164:167], v170, s[4:5] offset:3072 nt
	s_waitcnt vmcnt(36)
	v_add_f32_e32 v180, v40, v41
	v_add_f32_e32 v181, v44, v45
	v_add_f32_e32 v182, v48, v49
	v_add_f32_e32 v183, v52, v53
	v_add_f32_e32 v180, v180, v42
	v_add_f32_e32 v181, v181, v46
	v_add_f32_e32 v182, v182, v50
	v_add_f32_e32 v183, v183, v54
	v_add_f32_e32 v180, v180, v43
	v_add_f32_e32 v181, v181, v47
	v_add_f32_e32 v182, v182, v51
	v_add_f32_e32 v183, v183, v55
	v_add_f32_e32 v180, v180, v181
	v_add_f32_e32 v182, v182, v183
	v_add_f32_e32 v180, v180, v182
	s_nop 1
	v_add_f32_dpp v180, v180, v180 quad_perm:[1,0,3,2] row_mask:0xf bank_mask:0xf
	s_nop 1
	v_add_f32_dpp v180, v180, v180 quad_perm:[2,3,0,1] row_mask:0xf bank_mask:0xf
	s_nop 1
	v_add_f32_dpp v180, v180, v180 row_half_mirror row_mask:0xf bank_mask:0xf
	s_nop 1
	v_add_f32_dpp v180, v180, v180 row_mirror row_mask:0xf bank_mask:0xf
	s_nop 1
	v_add_f32_dpp v180, v180, v180 row_bcast:15 row_mask:0xa bank_mask:0xf
	s_nop 1
	v_add_f32_dpp v180, v180, v180 row_bcast:31 row_mask:0xc bank_mask:0xf
	s_nop 0
	v_readlane_b32 s20, v180, 63
	s_nop 1
	v_mul_f32_e32 v184, s20, v2
	v_sub_f32_e32 v40, v40, v184
	v_sub_f32_e32 v41, v41, v184
	v_sub_f32_e32 v42, v42, v184
	v_sub_f32_e32 v43, v43, v184
	v_sub_f32_e32 v44, v44, v184
	v_sub_f32_e32 v45, v45, v184
	v_sub_f32_e32 v46, v46, v184
	v_sub_f32_e32 v47, v47, v184
	v_sub_f32_e32 v48, v48, v184
	v_sub_f32_e32 v49, v49, v184
	v_sub_f32_e32 v50, v50, v184
	v_sub_f32_e32 v51, v51, v184
	v_sub_f32_e32 v52, v52, v184
	v_sub_f32_e32 v53, v53, v184
	v_sub_f32_e32 v54, v54, v184
	v_sub_f32_e32 v55, v55, v184
	v_mul_f32_e32 v180, v40, v40
	v_mul_f32_e32 v181, v44, v44
	v_mul_f32_e32 v182, v48, v48
	v_mul_f32_e32 v183, v52, v52
	v_fmac_f32_e32 v180, v41, v41
	v_fmac_f32_e32 v181, v45, v45
	v_fmac_f32_e32 v182, v49, v49
	v_fmac_f32_e32 v183, v53, v53
	v_fmac_f32_e32 v180, v42, v42
	v_fmac_f32_e32 v181, v46, v46
	v_fmac_f32_e32 v182, v50, v50
	v_fmac_f32_e32 v183, v54, v54
	v_fmac_f32_e32 v180, v43, v43
	v_fmac_f32_e32 v181, v47, v47
	v_fmac_f32_e32 v182, v51, v51
	v_fmac_f32_e32 v183, v55, v55
	v_add_f32_e32 v180, v180, v181
	v_add_f32_e32 v182, v182, v183
	v_add_f32_e32 v180, v180, v182
	s_nop 1
	v_add_f32_dpp v180, v180, v180 quad_perm:[1,0,3,2] row_mask:0xf bank_mask:0xf
	s_nop 1
	v_add_f32_dpp v180, v180, v180 quad_perm:[2,3,0,1] row_mask:0xf bank_mask:0xf
	s_nop 1
	v_add_f32_dpp v180, v180, v180 row_half_mirror row_mask:0xf bank_mask:0xf
	s_nop 1
	v_add_f32_dpp v180, v180, v180 row_mirror row_mask:0xf bank_mask:0xf
	s_nop 1
	v_add_f32_dpp v180, v180, v180 row_bcast:15 row_mask:0xa bank_mask:0xf
	s_nop 1
	v_add_f32_dpp v180, v180, v180 row_bcast:31 row_mask:0xc bank_mask:0xf
	s_nop 0
	v_readlane_b32 s20, v180, 63
	s_nop 1
	v_mov_b32_e32 v185, s20
	v_fma_f32 v185, v185, v2, v4
	v_rsq_f32_e32 v185, v185
	s_nop 0
	v_mul_f32_e32 v40, v40, v185
	v_mul_f32_e32 v41, v41, v185
	v_mul_f32_e32 v42, v42, v185
	v_mul_f32_e32 v43, v43, v185
	v_mul_f32_e32 v44, v44, v185
	v_mul_f32_e32 v45, v45, v185
	v_mul_f32_e32 v46, v46, v185
	v_mul_f32_e32 v47, v47, v185
	v_mul_f32_e32 v48, v48, v185
	v_mul_f32_e32 v49, v49, v185
	v_mul_f32_e32 v50, v50, v185
	v_mul_f32_e32 v51, v51, v185
	v_mul_f32_e32 v52, v52, v185
	v_mul_f32_e32 v53, v53, v185
	v_mul_f32_e32 v54, v54, v185
	v_mul_f32_e32 v55, v55, v185
	s_waitcnt vmcnt(28)
	v_fma_f32 v40, v40, v8, v24
	v_fma_f32 v41, v41, v9, v25
	v_fma_f32 v42, v42, v10, v26
	v_fma_f32 v43, v43, v11, v27
	v_fma_f32 v44, v44, v12, v28
	v_fma_f32 v45, v45, v13, v29
	v_fma_f32 v46, v46, v14, v30
	v_fma_f32 v47, v47, v15, v31
	v_fma_f32 v48, v48, v16, v32
	v_fma_f32 v49, v49, v17, v33
	v_fma_f32 v50, v50, v18, v34
	v_fma_f32 v51, v51, v19, v35
	v_fma_f32 v52, v52, v20, v36
	v_fma_f32 v53, v53, v21, v37
	v_fma_f32 v54, v54, v22, v38
	v_fma_f32 v55, v55, v23, v39
	global_store_dwordx4 v1, v[40:43], s[4:5] nt
	global_store_dwordx4 v1, v[44:47], s[4:5] offset:1024 nt
	global_store_dwordx4 v1, v[48:51], s[4:5] offset:2048 nt
	global_store_dwordx4 v1, v[52:55], s[4:5] offset:3072 nt
	s_nop 1
	v_add_u32_e32 v170, 0x3000000, v1
	global_load_dwordx4 v[40:43], v170, s[4:5] nt
	global_load_dwordx4 v[44:47], v170, s[4:5] offset:1024 nt
	global_load_dwordx4 v[48:51], v170, s[4:5] offset:2048 nt
	global_load_dwordx4 v[52:55], v170, s[4:5] offset:3072 nt
	s_waitcnt vmcnt(32)
	v_add_f32_e32 v180, v56, v57
	v_add_f32_e32 v181, v60, v61
	v_add_f32_e32 v182, v64, v65
	v_add_f32_e32 v183, v68, v69
	v_add_f32_e32 v180, v180, v58
	v_add_f32_e32 v181, v181, v62
	v_add_f32_e32 v182, v182, v66
	v_add_f32_e32 v183, v183, v70
	v_add_f32_e32 v180, v180, v59
	v_add_f32_e32 v181, v181, v63
	v_add_f32_e32 v182, v182, v67
	v_add_f32_e32 v183, v183, v71
	v_add_f32_e32 v180, v180, v181
	v_add_f32_e32 v182, v182, v183
	v_add_f32_e32 v180, v180, v182
	s_nop 1
	v_add_f32_dpp v180, v180, v180 quad_perm:[1,0,3,2] row_mask:0xf bank_mask:0xf
	s_nop 1
	v_add_f32_dpp v180, v180, v180 quad_perm:[2,3,0,1] row_mask:0xf bank_mask:0xf
	s_nop 1
	v_add_f32_dpp v180, v180, v180 row_half_mirror row_mask:0xf bank_mask:0xf
	s_nop 1
	v_add_f32_dpp v180, v180, v180 row_mirror row_mask:0xf bank_mask:0xf
	s_nop 1
	v_add_f32_dpp v180, v180, v180 row_bcast:15 row_mask:0xa bank_mask:0xf
	s_nop 1
	v_add_f32_dpp v180, v180, v180 row_bcast:31 row_mask:0xc bank_mask:0xf
	s_nop 0
	v_readlane_b32 s20, v180, 63
	s_nop 1
	v_mul_f32_e32 v184, s20, v2
	v_sub_f32_e32 v56, v56, v184
	v_sub_f32_e32 v57, v57, v184
	v_sub_f32_e32 v58, v58, v184
	v_sub_f32_e32 v59, v59, v184
	v_sub_f32_e32 v60, v60, v184
	v_sub_f32_e32 v61, v61, v184
	v_sub_f32_e32 v62, v62, v184
	v_sub_f32_e32 v63, v63, v184
	v_sub_f32_e32 v64, v64, v184
	v_sub_f32_e32 v65, v65, v184
	v_sub_f32_e32 v66, v66, v184
	v_sub_f32_e32 v67, v67, v184
	v_sub_f32_e32 v68, v68, v184
	v_sub_f32_e32 v69, v69, v184
	v_sub_f32_e32 v70, v70, v184
	v_sub_f32_e32 v71, v71, v184
	v_mul_f32_e32 v180, v56, v56
	v_mul_f32_e32 v181, v60, v60
	v_mul_f32_e32 v182, v64, v64
	v_mul_f32_e32 v183, v68, v68
	v_fmac_f32_e32 v180, v57, v57
	v_fmac_f32_e32 v181, v61, v61
	v_fmac_f32_e32 v182, v65, v65
	v_fmac_f32_e32 v183, v69, v69
	v_fmac_f32_e32 v180, v58, v58
	v_fmac_f32_e32 v181, v62, v62
	v_fmac_f32_e32 v182, v66, v66
	v_fmac_f32_e32 v183, v70, v70
	v_fmac_f32_e32 v180, v59, v59
	v_fmac_f32_e32 v181, v63, v63
	v_fmac_f32_e32 v182, v67, v67
	v_fmac_f32_e32 v183, v71, v71
	v_add_f32_e32 v180, v180, v181
	v_add_f32_e32 v182, v182, v183
	v_add_f32_e32 v180, v180, v182
	s_nop 1
	v_add_f32_dpp v180, v180, v180 quad_perm:[1,0,3,2] row_mask:0xf bank_mask:0xf
	s_nop 1
	v_add_f32_dpp v180, v180, v180 quad_perm:[2,3,0,1] row_mask:0xf bank_mask:0xf
	s_nop 1
	v_add_f32_dpp v180, v180, v180 row_half_mirror row_mask:0xf bank_mask:0xf
	s_nop 1
	v_add_f32_dpp v180, v180, v180 row_mirror row_mask:0xf bank_mask:0xf
	s_nop 1
	v_add_f32_dpp v180, v180, v180 row_bcast:15 row_mask:0xa bank_mask:0xf
	s_nop 1
	v_add_f32_dpp v180, v180, v180 row_bcast:31 row_mask:0xc bank_mask:0xf
	s_nop 0
	v_readlane_b32 s20, v180, 63
	s_nop 1
	v_mov_b32_e32 v185, s20
	v_fma_f32 v185, v185, v2, v4
	v_rsq_f32_e32 v185, v185
	s_nop 0
	v_mul_f32_e32 v56, v56, v185
	v_mul_f32_e32 v57, v57, v185
	v_mul_f32_e32 v58, v58, v185
	v_mul_f32_e32 v59, v59, v185
	v_mul_f32_e32 v60, v60, v185
	v_mul_f32_e32 v61, v61, v185
	v_mul_f32_e32 v62, v62, v185
	v_mul_f32_e32 v63, v63, v185
	v_mul_f32_e32 v64, v64, v185
	v_mul_f32_e32 v65, v65, v185
	v_mul_f32_e32 v66, v66, v185
	v_mul_f32_e32 v67, v67, v185
	v_mul_f32_e32 v68, v68, v185
	v_mul_f32_e32 v69, v69, v185
	v_mul_f32_e32 v70, v70, v185
	v_mul_f32_e32 v71, v71, v185
	v_fma_f32 v56, v56, v8, v24
	v_fma_f32 v57, v57, v9, v25
	v_fma_f32 v58, v58, v10, v26
	v_fma_f32 v59, v59, v11, v27
	v_fma_f32 v60, v60, v12, v28
	v_fma_f32 v61, v61, v13, v29
	v_fma_f32 v62, v62, v14, v30
	v_fma_f32 v63, v63, v15, v31
	v_fma_f32 v64, v64, v16, v32
	v_fma_f32 v65, v65, v17, v33
	v_fma_f32 v66, v66, v18, v34
	v_fma_f32 v67, v67, v19, v35
	v_fma_f32 v68, v68, v20, v36
	v_fma_f32 v69, v69, v21, v37
	v_fma_f32 v70, v70, v22, v38
	v_fma_f32 v71, v71, v23, v39
	v_add_u32_e32 v171, 0x600000, v1
	global_store_dwordx4 v171, v[56:59], s[4:5] nt
	global_store_dwordx4 v171, v[60:63], s[4:5] offset:1024 nt
	global_store_dwordx4 v171, v[64:67], s[4:5] offset:2048 nt
	global_store_dwordx4 v171, v[68:71], s[4:5] offset:3072 nt
	s_nop 1
	v_add_u32_e32 v170, 0x3600000, v1
	global_load_dwordx4 v[56:59], v170, s[4:5] nt
	global_load_dwordx4 v[60:63], v170, s[4:5] offset:1024 nt
	global_load_dwordx4 v[64:67], v170, s[4:5] offset:2048 nt
	global_load_dwordx4 v[68:71], v170, s[4:5] offset:3072 nt
	s_waitcnt vmcnt(36)
	v_add_f32_e32 v180, v72, v73
	v_add_f32_e32 v181, v76, v77
	v_add_f32_e32 v182, v80, v81
	v_add_f32_e32 v183, v84, v85
	v_add_f32_e32 v180, v180, v74
	v_add_f32_e32 v181, v181, v78
	v_add_f32_e32 v182, v182, v82
	v_add_f32_e32 v183, v183, v86
	v_add_f32_e32 v180, v180, v75
	v_add_f32_e32 v181, v181, v79
	v_add_f32_e32 v182, v182, v83
	v_add_f32_e32 v183, v183, v87
	v_add_f32_e32 v180, v180, v181
	v_add_f32_e32 v182, v182, v183
	v_add_f32_e32 v180, v180, v182
	s_nop 1
	v_add_f32_dpp v180, v180, v180 quad_perm:[1,0,3,2] row_mask:0xf bank_mask:0xf
	s_nop 1
	v_add_f32_dpp v180, v180, v180 quad_perm:[2,3,0,1] row_mask:0xf bank_mask:0xf
	s_nop 1
	v_add_f32_dpp v180, v180, v180 row_half_mirror row_mask:0xf bank_mask:0xf
	s_nop 1
	v_add_f32_dpp v180, v180, v180 row_mirror row_mask:0xf bank_mask:0xf
	s_nop 1
	v_add_f32_dpp v180, v180, v180 row_bcast:15 row_mask:0xa bank_mask:0xf
	s_nop 1
	v_add_f32_dpp v180, v180, v180 row_bcast:31 row_mask:0xc bank_mask:0xf
	s_nop 0
	v_readlane_b32 s20, v180, 63
	s_nop 1
	v_mul_f32_e32 v184, s20, v2
	v_sub_f32_e32 v72, v72, v184
	v_sub_f32_e32 v73, v73, v184
	v_sub_f32_e32 v74, v74, v184
	v_sub_f32_e32 v75, v75, v184
	v_sub_f32_e32 v76, v76, v184
	v_sub_f32_e32 v77, v77, v184
	v_sub_f32_e32 v78, v78, v184
	v_sub_f32_e32 v79, v79, v184
	v_sub_f32_e32 v80, v80, v184
	v_sub_f32_e32 v81, v81, v184
	v_sub_f32_e32 v82, v82, v184
	v_sub_f32_e32 v83, v83, v184
	v_sub_f32_e32 v84, v84, v184
	v_sub_f32_e32 v85, v85, v184
	v_sub_f32_e32 v86, v86, v184
	v_sub_f32_e32 v87, v87, v184
	v_mul_f32_e32 v180, v72, v72
	v_mul_f32_e32 v181, v76, v76
	v_mul_f32_e32 v182, v80, v80
	v_mul_f32_e32 v183, v84, v84
	v_fmac_f32_e32 v180, v73, v73
	v_fmac_f32_e32 v181, v77, v77
	v_fmac_f32_e32 v182, v81, v81
	v_fmac_f32_e32 v183, v85, v85
	v_fmac_f32_e32 v180, v74, v74
	v_fmac_f32_e32 v181, v78, v78
	v_fmac_f32_e32 v182, v82, v82
	v_fmac_f32_e32 v183, v86, v86
	v_fmac_f32_e32 v180, v75, v75
	v_fmac_f32_e32 v181, v79, v79
	v_fmac_f32_e32 v182, v83, v83
	v_fmac_f32_e32 v183, v87, v87
	v_add_f32_e32 v180, v180, v181
	v_add_f32_e32 v182, v182, v183
	v_add_f32_e32 v180, v180, v182
	s_nop 1
	v_add_f32_dpp v180, v180, v180 quad_perm:[1,0,3,2] row_mask:0xf bank_mask:0xf
	s_nop 1
	v_add_f32_dpp v180, v180, v180 quad_perm:[2,3,0,1] row_mask:0xf bank_mask:0xf
	s_nop 1
	v_add_f32_dpp v180, v180, v180 row_half_mirror row_mask:0xf bank_mask:0xf
	s_nop 1
	v_add_f32_dpp v180, v180, v180 row_mirror row_mask:0xf bank_mask:0xf
	s_nop 1
	v_add_f32_dpp v180, v180, v180 row_bcast:15 row_mask:0xa bank_mask:0xf
	s_nop 1
	v_add_f32_dpp v180, v180, v180 row_bcast:31 row_mask:0xc bank_mask:0xf
	s_nop 0
	v_readlane_b32 s20, v180, 63
	s_nop 1
	v_mov_b32_e32 v185, s20
	v_fma_f32 v185, v185, v2, v4
	v_rsq_f32_e32 v185, v185
	s_nop 0
	v_mul_f32_e32 v72, v72, v185
	v_mul_f32_e32 v73, v73, v185
	v_mul_f32_e32 v74, v74, v185
	v_mul_f32_e32 v75, v75, v185
	v_mul_f32_e32 v76, v76, v185
	v_mul_f32_e32 v77, v77, v185
	v_mul_f32_e32 v78, v78, v185
	v_mul_f32_e32 v79, v79, v185
	v_mul_f32_e32 v80, v80, v185
	v_mul_f32_e32 v81, v81, v185
	v_mul_f32_e32 v82, v82, v185
	v_mul_f32_e32 v83, v83, v185
	v_mul_f32_e32 v84, v84, v185
	v_mul_f32_e32 v85, v85, v185
	v_mul_f32_e32 v86, v86, v185
	v_mul_f32_e32 v87, v87, v185
	v_fma_f32 v72, v72, v8, v24
	v_fma_f32 v73, v73, v9, v25
	v_fma_f32 v74, v74, v10, v26
	v_fma_f32 v75, v75, v11, v27
	v_fma_f32 v76, v76, v12, v28
	v_fma_f32 v77, v77, v13, v29
	v_fma_f32 v78, v78, v14, v30
	v_fma_f32 v79, v79, v15, v31
	v_fma_f32 v80, v80, v16, v32
	v_fma_f32 v81, v81, v17, v33
	v_fma_f32 v82, v82, v18, v34
	v_fma_f32 v83, v83, v19, v35
	v_fma_f32 v84, v84, v20, v36
	v_fma_f32 v85, v85, v21, v37
	v_fma_f32 v86, v86, v22, v38
	v_fma_f32 v87, v87, v23, v39
	v_add_u32_e32 v171, 0xc00000, v1
	global_store_dwordx4 v171, v[72:75], s[4:5] nt
	global_store_dwordx4 v171, v[76:79], s[4:5] offset:1024 nt
	global_store_dwordx4 v171, v[80:83], s[4:5] offset:2048 nt
	global_store_dwordx4 v171, v[84:87], s[4:5] offset:3072 nt
	s_waitcnt vmcnt(36)
	v_add_f32_e32 v180, v88, v89
	v_add_f32_e32 v181, v92, v93
	v_add_f32_e32 v182, v96, v97
	v_add_f32_e32 v183, v100, v101
	v_add_f32_e32 v180, v180, v90
	v_add_f32_e32 v181, v181, v94
	v_add_f32_e32 v182, v182, v98
	v_add_f32_e32 v183, v183, v102
	v_add_f32_e32 v180, v180, v91
	v_add_f32_e32 v181, v181, v95
	v_add_f32_e32 v182, v182, v99
	v_add_f32_e32 v183, v183, v103
	v_add_f32_e32 v180, v180, v181
	v_add_f32_e32 v182, v182, v183
	v_add_f32_e32 v180, v180, v182
	s_nop 1
	v_add_f32_dpp v180, v180, v180 quad_perm:[1,0,3,2] row_mask:0xf bank_mask:0xf
	s_nop 1
	v_add_f32_dpp v180, v180, v180 quad_perm:[2,3,0,1] row_mask:0xf bank_mask:0xf
	s_nop 1
	v_add_f32_dpp v180, v180, v180 row_half_mirror row_mask:0xf bank_mask:0xf
	s_nop 1
	v_add_f32_dpp v180, v180, v180 row_mirror row_mask:0xf bank_mask:0xf
	s_nop 1
	v_add_f32_dpp v180, v180, v180 row_bcast:15 row_mask:0xa bank_mask:0xf
	s_nop 1
	v_add_f32_dpp v180, v180, v180 row_bcast:31 row_mask:0xc bank_mask:0xf
	s_nop 0
	v_readlane_b32 s20, v180, 63
	s_nop 1
	v_mul_f32_e32 v184, s20, v2
	v_sub_f32_e32 v88, v88, v184
	v_sub_f32_e32 v89, v89, v184
	v_sub_f32_e32 v90, v90, v184
	v_sub_f32_e32 v91, v91, v184
	v_sub_f32_e32 v92, v92, v184
	v_sub_f32_e32 v93, v93, v184
	v_sub_f32_e32 v94, v94, v184
	v_sub_f32_e32 v95, v95, v184
	v_sub_f32_e32 v96, v96, v184
	v_sub_f32_e32 v97, v97, v184
	v_sub_f32_e32 v98, v98, v184
	v_sub_f32_e32 v99, v99, v184
	v_sub_f32_e32 v100, v100, v184
	v_sub_f32_e32 v101, v101, v184
	v_sub_f32_e32 v102, v102, v184
	v_sub_f32_e32 v103, v103, v184
	v_mul_f32_e32 v180, v88, v88
	v_mul_f32_e32 v181, v92, v92
	v_mul_f32_e32 v182, v96, v96
	v_mul_f32_e32 v183, v100, v100
	v_fmac_f32_e32 v180, v89, v89
	v_fmac_f32_e32 v181, v93, v93
	v_fmac_f32_e32 v182, v97, v97
	v_fmac_f32_e32 v183, v101, v101
	v_fmac_f32_e32 v180, v90, v90
	v_fmac_f32_e32 v181, v94, v94
	v_fmac_f32_e32 v182, v98, v98
	v_fmac_f32_e32 v183, v102, v102
	v_fmac_f32_e32 v180, v91, v91
	v_fmac_f32_e32 v181, v95, v95
	v_fmac_f32_e32 v182, v99, v99
	v_fmac_f32_e32 v183, v103, v103
	v_add_f32_e32 v180, v180, v181
	v_add_f32_e32 v182, v182, v183
	v_add_f32_e32 v180, v180, v182
	s_nop 1
	v_add_f32_dpp v180, v180, v180 quad_perm:[1,0,3,2] row_mask:0xf bank_mask:0xf
	s_nop 1
	v_add_f32_dpp v180, v180, v180 quad_perm:[2,3,0,1] row_mask:0xf bank_mask:0xf
	s_nop 1
	v_add_f32_dpp v180, v180, v180 row_half_mirror row_mask:0xf bank_mask:0xf
	s_nop 1
	v_add_f32_dpp v180, v180, v180 row_mirror row_mask:0xf bank_mask:0xf
	s_nop 1
	v_add_f32_dpp v180, v180, v180 row_bcast:15 row_mask:0xa bank_mask:0xf
	s_nop 1
	v_add_f32_dpp v180, v180, v180 row_bcast:31 row_mask:0xc bank_mask:0xf
	s_nop 0
	v_readlane_b32 s20, v180, 63
	s_nop 1
	v_mov_b32_e32 v185, s20
	v_fma_f32 v185, v185, v2, v4
	v_rsq_f32_e32 v185, v185
	s_nop 0
	v_mul_f32_e32 v88, v88, v185
	v_mul_f32_e32 v89, v89, v185
	v_mul_f32_e32 v90, v90, v185
	v_mul_f32_e32 v91, v91, v185
	v_mul_f32_e32 v92, v92, v185
	v_mul_f32_e32 v93, v93, v185
	v_mul_f32_e32 v94, v94, v185
	v_mul_f32_e32 v95, v95, v185
	v_mul_f32_e32 v96, v96, v185
	v_mul_f32_e32 v97, v97, v185
	v_mul_f32_e32 v98, v98, v185
	v_mul_f32_e32 v99, v99, v185
	v_mul_f32_e32 v100, v100, v185
	v_mul_f32_e32 v101, v101, v185
	v_mul_f32_e32 v102, v102, v185
	v_mul_f32_e32 v103, v103, v185
	v_fma_f32 v88, v88, v8, v24
	v_fma_f32 v89, v89, v9, v25
	v_fma_f32 v90, v90, v10, v26
	v_fma_f32 v91, v91, v11, v27
	v_fma_f32 v92, v92, v12, v28
	v_fma_f32 v93, v93, v13, v29
	v_fma_f32 v94, v94, v14, v30
	v_fma_f32 v95, v95, v15, v31
	v_fma_f32 v96, v96, v16, v32
	v_fma_f32 v97, v97, v17, v33
	v_fma_f32 v98, v98, v18, v34
	v_fma_f32 v99, v99, v19, v35
	v_fma_f32 v100, v100, v20, v36
	v_fma_f32 v101, v101, v21, v37
	v_fma_f32 v102, v102, v22, v38
	v_fma_f32 v103, v103, v23, v39
	v_add_u32_e32 v171, 0x1200000, v1
	global_store_dwordx4 v171, v[88:91], s[4:5] nt
	global_store_dwordx4 v171, v[92:95], s[4:5] offset:1024 nt
	global_store_dwordx4 v171, v[96:99], s[4:5] offset:2048 nt
	global_store_dwordx4 v171, v[100:103], s[4:5] offset:3072 nt
	s_waitcnt vmcnt(36)
	v_add_f32_e32 v180, v104, v105
	v_add_f32_e32 v181, v108, v109
	v_add_f32_e32 v182, v112, v113
	v_add_f32_e32 v183, v116, v117
	v_add_f32_e32 v180, v180, v106
	v_add_f32_e32 v181, v181, v110
	v_add_f32_e32 v182, v182, v114
	v_add_f32_e32 v183, v183, v118
	v_add_f32_e32 v180, v180, v107
	v_add_f32_e32 v181, v181, v111
	v_add_f32_e32 v182, v182, v115
	v_add_f32_e32 v183, v183, v119
	v_add_f32_e32 v180, v180, v181
	v_add_f32_e32 v182, v182, v183
	v_add_f32_e32 v180, v180, v182
	s_nop 1
	v_add_f32_dpp v180, v180, v180 quad_perm:[1,0,3,2] row_mask:0xf bank_mask:0xf
	s_nop 1
	v_add_f32_dpp v180, v180, v180 quad_perm:[2,3,0,1] row_mask:0xf bank_mask:0xf
	s_nop 1
	v_add_f32_dpp v180, v180, v180 row_half_mirror row_mask:0xf bank_mask:0xf
	s_nop 1
	v_add_f32_dpp v180, v180, v180 row_mirror row_mask:0xf bank_mask:0xf
	s_nop 1
	v_add_f32_dpp v180, v180, v180 row_bcast:15 row_mask:0xa bank_mask:0xf
	s_nop 1
	v_add_f32_dpp v180, v180, v180 row_bcast:31 row_mask:0xc bank_mask:0xf
	s_nop 0
	v_readlane_b32 s20, v180, 63
	s_nop 1
	v_mul_f32_e32 v184, s20, v2
	v_sub_f32_e32 v104, v104, v184
	v_sub_f32_e32 v105, v105, v184
	v_sub_f32_e32 v106, v106, v184
	v_sub_f32_e32 v107, v107, v184
	v_sub_f32_e32 v108, v108, v184
	v_sub_f32_e32 v109, v109, v184
	v_sub_f32_e32 v110, v110, v184
	v_sub_f32_e32 v111, v111, v184
	v_sub_f32_e32 v112, v112, v184
	v_sub_f32_e32 v113, v113, v184
	v_sub_f32_e32 v114, v114, v184
	v_sub_f32_e32 v115, v115, v184
	v_sub_f32_e32 v116, v116, v184
	v_sub_f32_e32 v117, v117, v184
	v_sub_f32_e32 v118, v118, v184
	v_sub_f32_e32 v119, v119, v184
	v_mul_f32_e32 v180, v104, v104
	v_mul_f32_e32 v181, v108, v108
	v_mul_f32_e32 v182, v112, v112
	v_mul_f32_e32 v183, v116, v116
	v_fmac_f32_e32 v180, v105, v105
	v_fmac_f32_e32 v181, v109, v109
	v_fmac_f32_e32 v182, v113, v113
	v_fmac_f32_e32 v183, v117, v117
	v_fmac_f32_e32 v180, v106, v106
	v_fmac_f32_e32 v181, v110, v110
	v_fmac_f32_e32 v182, v114, v114
	v_fmac_f32_e32 v183, v118, v118
	v_fmac_f32_e32 v180, v107, v107
	v_fmac_f32_e32 v181, v111, v111
	v_fmac_f32_e32 v182, v115, v115
	v_fmac_f32_e32 v183, v119, v119
	v_add_f32_e32 v180, v180, v181
	v_add_f32_e32 v182, v182, v183
	v_add_f32_e32 v180, v180, v182
	s_nop 1
	v_add_f32_dpp v180, v180, v180 quad_perm:[1,0,3,2] row_mask:0xf bank_mask:0xf
	s_nop 1
	v_add_f32_dpp v180, v180, v180 quad_perm:[2,3,0,1] row_mask:0xf bank_mask:0xf
	s_nop 1
	v_add_f32_dpp v180, v180, v180 row_half_mirror row_mask:0xf bank_mask:0xf
	s_nop 1
	v_add_f32_dpp v180, v180, v180 row_mirror row_mask:0xf bank_mask:0xf
	s_nop 1
	v_add_f32_dpp v180, v180, v180 row_bcast:15 row_mask:0xa bank_mask:0xf
	s_nop 1
	v_add_f32_dpp v180, v180, v180 row_bcast:31 row_mask:0xc bank_mask:0xf
	s_nop 0
	v_readlane_b32 s20, v180, 63
	s_nop 1
	v_mov_b32_e32 v185, s20
	v_fma_f32 v185, v185, v2, v4
	v_rsq_f32_e32 v185, v185
	s_nop 0
	v_mul_f32_e32 v104, v104, v185
	v_mul_f32_e32 v105, v105, v185
	v_mul_f32_e32 v106, v106, v185
	v_mul_f32_e32 v107, v107, v185
	v_mul_f32_e32 v108, v108, v185
	v_mul_f32_e32 v109, v109, v185
	v_mul_f32_e32 v110, v110, v185
	v_mul_f32_e32 v111, v111, v185
	v_mul_f32_e32 v112, v112, v185
	v_mul_f32_e32 v113, v113, v185
	v_mul_f32_e32 v114, v114, v185
	v_mul_f32_e32 v115, v115, v185
	v_mul_f32_e32 v116, v116, v185
	v_mul_f32_e32 v117, v117, v185
	v_mul_f32_e32 v118, v118, v185
	v_mul_f32_e32 v119, v119, v185
	v_fma_f32 v104, v104, v8, v24
	v_fma_f32 v105, v105, v9, v25
	v_fma_f32 v106, v106, v10, v26
	v_fma_f32 v107, v107, v11, v27
	v_fma_f32 v108, v108, v12, v28
	v_fma_f32 v109, v109, v13, v29
	v_fma_f32 v110, v110, v14, v30
	v_fma_f32 v111, v111, v15, v31
	v_fma_f32 v112, v112, v16, v32
	v_fma_f32 v113, v113, v17, v33
	v_fma_f32 v114, v114, v18, v34
	v_fma_f32 v115, v115, v19, v35
	v_fma_f32 v116, v116, v20, v36
	v_fma_f32 v117, v117, v21, v37
	v_fma_f32 v118, v118, v22, v38
	v_fma_f32 v119, v119, v23, v39
	v_add_u32_e32 v171, 0x1800000, v1
	global_store_dwordx4 v171, v[104:107], s[4:5] nt
	global_store_dwordx4 v171, v[108:111], s[4:5] offset:1024 nt
	global_store_dwordx4 v171, v[112:115], s[4:5] offset:2048 nt
	global_store_dwordx4 v171, v[116:119], s[4:5] offset:3072 nt
	s_waitcnt vmcnt(36)
	v_add_f32_e32 v180, v120, v121
	v_add_f32_e32 v181, v124, v125
	v_add_f32_e32 v182, v128, v129
	v_add_f32_e32 v183, v132, v133
	v_add_f32_e32 v180, v180, v122
	v_add_f32_e32 v181, v181, v126
	v_add_f32_e32 v182, v182, v130
	v_add_f32_e32 v183, v183, v134
	v_add_f32_e32 v180, v180, v123
	v_add_f32_e32 v181, v181, v127
	v_add_f32_e32 v182, v182, v131
	v_add_f32_e32 v183, v183, v135
	v_add_f32_e32 v180, v180, v181
	v_add_f32_e32 v182, v182, v183
	v_add_f32_e32 v180, v180, v182
	s_nop 1
	v_add_f32_dpp v180, v180, v180 quad_perm:[1,0,3,2] row_mask:0xf bank_mask:0xf
	s_nop 1
	v_add_f32_dpp v180, v180, v180 quad_perm:[2,3,0,1] row_mask:0xf bank_mask:0xf
	s_nop 1
	v_add_f32_dpp v180, v180, v180 row_half_mirror row_mask:0xf bank_mask:0xf
	s_nop 1
	v_add_f32_dpp v180, v180, v180 row_mirror row_mask:0xf bank_mask:0xf
	s_nop 1
	v_add_f32_dpp v180, v180, v180 row_bcast:15 row_mask:0xa bank_mask:0xf
	s_nop 1
	v_add_f32_dpp v180, v180, v180 row_bcast:31 row_mask:0xc bank_mask:0xf
	s_nop 0
	v_readlane_b32 s20, v180, 63
	s_nop 1
	v_mul_f32_e32 v184, s20, v2
	v_sub_f32_e32 v120, v120, v184
	v_sub_f32_e32 v121, v121, v184
	v_sub_f32_e32 v122, v122, v184
	v_sub_f32_e32 v123, v123, v184
	v_sub_f32_e32 v124, v124, v184
	v_sub_f32_e32 v125, v125, v184
	v_sub_f32_e32 v126, v126, v184
	v_sub_f32_e32 v127, v127, v184
	v_sub_f32_e32 v128, v128, v184
	v_sub_f32_e32 v129, v129, v184
	v_sub_f32_e32 v130, v130, v184
	v_sub_f32_e32 v131, v131, v184
	v_sub_f32_e32 v132, v132, v184
	v_sub_f32_e32 v133, v133, v184
	v_sub_f32_e32 v134, v134, v184
	v_sub_f32_e32 v135, v135, v184
	v_mul_f32_e32 v180, v120, v120
	v_mul_f32_e32 v181, v124, v124
	v_mul_f32_e32 v182, v128, v128
	v_mul_f32_e32 v183, v132, v132
	v_fmac_f32_e32 v180, v121, v121
	v_fmac_f32_e32 v181, v125, v125
	v_fmac_f32_e32 v182, v129, v129
	v_fmac_f32_e32 v183, v133, v133
	v_fmac_f32_e32 v180, v122, v122
	v_fmac_f32_e32 v181, v126, v126
	v_fmac_f32_e32 v182, v130, v130
	v_fmac_f32_e32 v183, v134, v134
	v_fmac_f32_e32 v180, v123, v123
	v_fmac_f32_e32 v181, v127, v127
	v_fmac_f32_e32 v182, v131, v131
	v_fmac_f32_e32 v183, v135, v135
	v_add_f32_e32 v180, v180, v181
	v_add_f32_e32 v182, v182, v183
	v_add_f32_e32 v180, v180, v182
	s_nop 1
	v_add_f32_dpp v180, v180, v180 quad_perm:[1,0,3,2] row_mask:0xf bank_mask:0xf
	s_nop 1
	v_add_f32_dpp v180, v180, v180 quad_perm:[2,3,0,1] row_mask:0xf bank_mask:0xf
	s_nop 1
	v_add_f32_dpp v180, v180, v180 row_half_mirror row_mask:0xf bank_mask:0xf
	s_nop 1
	v_add_f32_dpp v180, v180, v180 row_mirror row_mask:0xf bank_mask:0xf
	s_nop 1
	v_add_f32_dpp v180, v180, v180 row_bcast:15 row_mask:0xa bank_mask:0xf
	s_nop 1
	v_add_f32_dpp v180, v180, v180 row_bcast:31 row_mask:0xc bank_mask:0xf
	s_nop 0
	v_readlane_b32 s20, v180, 63
	s_nop 1
	v_mov_b32_e32 v185, s20
	v_fma_f32 v185, v185, v2, v4
	v_rsq_f32_e32 v185, v185
	s_nop 0
	v_mul_f32_e32 v120, v120, v185
	v_mul_f32_e32 v121, v121, v185
	v_mul_f32_e32 v122, v122, v185
	v_mul_f32_e32 v123, v123, v185
	v_mul_f32_e32 v124, v124, v185
	v_mul_f32_e32 v125, v125, v185
	v_mul_f32_e32 v126, v126, v185
	v_mul_f32_e32 v127, v127, v185
	v_mul_f32_e32 v128, v128, v185
	v_mul_f32_e32 v129, v129, v185
	v_mul_f32_e32 v130, v130, v185
	v_mul_f32_e32 v131, v131, v185
	v_mul_f32_e32 v132, v132, v185
	v_mul_f32_e32 v133, v133, v185
	v_mul_f32_e32 v134, v134, v185
	v_mul_f32_e32 v135, v135, v185
	v_fma_f32 v120, v120, v8, v24
	v_fma_f32 v121, v121, v9, v25
	v_fma_f32 v122, v122, v10, v26
	v_fma_f32 v123, v123, v11, v27
	v_fma_f32 v124, v124, v12, v28
	v_fma_f32 v125, v125, v13, v29
	v_fma_f32 v126, v126, v14, v30
	v_fma_f32 v127, v127, v15, v31
	v_fma_f32 v128, v128, v16, v32
	v_fma_f32 v129, v129, v17, v33
	v_fma_f32 v130, v130, v18, v34
	v_fma_f32 v131, v131, v19, v35
	v_fma_f32 v132, v132, v20, v36
	v_fma_f32 v133, v133, v21, v37
	v_fma_f32 v134, v134, v22, v38
	v_fma_f32 v135, v135, v23, v39
	v_add_u32_e32 v171, 0x1e00000, v1
	global_store_dwordx4 v171, v[120:123], s[4:5] nt
	global_store_dwordx4 v171, v[124:127], s[4:5] offset:1024 nt
	global_store_dwordx4 v171, v[128:131], s[4:5] offset:2048 nt
	global_store_dwordx4 v171, v[132:135], s[4:5] offset:3072 nt
	s_waitcnt vmcnt(36)
	v_add_f32_e32 v180, v136, v137
	v_add_f32_e32 v181, v140, v141
	v_add_f32_e32 v182, v144, v145
	v_add_f32_e32 v183, v148, v149
	v_add_f32_e32 v180, v180, v138
	v_add_f32_e32 v181, v181, v142
	v_add_f32_e32 v182, v182, v146
	v_add_f32_e32 v183, v183, v150
	v_add_f32_e32 v180, v180, v139
	v_add_f32_e32 v181, v181, v143
	v_add_f32_e32 v182, v182, v147
	v_add_f32_e32 v183, v183, v151
	v_add_f32_e32 v180, v180, v181
	v_add_f32_e32 v182, v182, v183
	v_add_f32_e32 v180, v180, v182
	s_nop 1
	v_add_f32_dpp v180, v180, v180 quad_perm:[1,0,3,2] row_mask:0xf bank_mask:0xf
	s_nop 1
	v_add_f32_dpp v180, v180, v180 quad_perm:[2,3,0,1] row_mask:0xf bank_mask:0xf
	s_nop 1
	v_add_f32_dpp v180, v180, v180 row_half_mirror row_mask:0xf bank_mask:0xf
	s_nop 1
	v_add_f32_dpp v180, v180, v180 row_mirror row_mask:0xf bank_mask:0xf
	s_nop 1
	v_add_f32_dpp v180, v180, v180 row_bcast:15 row_mask:0xa bank_mask:0xf
	s_nop 1
	v_add_f32_dpp v180, v180, v180 row_bcast:31 row_mask:0xc bank_mask:0xf
	s_nop 0
	v_readlane_b32 s20, v180, 63
	s_nop 1
	v_mul_f32_e32 v184, s20, v2
	v_sub_f32_e32 v136, v136, v184
	v_sub_f32_e32 v137, v137, v184
	v_sub_f32_e32 v138, v138, v184
	v_sub_f32_e32 v139, v139, v184
	v_sub_f32_e32 v140, v140, v184
	v_sub_f32_e32 v141, v141, v184
	v_sub_f32_e32 v142, v142, v184
	v_sub_f32_e32 v143, v143, v184
	v_sub_f32_e32 v144, v144, v184
	v_sub_f32_e32 v145, v145, v184
	v_sub_f32_e32 v146, v146, v184
	v_sub_f32_e32 v147, v147, v184
	v_sub_f32_e32 v148, v148, v184
	v_sub_f32_e32 v149, v149, v184
	v_sub_f32_e32 v150, v150, v184
	v_sub_f32_e32 v151, v151, v184
	v_mul_f32_e32 v180, v136, v136
	v_mul_f32_e32 v181, v140, v140
	v_mul_f32_e32 v182, v144, v144
	v_mul_f32_e32 v183, v148, v148
	v_fmac_f32_e32 v180, v137, v137
	v_fmac_f32_e32 v181, v141, v141
	v_fmac_f32_e32 v182, v145, v145
	v_fmac_f32_e32 v183, v149, v149
	v_fmac_f32_e32 v180, v138, v138
	v_fmac_f32_e32 v181, v142, v142
	v_fmac_f32_e32 v182, v146, v146
	v_fmac_f32_e32 v183, v150, v150
	v_fmac_f32_e32 v180, v139, v139
	v_fmac_f32_e32 v181, v143, v143
	v_fmac_f32_e32 v182, v147, v147
	v_fmac_f32_e32 v183, v151, v151
	v_add_f32_e32 v180, v180, v181
	v_add_f32_e32 v182, v182, v183
	v_add_f32_e32 v180, v180, v182
	s_nop 1
	v_add_f32_dpp v180, v180, v180 quad_perm:[1,0,3,2] row_mask:0xf bank_mask:0xf
	s_nop 1
	v_add_f32_dpp v180, v180, v180 quad_perm:[2,3,0,1] row_mask:0xf bank_mask:0xf
	s_nop 1
	v_add_f32_dpp v180, v180, v180 row_half_mirror row_mask:0xf bank_mask:0xf
	s_nop 1
	v_add_f32_dpp v180, v180, v180 row_mirror row_mask:0xf bank_mask:0xf
	s_nop 1
	v_add_f32_dpp v180, v180, v180 row_bcast:15 row_mask:0xa bank_mask:0xf
	s_nop 1
	v_add_f32_dpp v180, v180, v180 row_bcast:31 row_mask:0xc bank_mask:0xf
	s_nop 0
	v_readlane_b32 s20, v180, 63
	s_nop 1
	v_mov_b32_e32 v185, s20
	v_fma_f32 v185, v185, v2, v4
	v_rsq_f32_e32 v185, v185
	s_nop 0
	v_mul_f32_e32 v136, v136, v185
	v_mul_f32_e32 v137, v137, v185
	v_mul_f32_e32 v138, v138, v185
	v_mul_f32_e32 v139, v139, v185
	v_mul_f32_e32 v140, v140, v185
	v_mul_f32_e32 v141, v141, v185
	v_mul_f32_e32 v142, v142, v185
	v_mul_f32_e32 v143, v143, v185
	v_mul_f32_e32 v144, v144, v185
	v_mul_f32_e32 v145, v145, v185
	v_mul_f32_e32 v146, v146, v185
	v_mul_f32_e32 v147, v147, v185
	v_mul_f32_e32 v148, v148, v185
	v_mul_f32_e32 v149, v149, v185
	v_mul_f32_e32 v150, v150, v185
	v_mul_f32_e32 v151, v151, v185
	v_fma_f32 v136, v136, v8, v24
	v_fma_f32 v137, v137, v9, v25
	v_fma_f32 v138, v138, v10, v26
	v_fma_f32 v139, v139, v11, v27
	v_fma_f32 v140, v140, v12, v28
	v_fma_f32 v141, v141, v13, v29
	v_fma_f32 v142, v142, v14, v30
	v_fma_f32 v143, v143, v15, v31
	v_fma_f32 v144, v144, v16, v32
	v_fma_f32 v145, v145, v17, v33
	v_fma_f32 v146, v146, v18, v34
	v_fma_f32 v147, v147, v19, v35
	v_fma_f32 v148, v148, v20, v36
	v_fma_f32 v149, v149, v21, v37
	v_fma_f32 v150, v150, v22, v38
	v_fma_f32 v151, v151, v23, v39
	v_add_u32_e32 v171, 0x2400000, v1
	global_store_dwordx4 v171, v[136:139], s[4:5] nt
	global_store_dwordx4 v171, v[140:143], s[4:5] offset:1024 nt
	global_store_dwordx4 v171, v[144:147], s[4:5] offset:2048 nt
	global_store_dwordx4 v171, v[148:151], s[4:5] offset:3072 nt
	s_waitcnt vmcnt(36)
	v_add_f32_e32 v180, v152, v153
	v_add_f32_e32 v181, v156, v157
	v_add_f32_e32 v182, v160, v161
	v_add_f32_e32 v183, v164, v165
	v_add_f32_e32 v180, v180, v154
	v_add_f32_e32 v181, v181, v158
	v_add_f32_e32 v182, v182, v162
	v_add_f32_e32 v183, v183, v166
	v_add_f32_e32 v180, v180, v155
	v_add_f32_e32 v181, v181, v159
	v_add_f32_e32 v182, v182, v163
	v_add_f32_e32 v183, v183, v167
	v_add_f32_e32 v180, v180, v181
	v_add_f32_e32 v182, v182, v183
	v_add_f32_e32 v180, v180, v182
	s_nop 1
	v_add_f32_dpp v180, v180, v180 quad_perm:[1,0,3,2] row_mask:0xf bank_mask:0xf
	s_nop 1
	v_add_f32_dpp v180, v180, v180 quad_perm:[2,3,0,1] row_mask:0xf bank_mask:0xf
	s_nop 1
	v_add_f32_dpp v180, v180, v180 row_half_mirror row_mask:0xf bank_mask:0xf
	s_nop 1
	v_add_f32_dpp v180, v180, v180 row_mirror row_mask:0xf bank_mask:0xf
	s_nop 1
	v_add_f32_dpp v180, v180, v180 row_bcast:15 row_mask:0xa bank_mask:0xf
	s_nop 1
	v_add_f32_dpp v180, v180, v180 row_bcast:31 row_mask:0xc bank_mask:0xf
	s_nop 0
	v_readlane_b32 s20, v180, 63
	s_nop 1
	v_mul_f32_e32 v184, s20, v2
	v_sub_f32_e32 v152, v152, v184
	v_sub_f32_e32 v153, v153, v184
	v_sub_f32_e32 v154, v154, v184
	v_sub_f32_e32 v155, v155, v184
	v_sub_f32_e32 v156, v156, v184
	v_sub_f32_e32 v157, v157, v184
	v_sub_f32_e32 v158, v158, v184
	v_sub_f32_e32 v159, v159, v184
	v_sub_f32_e32 v160, v160, v184
	v_sub_f32_e32 v161, v161, v184
	v_sub_f32_e32 v162, v162, v184
	v_sub_f32_e32 v163, v163, v184
	v_sub_f32_e32 v164, v164, v184
	v_sub_f32_e32 v165, v165, v184
	v_sub_f32_e32 v166, v166, v184
	v_sub_f32_e32 v167, v167, v184
	v_mul_f32_e32 v180, v152, v152
	v_mul_f32_e32 v181, v156, v156
	v_mul_f32_e32 v182, v160, v160
	v_mul_f32_e32 v183, v164, v164
	v_fmac_f32_e32 v180, v153, v153
	v_fmac_f32_e32 v181, v157, v157
	v_fmac_f32_e32 v182, v161, v161
	v_fmac_f32_e32 v183, v165, v165
	v_fmac_f32_e32 v180, v154, v154
	v_fmac_f32_e32 v181, v158, v158
	v_fmac_f32_e32 v182, v162, v162
	v_fmac_f32_e32 v183, v166, v166
	v_fmac_f32_e32 v180, v155, v155
	v_fmac_f32_e32 v181, v159, v159
	v_fmac_f32_e32 v182, v163, v163
	v_fmac_f32_e32 v183, v167, v167
	v_add_f32_e32 v180, v180, v181
	v_add_f32_e32 v182, v182, v183
	v_add_f32_e32 v180, v180, v182
	s_nop 1
	v_add_f32_dpp v180, v180, v180 quad_perm:[1,0,3,2] row_mask:0xf bank_mask:0xf
	s_nop 1
	v_add_f32_dpp v180, v180, v180 quad_perm:[2,3,0,1] row_mask:0xf bank_mask:0xf
	s_nop 1
	v_add_f32_dpp v180, v180, v180 row_half_mirror row_mask:0xf bank_mask:0xf
	s_nop 1
	v_add_f32_dpp v180, v180, v180 row_mirror row_mask:0xf bank_mask:0xf
	s_nop 1
	v_add_f32_dpp v180, v180, v180 row_bcast:15 row_mask:0xa bank_mask:0xf
	s_nop 1
	v_add_f32_dpp v180, v180, v180 row_bcast:31 row_mask:0xc bank_mask:0xf
	s_nop 0
	v_readlane_b32 s20, v180, 63
	s_nop 1
	v_mov_b32_e32 v185, s20
	v_fma_f32 v185, v185, v2, v4
	v_rsq_f32_e32 v185, v185
	s_nop 0
	v_mul_f32_e32 v152, v152, v185
	v_mul_f32_e32 v153, v153, v185
	v_mul_f32_e32 v154, v154, v185
	v_mul_f32_e32 v155, v155, v185
	v_mul_f32_e32 v156, v156, v185
	v_mul_f32_e32 v157, v157, v185
	v_mul_f32_e32 v158, v158, v185
	v_mul_f32_e32 v159, v159, v185
	v_mul_f32_e32 v160, v160, v185
	v_mul_f32_e32 v161, v161, v185
	v_mul_f32_e32 v162, v162, v185
	v_mul_f32_e32 v163, v163, v185
	v_mul_f32_e32 v164, v164, v185
	v_mul_f32_e32 v165, v165, v185
	v_mul_f32_e32 v166, v166, v185
	v_mul_f32_e32 v167, v167, v185
	v_fma_f32 v152, v152, v8, v24
	v_fma_f32 v153, v153, v9, v25
	v_fma_f32 v154, v154, v10, v26
	v_fma_f32 v155, v155, v11, v27
	v_fma_f32 v156, v156, v12, v28
	v_fma_f32 v157, v157, v13, v29
	v_fma_f32 v158, v158, v14, v30
	v_fma_f32 v159, v159, v15, v31
	v_fma_f32 v160, v160, v16, v32
	v_fma_f32 v161, v161, v17, v33
	v_fma_f32 v162, v162, v18, v34
	v_fma_f32 v163, v163, v19, v35
	v_fma_f32 v164, v164, v20, v36
	v_fma_f32 v165, v165, v21, v37
	v_fma_f32 v166, v166, v22, v38
	v_fma_f32 v167, v167, v23, v39
	v_add_u32_e32 v171, 0x2a00000, v1
	global_store_dwordx4 v171, v[152:155], s[4:5] nt
	global_store_dwordx4 v171, v[156:159], s[4:5] offset:1024 nt
	global_store_dwordx4 v171, v[160:163], s[4:5] offset:2048 nt
	global_store_dwordx4 v171, v[164:167], s[4:5] offset:3072 nt
	s_waitcnt vmcnt(32)
	v_add_f32_e32 v180, v40, v41
	v_add_f32_e32 v181, v44, v45
	v_add_f32_e32 v182, v48, v49
	v_add_f32_e32 v183, v52, v53
	v_add_f32_e32 v180, v180, v42
	v_add_f32_e32 v181, v181, v46
	v_add_f32_e32 v182, v182, v50
	v_add_f32_e32 v183, v183, v54
	v_add_f32_e32 v180, v180, v43
	v_add_f32_e32 v181, v181, v47
	v_add_f32_e32 v182, v182, v51
	v_add_f32_e32 v183, v183, v55
	v_add_f32_e32 v180, v180, v181
	v_add_f32_e32 v182, v182, v183
	v_add_f32_e32 v180, v180, v182
	s_nop 1
	v_add_f32_dpp v180, v180, v180 quad_perm:[1,0,3,2] row_mask:0xf bank_mask:0xf
	s_nop 1
	v_add_f32_dpp v180, v180, v180 quad_perm:[2,3,0,1] row_mask:0xf bank_mask:0xf
	s_nop 1
	v_add_f32_dpp v180, v180, v180 row_half_mirror row_mask:0xf bank_mask:0xf
	s_nop 1
	v_add_f32_dpp v180, v180, v180 row_mirror row_mask:0xf bank_mask:0xf
	s_nop 1
	v_add_f32_dpp v180, v180, v180 row_bcast:15 row_mask:0xa bank_mask:0xf
	s_nop 1
	v_add_f32_dpp v180, v180, v180 row_bcast:31 row_mask:0xc bank_mask:0xf
	s_nop 0
	v_readlane_b32 s20, v180, 63
	s_nop 1
	v_mul_f32_e32 v184, s20, v2
	v_sub_f32_e32 v40, v40, v184
	v_sub_f32_e32 v41, v41, v184
	v_sub_f32_e32 v42, v42, v184
	v_sub_f32_e32 v43, v43, v184
	v_sub_f32_e32 v44, v44, v184
	v_sub_f32_e32 v45, v45, v184
	v_sub_f32_e32 v46, v46, v184
	v_sub_f32_e32 v47, v47, v184
	v_sub_f32_e32 v48, v48, v184
	v_sub_f32_e32 v49, v49, v184
	v_sub_f32_e32 v50, v50, v184
	v_sub_f32_e32 v51, v51, v184
	v_sub_f32_e32 v52, v52, v184
	v_sub_f32_e32 v53, v53, v184
	v_sub_f32_e32 v54, v54, v184
	v_sub_f32_e32 v55, v55, v184
	v_mul_f32_e32 v180, v40, v40
	v_mul_f32_e32 v181, v44, v44
	v_mul_f32_e32 v182, v48, v48
	v_mul_f32_e32 v183, v52, v52
	v_fmac_f32_e32 v180, v41, v41
	v_fmac_f32_e32 v181, v45, v45
	v_fmac_f32_e32 v182, v49, v49
	v_fmac_f32_e32 v183, v53, v53
	v_fmac_f32_e32 v180, v42, v42
	v_fmac_f32_e32 v181, v46, v46
	v_fmac_f32_e32 v182, v50, v50
	v_fmac_f32_e32 v183, v54, v54
	v_fmac_f32_e32 v180, v43, v43
	v_fmac_f32_e32 v181, v47, v47
	v_fmac_f32_e32 v182, v51, v51
	v_fmac_f32_e32 v183, v55, v55
	v_add_f32_e32 v180, v180, v181
	v_add_f32_e32 v182, v182, v183
	v_add_f32_e32 v180, v180, v182
	s_nop 1
	v_add_f32_dpp v180, v180, v180 quad_perm:[1,0,3,2] row_mask:0xf bank_mask:0xf
	s_nop 1
	v_add_f32_dpp v180, v180, v180 quad_perm:[2,3,0,1] row_mask:0xf bank_mask:0xf
	s_nop 1
	v_add_f32_dpp v180, v180, v180 row_half_mirror row_mask:0xf bank_mask:0xf
	s_nop 1
	v_add_f32_dpp v180, v180, v180 row_mirror row_mask:0xf bank_mask:0xf
	s_nop 1
	v_add_f32_dpp v180, v180, v180 row_bcast:15 row_mask:0xa bank_mask:0xf
	s_nop 1
	v_add_f32_dpp v180, v180, v180 row_bcast:31 row_mask:0xc bank_mask:0xf
	s_nop 0
	v_readlane_b32 s20, v180, 63
	s_nop 1
	v_mov_b32_e32 v185, s20
	v_fma_f32 v185, v185, v2, v4
	v_rsq_f32_e32 v185, v185
	s_nop 0
	v_mul_f32_e32 v40, v40, v185
	v_mul_f32_e32 v41, v41, v185
	v_mul_f32_e32 v42, v42, v185
	v_mul_f32_e32 v43, v43, v185
	v_mul_f32_e32 v44, v44, v185
	v_mul_f32_e32 v45, v45, v185
	v_mul_f32_e32 v46, v46, v185
	v_mul_f32_e32 v47, v47, v185
	v_mul_f32_e32 v48, v48, v185
	v_mul_f32_e32 v49, v49, v185
	v_mul_f32_e32 v50, v50, v185
	v_mul_f32_e32 v51, v51, v185
	v_mul_f32_e32 v52, v52, v185
	v_mul_f32_e32 v53, v53, v185
	v_mul_f32_e32 v54, v54, v185
	v_mul_f32_e32 v55, v55, v185
	v_fma_f32 v40, v40, v8, v24
	v_fma_f32 v41, v41, v9, v25
	v_fma_f32 v42, v42, v10, v26
	v_fma_f32 v43, v43, v11, v27
	v_fma_f32 v44, v44, v12, v28
	v_fma_f32 v45, v45, v13, v29
	v_fma_f32 v46, v46, v14, v30
	v_fma_f32 v47, v47, v15, v31
	v_fma_f32 v48, v48, v16, v32
	v_fma_f32 v49, v49, v17, v33
	v_fma_f32 v50, v50, v18, v34
	v_fma_f32 v51, v51, v19, v35
	v_fma_f32 v52, v52, v20, v36
	v_fma_f32 v53, v53, v21, v37
	v_fma_f32 v54, v54, v22, v38
	v_fma_f32 v55, v55, v23, v39
	v_add_u32_e32 v171, 0x3000000, v1
	global_store_dwordx4 v171, v[40:43], s[4:5] nt
	global_store_dwordx4 v171, v[44:47], s[4:5] offset:1024 nt
	global_store_dwordx4 v171, v[48:51], s[4:5] offset:2048 nt
	global_store_dwordx4 v171, v[52:55], s[4:5] offset:3072 nt
	s_waitcnt vmcnt(28)
	v_add_f32_e32 v180, v56, v57
	v_add_f32_e32 v181, v60, v61
	v_add_f32_e32 v182, v64, v65
	v_add_f32_e32 v183, v68, v69
	v_add_f32_e32 v180, v180, v58
	v_add_f32_e32 v181, v181, v62
	v_add_f32_e32 v182, v182, v66
	v_add_f32_e32 v183, v183, v70
	v_add_f32_e32 v180, v180, v59
	v_add_f32_e32 v181, v181, v63
	v_add_f32_e32 v182, v182, v67
	v_add_f32_e32 v183, v183, v71
	v_add_f32_e32 v180, v180, v181
	v_add_f32_e32 v182, v182, v183
	v_add_f32_e32 v180, v180, v182
	s_nop 1
	v_add_f32_dpp v180, v180, v180 quad_perm:[1,0,3,2] row_mask:0xf bank_mask:0xf
	s_nop 1
	v_add_f32_dpp v180, v180, v180 quad_perm:[2,3,0,1] row_mask:0xf bank_mask:0xf
	s_nop 1
	v_add_f32_dpp v180, v180, v180 row_half_mirror row_mask:0xf bank_mask:0xf
	s_nop 1
	v_add_f32_dpp v180, v180, v180 row_mirror row_mask:0xf bank_mask:0xf
	s_nop 1
	v_add_f32_dpp v180, v180, v180 row_bcast:15 row_mask:0xa bank_mask:0xf
	s_nop 1
	v_add_f32_dpp v180, v180, v180 row_bcast:31 row_mask:0xc bank_mask:0xf
	s_nop 0
	v_readlane_b32 s20, v180, 63
	s_nop 1
	v_mul_f32_e32 v184, s20, v2
	v_sub_f32_e32 v56, v56, v184
	v_sub_f32_e32 v57, v57, v184
	v_sub_f32_e32 v58, v58, v184
	v_sub_f32_e32 v59, v59, v184
	v_sub_f32_e32 v60, v60, v184
	v_sub_f32_e32 v61, v61, v184
	v_sub_f32_e32 v62, v62, v184
	v_sub_f32_e32 v63, v63, v184
	v_sub_f32_e32 v64, v64, v184
	v_sub_f32_e32 v65, v65, v184
	v_sub_f32_e32 v66, v66, v184
	v_sub_f32_e32 v67, v67, v184
	v_sub_f32_e32 v68, v68, v184
	v_sub_f32_e32 v69, v69, v184
	v_sub_f32_e32 v70, v70, v184
	v_sub_f32_e32 v71, v71, v184
	v_mul_f32_e32 v180, v56, v56
	v_mul_f32_e32 v181, v60, v60
	v_mul_f32_e32 v182, v64, v64
	v_mul_f32_e32 v183, v68, v68
	v_fmac_f32_e32 v180, v57, v57
	v_fmac_f32_e32 v181, v61, v61
	v_fmac_f32_e32 v182, v65, v65
	v_fmac_f32_e32 v183, v69, v69
	v_fmac_f32_e32 v180, v58, v58
	v_fmac_f32_e32 v181, v62, v62
	v_fmac_f32_e32 v182, v66, v66
	v_fmac_f32_e32 v183, v70, v70
	v_fmac_f32_e32 v180, v59, v59
	v_fmac_f32_e32 v181, v63, v63
	v_fmac_f32_e32 v182, v67, v67
	v_fmac_f32_e32 v183, v71, v71
	v_add_f32_e32 v180, v180, v181
	v_add_f32_e32 v182, v182, v183
	v_add_f32_e32 v180, v180, v182
	s_nop 1
	v_add_f32_dpp v180, v180, v180 quad_perm:[1,0,3,2] row_mask:0xf bank_mask:0xf
	s_nop 1
	v_add_f32_dpp v180, v180, v180 quad_perm:[2,3,0,1] row_mask:0xf bank_mask:0xf
	s_nop 1
	v_add_f32_dpp v180, v180, v180 row_half_mirror row_mask:0xf bank_mask:0xf
	s_nop 1
	v_add_f32_dpp v180, v180, v180 row_mirror row_mask:0xf bank_mask:0xf
	s_nop 1
	v_add_f32_dpp v180, v180, v180 row_bcast:15 row_mask:0xa bank_mask:0xf
	s_nop 1
	v_add_f32_dpp v180, v180, v180 row_bcast:31 row_mask:0xc bank_mask:0xf
	s_nop 0
	v_readlane_b32 s20, v180, 63
	s_nop 1
	v_mov_b32_e32 v185, s20
	v_fma_f32 v185, v185, v2, v4
	v_rsq_f32_e32 v185, v185
	s_nop 0
	v_mul_f32_e32 v56, v56, v185
	v_mul_f32_e32 v57, v57, v185
	v_mul_f32_e32 v58, v58, v185
	v_mul_f32_e32 v59, v59, v185
	v_mul_f32_e32 v60, v60, v185
	v_mul_f32_e32 v61, v61, v185
	v_mul_f32_e32 v62, v62, v185
	v_mul_f32_e32 v63, v63, v185
	v_mul_f32_e32 v64, v64, v185
	v_mul_f32_e32 v65, v65, v185
	v_mul_f32_e32 v66, v66, v185
	v_mul_f32_e32 v67, v67, v185
	v_mul_f32_e32 v68, v68, v185
	v_mul_f32_e32 v69, v69, v185
	v_mul_f32_e32 v70, v70, v185
	v_mul_f32_e32 v71, v71, v185
	v_fma_f32 v56, v56, v8, v24
	v_fma_f32 v57, v57, v9, v25
	v_fma_f32 v58, v58, v10, v26
	v_fma_f32 v59, v59, v11, v27
	v_fma_f32 v60, v60, v12, v28
	v_fma_f32 v61, v61, v13, v29
	v_fma_f32 v62, v62, v14, v30
	v_fma_f32 v63, v63, v15, v31
	v_fma_f32 v64, v64, v16, v32
	v_fma_f32 v65, v65, v17, v33
	v_fma_f32 v66, v66, v18, v34
	v_fma_f32 v67, v67, v19, v35
	v_fma_f32 v68, v68, v20, v36
	v_fma_f32 v69, v69, v21, v37
	v_fma_f32 v70, v70, v22, v38
	v_fma_f32 v71, v71, v23, v39
	v_add_u32_e32 v171, 0x3600000, v1
	global_store_dwordx4 v171, v[56:59], s[4:5] nt
	global_store_dwordx4 v171, v[60:63], s[4:5] offset:1024 nt
	global_store_dwordx4 v171, v[64:67], s[4:5] offset:2048 nt
	global_store_dwordx4 v171, v[68:71], s[4:5] offset:3072 nt
	s_branch .Ltr_29
.Llo_even:
	s_lshr_b32 s1, s86, 3
	s_lshl_b32 s1, s1, 6
	s_lshl_b32 s0, s0, 3
	s_add_i32 s0, s0, s1
	s_and_b32 s1, s86, 7
	s_lshl_b32 s1, s1, 11
	s_add_i32 s0, s0, s1
	s_lshl_b32 s0, s0, 12
	s_add_u32 s4, s4, s0
	s_addc_u32 s5, s5, 0
	global_load_dwordx4 v[40:43], v1, s[4:5] nt
	global_load_dwordx4 v[44:47], v1, s[4:5] offset:1024 nt
	global_load_dwordx4 v[48:51], v1, s[4:5] offset:2048 nt
	global_load_dwordx4 v[52:55], v1, s[4:5] offset:3072 nt
	global_load_dwordx4 v[8:11], v1, s[40:41]
	global_load_dwordx4 v[12:15], v1, s[40:41] offset:1024
	global_load_dwordx4 v[16:19], v1, s[40:41] offset:2048
	global_load_dwordx4 v[20:23], v1, s[40:41] offset:3072
	global_load_dwordx4 v[24:27], v1, s[42:43]
	global_load_dwordx4 v[28:31], v1, s[42:43] offset:1024
	global_load_dwordx4 v[32:35], v1, s[42:43] offset:2048
	global_load_dwordx4 v[36:39], v1, s[42:43] offset:3072
	v_add_u32_e32 v170, 0x1000, v1
	global_load_dwordx4 v[56:59], v170, s[4:5] nt
	global_load_dwordx4 v[60:63], v170, s[4:5] offset:1024 nt
	global_load_dwordx4 v[64:67], v170, s[4:5] offset:2048 nt
	global_load_dwordx4 v[68:71], v170, s[4:5] offset:3072 nt
	v_add_u32_e32 v170, 0x2000, v1
	global_load_dwordx4 v[72:75], v170, s[4:5] nt
	global_load_dwordx4 v[76:79], v170, s[4:5] offset:1024 nt
	global_load_dwordx4 v[80:83], v170, s[4:5] offset:2048 nt
	global_load_dwordx4 v[84:87], v170, s[4:5] offset:3072 nt
	v_add_u32_e32 v170, 0x3000, v1
	global_load_dwordx4 v[88:91], v170, s[4:5] nt
	global_load_dwordx4 v[92:95], v170, s[4:5] offset:1024 nt
	global_load_dwordx4 v[96:99], v170, s[4:5] offset:2048 nt
	global_load_dwordx4 v[100:103], v170, s[4:5] offset:3072 nt
	v_add_u32_e32 v170, 0x4000, v1
	global_load_dwordx4 v[104:107], v170, s[4:5] nt
	global_load_dwordx4 v[108:111], v170, s[4:5] offset:1024 nt
	global_load_dwordx4 v[112:115], v170, s[4:5] offset:2048 nt
	global_load_dwordx4 v[116:119], v170, s[4:5] offset:3072 nt
	v_add_u32_e32 v170, 0x5000, v1
	global_load_dwordx4 v[120:123], v170, s[4:5] nt
	global_load_dwordx4 v[124:127], v170, s[4:5] offset:1024 nt
	global_load_dwordx4 v[128:131], v170, s[4:5] offset:2048 nt
	global_load_dwordx4 v[132:135], v170, s[4:5] offset:3072 nt
	v_add_u32_e32 v170, 0x6000, v1
	global_load_dwordx4 v[136:139], v170, s[4:5] nt
	global_load_dwordx4 v[140:143], v170, s[4:5] offset:1024 nt
	global_load_dwordx4 v[144:147], v170, s[4:5] offset:2048 nt
	global_load_dwordx4 v[148:151], v170, s[4:5] offset:3072 nt
	v_add_u32_e32 v170, 0x7000, v1
	global_load_dwordx4 v[152:155], v170, s[4:5] nt
	global_load_dwordx4 v[156:159], v170, s[4:5] offset:1024 nt
	global_load_dwordx4 v[160:163], v170, s[4:5] offset:2048 nt
	global_load_dwordx4 v[164:167], v170, s[4:5] offset:3072 nt
	s_waitcnt vmcnt(36)
	v_add_f32_e32 v180, v40, v41
	v_add_f32_e32 v181, v44, v45
	v_add_f32_e32 v182, v48, v49
	v_add_f32_e32 v183, v52, v53
	v_add_f32_e32 v180, v180, v42
	v_add_f32_e32 v181, v181, v46
	v_add_f32_e32 v182, v182, v50
	v_add_f32_e32 v183, v183, v54
	v_add_f32_e32 v180, v180, v43
	v_add_f32_e32 v181, v181, v47
	v_add_f32_e32 v182, v182, v51
	v_add_f32_e32 v183, v183, v55
	v_add_f32_e32 v180, v180, v181
	v_add_f32_e32 v182, v182, v183
	v_add_f32_e32 v180, v180, v182
	s_nop 1
	v_add_f32_dpp v180, v180, v180 quad_perm:[1,0,3,2] row_mask:0xf bank_mask:0xf
	s_nop 1
	v_add_f32_dpp v180, v180, v180 quad_perm:[2,3,0,1] row_mask:0xf bank_mask:0xf
	s_nop 1
	v_add_f32_dpp v180, v180, v180 row_half_mirror row_mask:0xf bank_mask:0xf
	s_nop 1
	v_add_f32_dpp v180, v180, v180 row_mirror row_mask:0xf bank_mask:0xf
	s_nop 1
	v_add_f32_dpp v180, v180, v180 row_bcast:15 row_mask:0xa bank_mask:0xf
	s_nop 1
	v_add_f32_dpp v180, v180, v180 row_bcast:31 row_mask:0xc bank_mask:0xf
	s_nop 0
	v_readlane_b32 s20, v180, 63
	s_nop 1
	v_mul_f32_e32 v184, s20, v2
	v_sub_f32_e32 v40, v40, v184
	v_sub_f32_e32 v41, v41, v184
	v_sub_f32_e32 v42, v42, v184
	v_sub_f32_e32 v43, v43, v184
	v_sub_f32_e32 v44, v44, v184
	v_sub_f32_e32 v45, v45, v184
	v_sub_f32_e32 v46, v46, v184
	v_sub_f32_e32 v47, v47, v184
	v_sub_f32_e32 v48, v48, v184
	v_sub_f32_e32 v49, v49, v184
	v_sub_f32_e32 v50, v50, v184
	v_sub_f32_e32 v51, v51, v184
	v_sub_f32_e32 v52, v52, v184
	v_sub_f32_e32 v53, v53, v184
	v_sub_f32_e32 v54, v54, v184
	v_sub_f32_e32 v55, v55, v184
	v_mul_f32_e32 v180, v40, v40
	v_mul_f32_e32 v181, v44, v44
	v_mul_f32_e32 v182, v48, v48
	v_mul_f32_e32 v183, v52, v52
	v_fmac_f32_e32 v180, v41, v41
	v_fmac_f32_e32 v181, v45, v45
	v_fmac_f32_e32 v182, v49, v49
	v_fmac_f32_e32 v183, v53, v53
	v_fmac_f32_e32 v180, v42, v42
	v_fmac_f32_e32 v181, v46, v46
	v_fmac_f32_e32 v182, v50, v50
	v_fmac_f32_e32 v183, v54, v54
	v_fmac_f32_e32 v180, v43, v43
	v_fmac_f32_e32 v181, v47, v47
	v_fmac_f32_e32 v182, v51, v51
	v_fmac_f32_e32 v183, v55, v55
	v_add_f32_e32 v180, v180, v181
	v_add_f32_e32 v182, v182, v183
	v_add_f32_e32 v180, v180, v182
	s_nop 1
	v_add_f32_dpp v180, v180, v180 quad_perm:[1,0,3,2] row_mask:0xf bank_mask:0xf
	s_nop 1
	v_add_f32_dpp v180, v180, v180 quad_perm:[2,3,0,1] row_mask:0xf bank_mask:0xf
	s_nop 1
	v_add_f32_dpp v180, v180, v180 row_half_mirror row_mask:0xf bank_mask:0xf
	s_nop 1
	v_add_f32_dpp v180, v180, v180 row_mirror row_mask:0xf bank_mask:0xf
	s_nop 1
	v_add_f32_dpp v180, v180, v180 row_bcast:15 row_mask:0xa bank_mask:0xf
	s_nop 1
	v_add_f32_dpp v180, v180, v180 row_bcast:31 row_mask:0xc bank_mask:0xf
	s_nop 0
	v_readlane_b32 s20, v180, 63
	s_nop 1
	v_mov_b32_e32 v185, s20
	v_fma_f32 v185, v185, v2, v4
	v_rsq_f32_e32 v185, v185
	s_nop 0
	v_mul_f32_e32 v40, v40, v185
	v_mul_f32_e32 v41, v41, v185
	v_mul_f32_e32 v42, v42, v185
	v_mul_f32_e32 v43, v43, v185
	v_mul_f32_e32 v44, v44, v185
	v_mul_f32_e32 v45, v45, v185
	v_mul_f32_e32 v46, v46, v185
	v_mul_f32_e32 v47, v47, v185
	v_mul_f32_e32 v48, v48, v185
	v_mul_f32_e32 v49, v49, v185
	v_mul_f32_e32 v50, v50, v185
	v_mul_f32_e32 v51, v51, v185
	v_mul_f32_e32 v52, v52, v185
	v_mul_f32_e32 v53, v53, v185
	v_mul_f32_e32 v54, v54, v185
	v_mul_f32_e32 v55, v55, v185
	s_waitcnt vmcnt(28)
	v_fma_f32 v40, v40, v8, v24
	v_fma_f32 v41, v41, v9, v25
	v_fma_f32 v42, v42, v10, v26
	v_fma_f32 v43, v43, v11, v27
	v_fma_f32 v44, v44, v12, v28
	v_fma_f32 v45, v45, v13, v29
	v_fma_f32 v46, v46, v14, v30
	v_fma_f32 v47, v47, v15, v31
	v_fma_f32 v48, v48, v16, v32
	v_fma_f32 v49, v49, v17, v33
	v_fma_f32 v50, v50, v18, v34
	v_fma_f32 v51, v51, v19, v35
	v_fma_f32 v52, v52, v20, v36
	v_fma_f32 v53, v53, v21, v37
	v_fma_f32 v54, v54, v22, v38
	v_fma_f32 v55, v55, v23, v39
	global_store_dwordx4 v1, v[40:43], s[4:5] nt
	global_store_dwordx4 v1, v[44:47], s[4:5] offset:1024 nt
	global_store_dwordx4 v1, v[48:51], s[4:5] offset:2048 nt
	global_store_dwordx4 v1, v[52:55], s[4:5] offset:3072 nt
	s_waitcnt vmcnt(28)
	v_add_f32_e32 v180, v56, v57
	v_add_f32_e32 v181, v60, v61
	v_add_f32_e32 v182, v64, v65
	v_add_f32_e32 v183, v68, v69
	v_add_f32_e32 v180, v180, v58
	v_add_f32_e32 v181, v181, v62
	v_add_f32_e32 v182, v182, v66
	v_add_f32_e32 v183, v183, v70
	v_add_f32_e32 v180, v180, v59
	v_add_f32_e32 v181, v181, v63
	v_add_f32_e32 v182, v182, v67
	v_add_f32_e32 v183, v183, v71
	v_add_f32_e32 v180, v180, v181
	v_add_f32_e32 v182, v182, v183
	v_add_f32_e32 v180, v180, v182
	s_nop 1
	v_add_f32_dpp v180, v180, v180 quad_perm:[1,0,3,2] row_mask:0xf bank_mask:0xf
	s_nop 1
	v_add_f32_dpp v180, v180, v180 quad_perm:[2,3,0,1] row_mask:0xf bank_mask:0xf
	s_nop 1
	v_add_f32_dpp v180, v180, v180 row_half_mirror row_mask:0xf bank_mask:0xf
	s_nop 1
	v_add_f32_dpp v180, v180, v180 row_mirror row_mask:0xf bank_mask:0xf
	s_nop 1
	v_add_f32_dpp v180, v180, v180 row_bcast:15 row_mask:0xa bank_mask:0xf
	s_nop 1
	v_add_f32_dpp v180, v180, v180 row_bcast:31 row_mask:0xc bank_mask:0xf
	s_nop 0
	v_readlane_b32 s20, v180, 63
	s_nop 1
	v_mul_f32_e32 v184, s20, v2
	v_sub_f32_e32 v56, v56, v184
	v_sub_f32_e32 v57, v57, v184
	v_sub_f32_e32 v58, v58, v184
	v_sub_f32_e32 v59, v59, v184
	v_sub_f32_e32 v60, v60, v184
	v_sub_f32_e32 v61, v61, v184
	v_sub_f32_e32 v62, v62, v184
	v_sub_f32_e32 v63, v63, v184
	v_sub_f32_e32 v64, v64, v184
	v_sub_f32_e32 v65, v65, v184
	v_sub_f32_e32 v66, v66, v184
	v_sub_f32_e32 v67, v67, v184
	v_sub_f32_e32 v68, v68, v184
	v_sub_f32_e32 v69, v69, v184
	v_sub_f32_e32 v70, v70, v184
	v_sub_f32_e32 v71, v71, v184
	v_mul_f32_e32 v180, v56, v56
	v_mul_f32_e32 v181, v60, v60
	v_mul_f32_e32 v182, v64, v64
	v_mul_f32_e32 v183, v68, v68
	v_fmac_f32_e32 v180, v57, v57
	v_fmac_f32_e32 v181, v61, v61
	v_fmac_f32_e32 v182, v65, v65
	v_fmac_f32_e32 v183, v69, v69
	v_fmac_f32_e32 v180, v58, v58
	v_fmac_f32_e32 v181, v62, v62
	v_fmac_f32_e32 v182, v66, v66
	v_fmac_f32_e32 v183, v70, v70
	v_fmac_f32_e32 v180, v59, v59
	v_fmac_f32_e32 v181, v63, v63
	v_fmac_f32_e32 v182, v67, v67
	v_fmac_f32_e32 v183, v71, v71
	v_add_f32_e32 v180, v180, v181
	v_add_f32_e32 v182, v182, v183
	v_add_f32_e32 v180, v180, v182
	s_nop 1
	v_add_f32_dpp v180, v180, v180 quad_perm:[1,0,3,2] row_mask:0xf bank_mask:0xf
	s_nop 1
	v_add_f32_dpp v180, v180, v180 quad_perm:[2,3,0,1] row_mask:0xf bank_mask:0xf
	s_nop 1
	v_add_f32_dpp v180, v180, v180 row_half_mirror row_mask:0xf bank_mask:0xf
	s_nop 1
	v_add_f32_dpp v180, v180, v180 row_mirror row_mask:0xf bank_mask:0xf
	s_nop 1
	v_add_f32_dpp v180, v180, v180 row_bcast:15 row_mask:0xa bank_mask:0xf
	s_nop 1
	v_add_f32_dpp v180, v180, v180 row_bcast:31 row_mask:0xc bank_mask:0xf
	s_nop 0
	v_readlane_b32 s20, v180, 63
	s_nop 1
	v_mov_b32_e32 v185, s20
	v_fma_f32 v185, v185, v2, v4
	v_rsq_f32_e32 v185, v185
	s_nop 0
	v_mul_f32_e32 v56, v56, v185
	v_mul_f32_e32 v57, v57, v185
	v_mul_f32_e32 v58, v58, v185
	v_mul_f32_e32 v59, v59, v185
	v_mul_f32_e32 v60, v60, v185
	v_mul_f32_e32 v61, v61, v185
	v_mul_f32_e32 v62, v62, v185
	v_mul_f32_e32 v63, v63, v185
	v_mul_f32_e32 v64, v64, v185
	v_mul_f32_e32 v65, v65, v185
	v_mul_f32_e32 v66, v66, v185
	v_mul_f32_e32 v67, v67, v185
	v_mul_f32_e32 v68, v68, v185
	v_mul_f32_e32 v69, v69, v185
	v_mul_f32_e32 v70, v70, v185
	v_mul_f32_e32 v71, v71, v185
	v_fma_f32 v56, v56, v8, v24
	v_fma_f32 v57, v57, v9, v25
	v_fma_f32 v58, v58, v10, v26
	v_fma_f32 v59, v59, v11, v27
	v_fma_f32 v60, v60, v12, v28
	v_fma_f32 v61, v61, v13, v29
	v_fma_f32 v62, v62, v14, v30
	v_fma_f32 v63, v63, v15, v31
	v_fma_f32 v64, v64, v16, v32
	v_fma_f32 v65, v65, v17, v33
	v_fma_f32 v66, v66, v18, v34
	v_fma_f32 v67, v67, v19, v35
	v_fma_f32 v68, v68, v20, v36
	v_fma_f32 v69, v69, v21, v37
	v_fma_f32 v70, v70, v22, v38
	v_fma_f32 v71, v71, v23, v39
	v_add_u32_e32 v171, 0x1000, v1
	global_store_dwordx4 v171, v[56:59], s[4:5] nt
	global_store_dwordx4 v171, v[60:63], s[4:5] offset:1024 nt
	global_store_dwordx4 v171, v[64:67], s[4:5] offset:2048 nt
	global_store_dwordx4 v171, v[68:71], s[4:5] offset:3072 nt
	s_waitcnt vmcnt(28)
	v_add_f32_e32 v180, v72, v73
	v_add_f32_e32 v181, v76, v77
	v_add_f32_e32 v182, v80, v81
	v_add_f32_e32 v183, v84, v85
	v_add_f32_e32 v180, v180, v74
	v_add_f32_e32 v181, v181, v78
	v_add_f32_e32 v182, v182, v82
	v_add_f32_e32 v183, v183, v86
	v_add_f32_e32 v180, v180, v75
	v_add_f32_e32 v181, v181, v79
	v_add_f32_e32 v182, v182, v83
	v_add_f32_e32 v183, v183, v87
	v_add_f32_e32 v180, v180, v181
	v_add_f32_e32 v182, v182, v183
	v_add_f32_e32 v180, v180, v182
	s_nop 1
	v_add_f32_dpp v180, v180, v180 quad_perm:[1,0,3,2] row_mask:0xf bank_mask:0xf
	s_nop 1
	v_add_f32_dpp v180, v180, v180 quad_perm:[2,3,0,1] row_mask:0xf bank_mask:0xf
	s_nop 1
	v_add_f32_dpp v180, v180, v180 row_half_mirror row_mask:0xf bank_mask:0xf
	s_nop 1
	v_add_f32_dpp v180, v180, v180 row_mirror row_mask:0xf bank_mask:0xf
	s_nop 1
	v_add_f32_dpp v180, v180, v180 row_bcast:15 row_mask:0xa bank_mask:0xf
	s_nop 1
	v_add_f32_dpp v180, v180, v180 row_bcast:31 row_mask:0xc bank_mask:0xf
	s_nop 0
	v_readlane_b32 s20, v180, 63
	s_nop 1
	v_mul_f32_e32 v184, s20, v2
	v_sub_f32_e32 v72, v72, v184
	v_sub_f32_e32 v73, v73, v184
	v_sub_f32_e32 v74, v74, v184
	v_sub_f32_e32 v75, v75, v184
	v_sub_f32_e32 v76, v76, v184
	v_sub_f32_e32 v77, v77, v184
	v_sub_f32_e32 v78, v78, v184
	v_sub_f32_e32 v79, v79, v184
	v_sub_f32_e32 v80, v80, v184
	v_sub_f32_e32 v81, v81, v184
	v_sub_f32_e32 v82, v82, v184
	v_sub_f32_e32 v83, v83, v184
	v_sub_f32_e32 v84, v84, v184
	v_sub_f32_e32 v85, v85, v184
	v_sub_f32_e32 v86, v86, v184
	v_sub_f32_e32 v87, v87, v184
	v_mul_f32_e32 v180, v72, v72
	v_mul_f32_e32 v181, v76, v76
	v_mul_f32_e32 v182, v80, v80
	v_mul_f32_e32 v183, v84, v84
	v_fmac_f32_e32 v180, v73, v73
	v_fmac_f32_e32 v181, v77, v77
	v_fmac_f32_e32 v182, v81, v81
	v_fmac_f32_e32 v183, v85, v85
	v_fmac_f32_e32 v180, v74, v74
	v_fmac_f32_e32 v181, v78, v78
	v_fmac_f32_e32 v182, v82, v82
	v_fmac_f32_e32 v183, v86, v86
	v_fmac_f32_e32 v180, v75, v75
	v_fmac_f32_e32 v181, v79, v79
	v_fmac_f32_e32 v182, v83, v83
	v_fmac_f32_e32 v183, v87, v87
	v_add_f32_e32 v180, v180, v181
	v_add_f32_e32 v182, v182, v183
	v_add_f32_e32 v180, v180, v182
	s_nop 1
	v_add_f32_dpp v180, v180, v180 quad_perm:[1,0,3,2] row_mask:0xf bank_mask:0xf
	s_nop 1
	v_add_f32_dpp v180, v180, v180 quad_perm:[2,3,0,1] row_mask:0xf bank_mask:0xf
	s_nop 1
	v_add_f32_dpp v180, v180, v180 row_half_mirror row_mask:0xf bank_mask:0xf
	s_nop 1
	v_add_f32_dpp v180, v180, v180 row_mirror row_mask:0xf bank_mask:0xf
	s_nop 1
	v_add_f32_dpp v180, v180, v180 row_bcast:15 row_mask:0xa bank_mask:0xf
	s_nop 1
	v_add_f32_dpp v180, v180, v180 row_bcast:31 row_mask:0xc bank_mask:0xf
	s_nop 0
	v_readlane_b32 s20, v180, 63
	s_nop 1
	v_mov_b32_e32 v185, s20
	v_fma_f32 v185, v185, v2, v4
	v_rsq_f32_e32 v185, v185
	s_nop 0
	v_mul_f32_e32 v72, v72, v185
	v_mul_f32_e32 v73, v73, v185
	v_mul_f32_e32 v74, v74, v185
	v_mul_f32_e32 v75, v75, v185
	v_mul_f32_e32 v76, v76, v185
	v_mul_f32_e32 v77, v77, v185
	v_mul_f32_e32 v78, v78, v185
	v_mul_f32_e32 v79, v79, v185
	v_mul_f32_e32 v80, v80, v185
	v_mul_f32_e32 v81, v81, v185
	v_mul_f32_e32 v82, v82, v185
	v_mul_f32_e32 v83, v83, v185
	v_mul_f32_e32 v84, v84, v185
	v_mul_f32_e32 v85, v85, v185
	v_mul_f32_e32 v86, v86, v185
	v_mul_f32_e32 v87, v87, v185
	v_fma_f32 v72, v72, v8, v24
	v_fma_f32 v73, v73, v9, v25
	v_fma_f32 v74, v74, v10, v26
	v_fma_f32 v75, v75, v11, v27
	v_fma_f32 v76, v76, v12, v28
	v_fma_f32 v77, v77, v13, v29
	v_fma_f32 v78, v78, v14, v30
	v_fma_f32 v79, v79, v15, v31
	v_fma_f32 v80, v80, v16, v32
	v_fma_f32 v81, v81, v17, v33
	v_fma_f32 v82, v82, v18, v34
	v_fma_f32 v83, v83, v19, v35
	v_fma_f32 v84, v84, v20, v36
	v_fma_f32 v85, v85, v21, v37
	v_fma_f32 v86, v86, v22, v38
	v_fma_f32 v87, v87, v23, v39
	v_add_u32_e32 v171, 0x2000, v1
	global_store_dwordx4 v171, v[72:75], s[4:5] nt
	global_store_dwordx4 v171, v[76:79], s[4:5] offset:1024 nt
	global_store_dwordx4 v171, v[80:83], s[4:5] offset:2048 nt
	global_store_dwordx4 v171, v[84:87], s[4:5] offset:3072 nt
	s_waitcnt vmcnt(28)
	v_add_f32_e32 v180, v88, v89
	v_add_f32_e32 v181, v92, v93
	v_add_f32_e32 v182, v96, v97
	v_add_f32_e32 v183, v100, v101
	v_add_f32_e32 v180, v180, v90
	v_add_f32_e32 v181, v181, v94
	v_add_f32_e32 v182, v182, v98
	v_add_f32_e32 v183, v183, v102
	v_add_f32_e32 v180, v180, v91
	v_add_f32_e32 v181, v181, v95
	v_add_f32_e32 v182, v182, v99
	v_add_f32_e32 v183, v183, v103
	v_add_f32_e32 v180, v180, v181
	v_add_f32_e32 v182, v182, v183
	v_add_f32_e32 v180, v180, v182
	s_nop 1
	v_add_f32_dpp v180, v180, v180 quad_perm:[1,0,3,2] row_mask:0xf bank_mask:0xf
	s_nop 1
	v_add_f32_dpp v180, v180, v180 quad_perm:[2,3,0,1] row_mask:0xf bank_mask:0xf
	s_nop 1
	v_add_f32_dpp v180, v180, v180 row_half_mirror row_mask:0xf bank_mask:0xf
	s_nop 1
	v_add_f32_dpp v180, v180, v180 row_mirror row_mask:0xf bank_mask:0xf
	s_nop 1
	v_add_f32_dpp v180, v180, v180 row_bcast:15 row_mask:0xa bank_mask:0xf
	s_nop 1
	v_add_f32_dpp v180, v180, v180 row_bcast:31 row_mask:0xc bank_mask:0xf
	s_nop 0
	v_readlane_b32 s20, v180, 63
	s_nop 1
	v_mul_f32_e32 v184, s20, v2
	v_sub_f32_e32 v88, v88, v184
	v_sub_f32_e32 v89, v89, v184
	v_sub_f32_e32 v90, v90, v184
	v_sub_f32_e32 v91, v91, v184
	v_sub_f32_e32 v92, v92, v184
	v_sub_f32_e32 v93, v93, v184
	v_sub_f32_e32 v94, v94, v184
	v_sub_f32_e32 v95, v95, v184
	v_sub_f32_e32 v96, v96, v184
	v_sub_f32_e32 v97, v97, v184
	v_sub_f32_e32 v98, v98, v184
	v_sub_f32_e32 v99, v99, v184
	v_sub_f32_e32 v100, v100, v184
	v_sub_f32_e32 v101, v101, v184
	v_sub_f32_e32 v102, v102, v184
	v_sub_f32_e32 v103, v103, v184
	v_mul_f32_e32 v180, v88, v88
	v_mul_f32_e32 v181, v92, v92
	v_mul_f32_e32 v182, v96, v96
	v_mul_f32_e32 v183, v100, v100
	v_fmac_f32_e32 v180, v89, v89
	v_fmac_f32_e32 v181, v93, v93
	v_fmac_f32_e32 v182, v97, v97
	v_fmac_f32_e32 v183, v101, v101
	v_fmac_f32_e32 v180, v90, v90
	v_fmac_f32_e32 v181, v94, v94
	v_fmac_f32_e32 v182, v98, v98
	v_fmac_f32_e32 v183, v102, v102
	v_fmac_f32_e32 v180, v91, v91
	v_fmac_f32_e32 v181, v95, v95
	v_fmac_f32_e32 v182, v99, v99
	v_fmac_f32_e32 v183, v103, v103
	v_add_f32_e32 v180, v180, v181
	v_add_f32_e32 v182, v182, v183
	v_add_f32_e32 v180, v180, v182
	s_nop 1
	v_add_f32_dpp v180, v180, v180 quad_perm:[1,0,3,2] row_mask:0xf bank_mask:0xf
	s_nop 1
	v_add_f32_dpp v180, v180, v180 quad_perm:[2,3,0,1] row_mask:0xf bank_mask:0xf
	s_nop 1
	v_add_f32_dpp v180, v180, v180 row_half_mirror row_mask:0xf bank_mask:0xf
	s_nop 1
	v_add_f32_dpp v180, v180, v180 row_mirror row_mask:0xf bank_mask:0xf
	s_nop 1
	v_add_f32_dpp v180, v180, v180 row_bcast:15 row_mask:0xa bank_mask:0xf
	s_nop 1
	v_add_f32_dpp v180, v180, v180 row_bcast:31 row_mask:0xc bank_mask:0xf
	s_nop 0
	v_readlane_b32 s20, v180, 63
	s_nop 1
	v_mov_b32_e32 v185, s20
	v_fma_f32 v185, v185, v2, v4
	v_rsq_f32_e32 v185, v185
	s_nop 0
	v_mul_f32_e32 v88, v88, v185
	v_mul_f32_e32 v89, v89, v185
	v_mul_f32_e32 v90, v90, v185
	v_mul_f32_e32 v91, v91, v185
	v_mul_f32_e32 v92, v92, v185
	v_mul_f32_e32 v93, v93, v185
	v_mul_f32_e32 v94, v94, v185
	v_mul_f32_e32 v95, v95, v185
	v_mul_f32_e32 v96, v96, v185
	v_mul_f32_e32 v97, v97, v185
	v_mul_f32_e32 v98, v98, v185
	v_mul_f32_e32 v99, v99, v185
	v_mul_f32_e32 v100, v100, v185
	v_mul_f32_e32 v101, v101, v185
	v_mul_f32_e32 v102, v102, v185
	v_mul_f32_e32 v103, v103, v185
	v_fma_f32 v88, v88, v8, v24
	v_fma_f32 v89, v89, v9, v25
	v_fma_f32 v90, v90, v10, v26
	v_fma_f32 v91, v91, v11, v27
	v_fma_f32 v92, v92, v12, v28
	v_fma_f32 v93, v93, v13, v29
	v_fma_f32 v94, v94, v14, v30
	v_fma_f32 v95, v95, v15, v31
	v_fma_f32 v96, v96, v16, v32
	v_fma_f32 v97, v97, v17, v33
	v_fma_f32 v98, v98, v18, v34
	v_fma_f32 v99, v99, v19, v35
	v_fma_f32 v100, v100, v20, v36
	v_fma_f32 v101, v101, v21, v37
	v_fma_f32 v102, v102, v22, v38
	v_fma_f32 v103, v103, v23, v39
	v_add_u32_e32 v171, 0x3000, v1
	global_store_dwordx4 v171, v[88:91], s[4:5] nt
	global_store_dwordx4 v171, v[92:95], s[4:5] offset:1024 nt
	global_store_dwordx4 v171, v[96:99], s[4:5] offset:2048 nt
	global_store_dwordx4 v171, v[100:103], s[4:5] offset:3072 nt
	s_waitcnt vmcnt(28)
	v_add_f32_e32 v180, v104, v105
	v_add_f32_e32 v181, v108, v109
	v_add_f32_e32 v182, v112, v113
	v_add_f32_e32 v183, v116, v117
	v_add_f32_e32 v180, v180, v106
	v_add_f32_e32 v181, v181, v110
	v_add_f32_e32 v182, v182, v114
	v_add_f32_e32 v183, v183, v118
	v_add_f32_e32 v180, v180, v107
	v_add_f32_e32 v181, v181, v111
	v_add_f32_e32 v182, v182, v115
	v_add_f32_e32 v183, v183, v119
	v_add_f32_e32 v180, v180, v181
	v_add_f32_e32 v182, v182, v183
	v_add_f32_e32 v180, v180, v182
	s_nop 1
	v_add_f32_dpp v180, v180, v180 quad_perm:[1,0,3,2] row_mask:0xf bank_mask:0xf
	s_nop 1
	v_add_f32_dpp v180, v180, v180 quad_perm:[2,3,0,1] row_mask:0xf bank_mask:0xf
	s_nop 1
	v_add_f32_dpp v180, v180, v180 row_half_mirror row_mask:0xf bank_mask:0xf
	s_nop 1
	v_add_f32_dpp v180, v180, v180 row_mirror row_mask:0xf bank_mask:0xf
	s_nop 1
	v_add_f32_dpp v180, v180, v180 row_bcast:15 row_mask:0xa bank_mask:0xf
	s_nop 1
	v_add_f32_dpp v180, v180, v180 row_bcast:31 row_mask:0xc bank_mask:0xf
	s_nop 0
	v_readlane_b32 s20, v180, 63
	s_nop 1
	v_mul_f32_e32 v184, s20, v2
	v_sub_f32_e32 v104, v104, v184
	v_sub_f32_e32 v105, v105, v184
	v_sub_f32_e32 v106, v106, v184
	v_sub_f32_e32 v107, v107, v184
	v_sub_f32_e32 v108, v108, v184
	v_sub_f32_e32 v109, v109, v184
	v_sub_f32_e32 v110, v110, v184
	v_sub_f32_e32 v111, v111, v184
	v_sub_f32_e32 v112, v112, v184
	v_sub_f32_e32 v113, v113, v184
	v_sub_f32_e32 v114, v114, v184
	v_sub_f32_e32 v115, v115, v184
	v_sub_f32_e32 v116, v116, v184
	v_sub_f32_e32 v117, v117, v184
	v_sub_f32_e32 v118, v118, v184
	v_sub_f32_e32 v119, v119, v184
	v_mul_f32_e32 v180, v104, v104
	v_mul_f32_e32 v181, v108, v108
	v_mul_f32_e32 v182, v112, v112
	v_mul_f32_e32 v183, v116, v116
	v_fmac_f32_e32 v180, v105, v105
	v_fmac_f32_e32 v181, v109, v109
	v_fmac_f32_e32 v182, v113, v113
	v_fmac_f32_e32 v183, v117, v117
	v_fmac_f32_e32 v180, v106, v106
	v_fmac_f32_e32 v181, v110, v110
	v_fmac_f32_e32 v182, v114, v114
	v_fmac_f32_e32 v183, v118, v118
	v_fmac_f32_e32 v180, v107, v107
	v_fmac_f32_e32 v181, v111, v111
	v_fmac_f32_e32 v182, v115, v115
	v_fmac_f32_e32 v183, v119, v119
	v_add_f32_e32 v180, v180, v181
	v_add_f32_e32 v182, v182, v183
	v_add_f32_e32 v180, v180, v182
	s_nop 1
	v_add_f32_dpp v180, v180, v180 quad_perm:[1,0,3,2] row_mask:0xf bank_mask:0xf
	s_nop 1
	v_add_f32_dpp v180, v180, v180 quad_perm:[2,3,0,1] row_mask:0xf bank_mask:0xf
	s_nop 1
	v_add_f32_dpp v180, v180, v180 row_half_mirror row_mask:0xf bank_mask:0xf
	s_nop 1
	v_add_f32_dpp v180, v180, v180 row_mirror row_mask:0xf bank_mask:0xf
	s_nop 1
	v_add_f32_dpp v180, v180, v180 row_bcast:15 row_mask:0xa bank_mask:0xf
	s_nop 1
	v_add_f32_dpp v180, v180, v180 row_bcast:31 row_mask:0xc bank_mask:0xf
	s_nop 0
	v_readlane_b32 s20, v180, 63
	s_nop 1
	v_mov_b32_e32 v185, s20
	v_fma_f32 v185, v185, v2, v4
	v_rsq_f32_e32 v185, v185
	s_nop 0
	v_mul_f32_e32 v104, v104, v185
	v_mul_f32_e32 v105, v105, v185
	v_mul_f32_e32 v106, v106, v185
	v_mul_f32_e32 v107, v107, v185
	v_mul_f32_e32 v108, v108, v185
	v_mul_f32_e32 v109, v109, v185
	v_mul_f32_e32 v110, v110, v185
	v_mul_f32_e32 v111, v111, v185
	v_mul_f32_e32 v112, v112, v185
	v_mul_f32_e32 v113, v113, v185
	v_mul_f32_e32 v114, v114, v185
	v_mul_f32_e32 v115, v115, v185
	v_mul_f32_e32 v116, v116, v185
	v_mul_f32_e32 v117, v117, v185
	v_mul_f32_e32 v118, v118, v185
	v_mul_f32_e32 v119, v119, v185
	v_fma_f32 v104, v104, v8, v24
	v_fma_f32 v105, v105, v9, v25
	v_fma_f32 v106, v106, v10, v26
	v_fma_f32 v107, v107, v11, v27
	v_fma_f32 v108, v108, v12, v28
	v_fma_f32 v109, v109, v13, v29
	v_fma_f32 v110, v110, v14, v30
	v_fma_f32 v111, v111, v15, v31
	v_fma_f32 v112, v112, v16, v32
	v_fma_f32 v113, v113, v17, v33
	v_fma_f32 v114, v114, v18, v34
	v_fma_f32 v115, v115, v19, v35
	v_fma_f32 v116, v116, v20, v36
	v_fma_f32 v117, v117, v21, v37
	v_fma_f32 v118, v118, v22, v38
	v_fma_f32 v119, v119, v23, v39
	v_add_u32_e32 v171, 0x4000, v1
	global_store_dwordx4 v171, v[104:107], s[4:5] nt
	global_store_dwordx4 v171, v[108:111], s[4:5] offset:1024 nt
	global_store_dwordx4 v171, v[112:115], s[4:5] offset:2048 nt
	global_store_dwordx4 v171, v[116:119], s[4:5] offset:3072 nt
	s_waitcnt vmcnt(28)
	v_add_f32_e32 v180, v120, v121
	v_add_f32_e32 v181, v124, v125
	v_add_f32_e32 v182, v128, v129
	v_add_f32_e32 v183, v132, v133
	v_add_f32_e32 v180, v180, v122
	v_add_f32_e32 v181, v181, v126
	v_add_f32_e32 v182, v182, v130
	v_add_f32_e32 v183, v183, v134
	v_add_f32_e32 v180, v180, v123
	v_add_f32_e32 v181, v181, v127
	v_add_f32_e32 v182, v182, v131
	v_add_f32_e32 v183, v183, v135
	v_add_f32_e32 v180, v180, v181
	v_add_f32_e32 v182, v182, v183
	v_add_f32_e32 v180, v180, v182
	s_nop 1
	v_add_f32_dpp v180, v180, v180 quad_perm:[1,0,3,2] row_mask:0xf bank_mask:0xf
	s_nop 1
	v_add_f32_dpp v180, v180, v180 quad_perm:[2,3,0,1] row_mask:0xf bank_mask:0xf
	s_nop 1
	v_add_f32_dpp v180, v180, v180 row_half_mirror row_mask:0xf bank_mask:0xf
	s_nop 1
	v_add_f32_dpp v180, v180, v180 row_mirror row_mask:0xf bank_mask:0xf
	s_nop 1
	v_add_f32_dpp v180, v180, v180 row_bcast:15 row_mask:0xa bank_mask:0xf
	s_nop 1
	v_add_f32_dpp v180, v180, v180 row_bcast:31 row_mask:0xc bank_mask:0xf
	s_nop 0
	v_readlane_b32 s20, v180, 63
	s_nop 1
	v_mul_f32_e32 v184, s20, v2
	v_sub_f32_e32 v120, v120, v184
	v_sub_f32_e32 v121, v121, v184
	v_sub_f32_e32 v122, v122, v184
	v_sub_f32_e32 v123, v123, v184
	v_sub_f32_e32 v124, v124, v184
	v_sub_f32_e32 v125, v125, v184
	v_sub_f32_e32 v126, v126, v184
	v_sub_f32_e32 v127, v127, v184
	v_sub_f32_e32 v128, v128, v184
	v_sub_f32_e32 v129, v129, v184
	v_sub_f32_e32 v130, v130, v184
	v_sub_f32_e32 v131, v131, v184
	v_sub_f32_e32 v132, v132, v184
	v_sub_f32_e32 v133, v133, v184
	v_sub_f32_e32 v134, v134, v184
	v_sub_f32_e32 v135, v135, v184
	v_mul_f32_e32 v180, v120, v120
	v_mul_f32_e32 v181, v124, v124
	v_mul_f32_e32 v182, v128, v128
	v_mul_f32_e32 v183, v132, v132
	v_fmac_f32_e32 v180, v121, v121
	v_fmac_f32_e32 v181, v125, v125
	v_fmac_f32_e32 v182, v129, v129
	v_fmac_f32_e32 v183, v133, v133
	v_fmac_f32_e32 v180, v122, v122
	v_fmac_f32_e32 v181, v126, v126
	v_fmac_f32_e32 v182, v130, v130
	v_fmac_f32_e32 v183, v134, v134
	v_fmac_f32_e32 v180, v123, v123
	v_fmac_f32_e32 v181, v127, v127
	v_fmac_f32_e32 v182, v131, v131
	v_fmac_f32_e32 v183, v135, v135
	v_add_f32_e32 v180, v180, v181
	v_add_f32_e32 v182, v182, v183
	v_add_f32_e32 v180, v180, v182
	s_nop 1
	v_add_f32_dpp v180, v180, v180 quad_perm:[1,0,3,2] row_mask:0xf bank_mask:0xf
	s_nop 1
	v_add_f32_dpp v180, v180, v180 quad_perm:[2,3,0,1] row_mask:0xf bank_mask:0xf
	s_nop 1
	v_add_f32_dpp v180, v180, v180 row_half_mirror row_mask:0xf bank_mask:0xf
	s_nop 1
	v_add_f32_dpp v180, v180, v180 row_mirror row_mask:0xf bank_mask:0xf
	s_nop 1
	v_add_f32_dpp v180, v180, v180 row_bcast:15 row_mask:0xa bank_mask:0xf
	s_nop 1
	v_add_f32_dpp v180, v180, v180 row_bcast:31 row_mask:0xc bank_mask:0xf
	s_nop 0
	v_readlane_b32 s20, v180, 63
	s_nop 1
	v_mov_b32_e32 v185, s20
	v_fma_f32 v185, v185, v2, v4
	v_rsq_f32_e32 v185, v185
	s_nop 0
	v_mul_f32_e32 v120, v120, v185
	v_mul_f32_e32 v121, v121, v185
	v_mul_f32_e32 v122, v122, v185
	v_mul_f32_e32 v123, v123, v185
	v_mul_f32_e32 v124, v124, v185
	v_mul_f32_e32 v125, v125, v185
	v_mul_f32_e32 v126, v126, v185
	v_mul_f32_e32 v127, v127, v185
	v_mul_f32_e32 v128, v128, v185
	v_mul_f32_e32 v129, v129, v185
	v_mul_f32_e32 v130, v130, v185
	v_mul_f32_e32 v131, v131, v185
	v_mul_f32_e32 v132, v132, v185
	v_mul_f32_e32 v133, v133, v185
	v_mul_f32_e32 v134, v134, v185
	v_mul_f32_e32 v135, v135, v185
	v_fma_f32 v120, v120, v8, v24
	v_fma_f32 v121, v121, v9, v25
	v_fma_f32 v122, v122, v10, v26
	v_fma_f32 v123, v123, v11, v27
	v_fma_f32 v124, v124, v12, v28
	v_fma_f32 v125, v125, v13, v29
	v_fma_f32 v126, v126, v14, v30
	v_fma_f32 v127, v127, v15, v31
	v_fma_f32 v128, v128, v16, v32
	v_fma_f32 v129, v129, v17, v33
	v_fma_f32 v130, v130, v18, v34
	v_fma_f32 v131, v131, v19, v35
	v_fma_f32 v132, v132, v20, v36
	v_fma_f32 v133, v133, v21, v37
	v_fma_f32 v134, v134, v22, v38
	v_fma_f32 v135, v135, v23, v39
	v_add_u32_e32 v171, 0x5000, v1
	global_store_dwordx4 v171, v[120:123], s[4:5] nt
	global_store_dwordx4 v171, v[124:127], s[4:5] offset:1024 nt
	global_store_dwordx4 v171, v[128:131], s[4:5] offset:2048 nt
	global_store_dwordx4 v171, v[132:135], s[4:5] offset:3072 nt
	s_waitcnt vmcnt(28)
	v_add_f32_e32 v180, v136, v137
	v_add_f32_e32 v181, v140, v141
	v_add_f32_e32 v182, v144, v145
	v_add_f32_e32 v183, v148, v149
	v_add_f32_e32 v180, v180, v138
	v_add_f32_e32 v181, v181, v142
	v_add_f32_e32 v182, v182, v146
	v_add_f32_e32 v183, v183, v150
	v_add_f32_e32 v180, v180, v139
	v_add_f32_e32 v181, v181, v143
	v_add_f32_e32 v182, v182, v147
	v_add_f32_e32 v183, v183, v151
	v_add_f32_e32 v180, v180, v181
	v_add_f32_e32 v182, v182, v183
	v_add_f32_e32 v180, v180, v182
	s_nop 1
	v_add_f32_dpp v180, v180, v180 quad_perm:[1,0,3,2] row_mask:0xf bank_mask:0xf
	s_nop 1
	v_add_f32_dpp v180, v180, v180 quad_perm:[2,3,0,1] row_mask:0xf bank_mask:0xf
	s_nop 1
	v_add_f32_dpp v180, v180, v180 row_half_mirror row_mask:0xf bank_mask:0xf
	s_nop 1
	v_add_f32_dpp v180, v180, v180 row_mirror row_mask:0xf bank_mask:0xf
	s_nop 1
	v_add_f32_dpp v180, v180, v180 row_bcast:15 row_mask:0xa bank_mask:0xf
	s_nop 1
	v_add_f32_dpp v180, v180, v180 row_bcast:31 row_mask:0xc bank_mask:0xf
	s_nop 0
	v_readlane_b32 s20, v180, 63
	s_nop 1
	v_mul_f32_e32 v184, s20, v2
	v_sub_f32_e32 v136, v136, v184
	v_sub_f32_e32 v137, v137, v184
	v_sub_f32_e32 v138, v138, v184
	v_sub_f32_e32 v139, v139, v184
	v_sub_f32_e32 v140, v140, v184
	v_sub_f32_e32 v141, v141, v184
	v_sub_f32_e32 v142, v142, v184
	v_sub_f32_e32 v143, v143, v184
	v_sub_f32_e32 v144, v144, v184
	v_sub_f32_e32 v145, v145, v184
	v_sub_f32_e32 v146, v146, v184
	v_sub_f32_e32 v147, v147, v184
	v_sub_f32_e32 v148, v148, v184
	v_sub_f32_e32 v149, v149, v184
	v_sub_f32_e32 v150, v150, v184
	v_sub_f32_e32 v151, v151, v184
	v_mul_f32_e32 v180, v136, v136
	v_mul_f32_e32 v181, v140, v140
	v_mul_f32_e32 v182, v144, v144
	v_mul_f32_e32 v183, v148, v148
	v_fmac_f32_e32 v180, v137, v137
	v_fmac_f32_e32 v181, v141, v141
	v_fmac_f32_e32 v182, v145, v145
	v_fmac_f32_e32 v183, v149, v149
	v_fmac_f32_e32 v180, v138, v138
	v_fmac_f32_e32 v181, v142, v142
	v_fmac_f32_e32 v182, v146, v146
	v_fmac_f32_e32 v183, v150, v150
	v_fmac_f32_e32 v180, v139, v139
	v_fmac_f32_e32 v181, v143, v143
	v_fmac_f32_e32 v182, v147, v147
	v_fmac_f32_e32 v183, v151, v151
	v_add_f32_e32 v180, v180, v181
	v_add_f32_e32 v182, v182, v183
	v_add_f32_e32 v180, v180, v182
	s_nop 1
	v_add_f32_dpp v180, v180, v180 quad_perm:[1,0,3,2] row_mask:0xf bank_mask:0xf
	s_nop 1
	v_add_f32_dpp v180, v180, v180 quad_perm:[2,3,0,1] row_mask:0xf bank_mask:0xf
	s_nop 1
	v_add_f32_dpp v180, v180, v180 row_half_mirror row_mask:0xf bank_mask:0xf
	s_nop 1
	v_add_f32_dpp v180, v180, v180 row_mirror row_mask:0xf bank_mask:0xf
	s_nop 1
	v_add_f32_dpp v180, v180, v180 row_bcast:15 row_mask:0xa bank_mask:0xf
	s_nop 1
	v_add_f32_dpp v180, v180, v180 row_bcast:31 row_mask:0xc bank_mask:0xf
	s_nop 0
	v_readlane_b32 s20, v180, 63
	s_nop 1
	v_mov_b32_e32 v185, s20
	v_fma_f32 v185, v185, v2, v4
	v_rsq_f32_e32 v185, v185
	s_nop 0
	v_mul_f32_e32 v136, v136, v185
	v_mul_f32_e32 v137, v137, v185
	v_mul_f32_e32 v138, v138, v185
	v_mul_f32_e32 v139, v139, v185
	v_mul_f32_e32 v140, v140, v185
	v_mul_f32_e32 v141, v141, v185
	v_mul_f32_e32 v142, v142, v185
	v_mul_f32_e32 v143, v143, v185
	v_mul_f32_e32 v144, v144, v185
	v_mul_f32_e32 v145, v145, v185
	v_mul_f32_e32 v146, v146, v185
	v_mul_f32_e32 v147, v147, v185
	v_mul_f32_e32 v148, v148, v185
	v_mul_f32_e32 v149, v149, v185
	v_mul_f32_e32 v150, v150, v185
	v_mul_f32_e32 v151, v151, v185
	v_fma_f32 v136, v136, v8, v24
	v_fma_f32 v137, v137, v9, v25
	v_fma_f32 v138, v138, v10, v26
	v_fma_f32 v139, v139, v11, v27
	v_fma_f32 v140, v140, v12, v28
	v_fma_f32 v141, v141, v13, v29
	v_fma_f32 v142, v142, v14, v30
	v_fma_f32 v143, v143, v15, v31
	v_fma_f32 v144, v144, v16, v32
	v_fma_f32 v145, v145, v17, v33
	v_fma_f32 v146, v146, v18, v34
	v_fma_f32 v147, v147, v19, v35
	v_fma_f32 v148, v148, v20, v36
	v_fma_f32 v149, v149, v21, v37
	v_fma_f32 v150, v150, v22, v38
	v_fma_f32 v151, v151, v23, v39
	v_add_u32_e32 v171, 0x6000, v1
	global_store_dwordx4 v171, v[136:139], s[4:5] nt
	global_store_dwordx4 v171, v[140:143], s[4:5] offset:1024 nt
	global_store_dwordx4 v171, v[144:147], s[4:5] offset:2048 nt
	global_store_dwordx4 v171, v[148:151], s[4:5] offset:3072 nt
	s_waitcnt vmcnt(28)
	v_add_f32_e32 v180, v152, v153
	v_add_f32_e32 v181, v156, v157
	v_add_f32_e32 v182, v160, v161
	v_add_f32_e32 v183, v164, v165
	v_add_f32_e32 v180, v180, v154
	v_add_f32_e32 v181, v181, v158
	v_add_f32_e32 v182, v182, v162
	v_add_f32_e32 v183, v183, v166
	v_add_f32_e32 v180, v180, v155
	v_add_f32_e32 v181, v181, v159
	v_add_f32_e32 v182, v182, v163
	v_add_f32_e32 v183, v183, v167
	v_add_f32_e32 v180, v180, v181
	v_add_f32_e32 v182, v182, v183
	v_add_f32_e32 v180, v180, v182
	s_nop 1
	v_add_f32_dpp v180, v180, v180 quad_perm:[1,0,3,2] row_mask:0xf bank_mask:0xf
	s_nop 1
	v_add_f32_dpp v180, v180, v180 quad_perm:[2,3,0,1] row_mask:0xf bank_mask:0xf
	s_nop 1
	v_add_f32_dpp v180, v180, v180 row_half_mirror row_mask:0xf bank_mask:0xf
	s_nop 1
	v_add_f32_dpp v180, v180, v180 row_mirror row_mask:0xf bank_mask:0xf
	s_nop 1
	v_add_f32_dpp v180, v180, v180 row_bcast:15 row_mask:0xa bank_mask:0xf
	s_nop 1
	v_add_f32_dpp v180, v180, v180 row_bcast:31 row_mask:0xc bank_mask:0xf
	s_nop 0
	v_readlane_b32 s20, v180, 63
	s_nop 1
	v_mul_f32_e32 v184, s20, v2
	v_sub_f32_e32 v152, v152, v184
	v_sub_f32_e32 v153, v153, v184
	v_sub_f32_e32 v154, v154, v184
	v_sub_f32_e32 v155, v155, v184
	v_sub_f32_e32 v156, v156, v184
	v_sub_f32_e32 v157, v157, v184
	v_sub_f32_e32 v158, v158, v184
	v_sub_f32_e32 v159, v159, v184
	v_sub_f32_e32 v160, v160, v184
	v_sub_f32_e32 v161, v161, v184
	v_sub_f32_e32 v162, v162, v184
	v_sub_f32_e32 v163, v163, v184
	v_sub_f32_e32 v164, v164, v184
	v_sub_f32_e32 v165, v165, v184
	v_sub_f32_e32 v166, v166, v184
	v_sub_f32_e32 v167, v167, v184
	v_mul_f32_e32 v180, v152, v152
	v_mul_f32_e32 v181, v156, v156
	v_mul_f32_e32 v182, v160, v160
	v_mul_f32_e32 v183, v164, v164
	v_fmac_f32_e32 v180, v153, v153
	v_fmac_f32_e32 v181, v157, v157
	v_fmac_f32_e32 v182, v161, v161
	v_fmac_f32_e32 v183, v165, v165
	v_fmac_f32_e32 v180, v154, v154
	v_fmac_f32_e32 v181, v158, v158
	v_fmac_f32_e32 v182, v162, v162
	v_fmac_f32_e32 v183, v166, v166
	v_fmac_f32_e32 v180, v155, v155
	v_fmac_f32_e32 v181, v159, v159
	v_fmac_f32_e32 v182, v163, v163
	v_fmac_f32_e32 v183, v167, v167
	v_add_f32_e32 v180, v180, v181
	v_add_f32_e32 v182, v182, v183
	v_add_f32_e32 v180, v180, v182
	s_nop 1
	v_add_f32_dpp v180, v180, v180 quad_perm:[1,0,3,2] row_mask:0xf bank_mask:0xf
	s_nop 1
	v_add_f32_dpp v180, v180, v180 quad_perm:[2,3,0,1] row_mask:0xf bank_mask:0xf
	s_nop 1
	v_add_f32_dpp v180, v180, v180 row_half_mirror row_mask:0xf bank_mask:0xf
	s_nop 1
	v_add_f32_dpp v180, v180, v180 row_mirror row_mask:0xf bank_mask:0xf
	s_nop 1
	v_add_f32_dpp v180, v180, v180 row_bcast:15 row_mask:0xa bank_mask:0xf
	s_nop 1
	v_add_f32_dpp v180, v180, v180 row_bcast:31 row_mask:0xc bank_mask:0xf
	s_nop 0
	v_readlane_b32 s20, v180, 63
	s_nop 1
	v_mov_b32_e32 v185, s20
	v_fma_f32 v185, v185, v2, v4
	v_rsq_f32_e32 v185, v185
	s_nop 0
	v_mul_f32_e32 v152, v152, v185
	v_mul_f32_e32 v153, v153, v185
	v_mul_f32_e32 v154, v154, v185
	v_mul_f32_e32 v155, v155, v185
	v_mul_f32_e32 v156, v156, v185
	v_mul_f32_e32 v157, v157, v185
	v_mul_f32_e32 v158, v158, v185
	v_mul_f32_e32 v159, v159, v185
	v_mul_f32_e32 v160, v160, v185
	v_mul_f32_e32 v161, v161, v185
	v_mul_f32_e32 v162, v162, v185
	v_mul_f32_e32 v163, v163, v185
	v_mul_f32_e32 v164, v164, v185
	v_mul_f32_e32 v165, v165, v185
	v_mul_f32_e32 v166, v166, v185
	v_mul_f32_e32 v167, v167, v185
	v_fma_f32 v152, v152, v8, v24
	v_fma_f32 v153, v153, v9, v25
	v_fma_f32 v154, v154, v10, v26
	v_fma_f32 v155, v155, v11, v27
	v_fma_f32 v156, v156, v12, v28
	v_fma_f32 v157, v157, v13, v29
	v_fma_f32 v158, v158, v14, v30
	v_fma_f32 v159, v159, v15, v31
	v_fma_f32 v160, v160, v16, v32
	v_fma_f32 v161, v161, v17, v33
	v_fma_f32 v162, v162, v18, v34
	v_fma_f32 v163, v163, v19, v35
	v_fma_f32 v164, v164, v20, v36
	v_fma_f32 v165, v165, v21, v37
	v_fma_f32 v166, v166, v22, v38
	v_fma_f32 v167, v167, v23, v39
	v_add_u32_e32 v171, 0x7000, v1
	global_store_dwordx4 v171, v[152:155], s[4:5] nt
	global_store_dwordx4 v171, v[156:159], s[4:5] offset:1024 nt
	global_store_dwordx4 v171, v[160:163], s[4:5] offset:2048 nt
	global_store_dwordx4 v171, v[164:167], s[4:5] offset:3072 nt
	s_branch .Ltr_29
